# LDS-staged scan (4 core waves share one staged feature stream, followers keep barriers) + 4-instruction exact rank compare in both PEER select phases
# speedup vs baseline: 1.0578x; 1.0483x over previous
; __device__ __forceinline__ void ph_peer_select(const Params& P, int layer, const h16* Q, int nrows, char* smem) {
;     ...
;     for (int i = tid; i < 64 * 50; i += NTHR) {
;       const int tok = i / 50, c = i % 50;
;       const float v = cd[tok * 52 + c];
;       int rank = 0;
;       for (int j = 0; j < 50; ++j) { const float o = cd[tok * 52 + j]; rank += (o > v || (o == v && j < c)) ? 1 : 0; }
;       if (rank < TOPK) { tv[tok * 16 + rank] = v; tp[tok * 16 + rank] = c; }
;     }
.LBB0_1896:
	v_mul_hi_i32 v8, v6, s48
	v_lshrrev_b32_e32 v9, 31, v8
	v_ashrrev_i32_e32 v8, 4, v8
	v_add_u32_e32 v89, v8, v9
	v_mul_lo_u32 v8, v89, s53
	v_add_u32_e32 v8, 0, v8
	v_add_u32_e32 v91, 0x10800, v8
	v_lshl_add_u32 v8, v89, 3, v88
	ds_read_b32 v90, v8
	ds_read_b128 v[92:95], v91
	v_mad_u64_u32 v[8:9], s[4:5], v89, s52, v[6:7]
	ds_read_b128 v[96:99], v91 offset:16
	v_mov_b32_e32 v9, 0
	s_waitcnt lgkmcnt(2)
	v_cmp_lt_f32_e64 s[22:23], 0, v90
	v_cmp_eq_f32_e64 s[24:25], 0, v90
	v_bfrev_b32_e32 v100, 1
	v_or_b32_e32 v100, 1, v100
	v_cndmask_b32_e64 v104, 1, -1, s[22:23]
	v_add_u32_e32 v104, v90, v104
	v_cndmask_b32_e64 v104, v104, v100, s[24:25]
	s_waitcnt lgkmcnt(1)
	v_cmp_lt_i32_e64 s[22:23], 0, v8
	v_cmp_lt_i32_e64 s[24:25], 1, v8
	v_cmp_lt_i32_e64 s[26:27], 2, v8
	v_cmp_lt_i32_e64 s[28:29], 3, v8
	v_cndmask_b32_e64 v100, v90, v104, s[22:23]
	v_cndmask_b32_e64 v101, v90, v104, s[24:25]
	v_cndmask_b32_e64 v102, v90, v104, s[26:27]
	v_cndmask_b32_e64 v103, v90, v104, s[28:29]
	v_cmp_gt_f32_e64 s[22:23], v92, v100
	v_cmp_gt_f32_e64 s[24:25], v93, v101
	v_cmp_gt_f32_e64 s[26:27], v94, v102
	v_cmp_gt_f32_e64 s[28:29], v95, v103
	ds_read_b128 v[92:95], v91 offset:32
	v_addc_co_u32_e64 v9, s[30:31], v9, 0, s[22:23]
	v_addc_co_u32_e64 v9, s[30:31], v9, 0, s[24:25]
	v_addc_co_u32_e64 v9, s[30:31], v9, 0, s[26:27]
	v_addc_co_u32_e64 v9, s[30:31], v9, 0, s[28:29]
	s_waitcnt lgkmcnt(1)
	v_cmp_lt_i32_e64 s[22:23], 4, v8
	v_cmp_lt_i32_e64 s[24:25], 5, v8
	v_cmp_lt_i32_e64 s[26:27], 6, v8
	v_cmp_lt_i32_e64 s[28:29], 7, v8
	v_cndmask_b32_e64 v100, v90, v104, s[22:23]
	v_cndmask_b32_e64 v101, v90, v104, s[24:25]
	v_cndmask_b32_e64 v102, v90, v104, s[26:27]
	v_cndmask_b32_e64 v103, v90, v104, s[28:29]
	v_cmp_gt_f32_e64 s[22:23], v96, v100
	v_cmp_gt_f32_e64 s[24:25], v97, v101
	v_cmp_gt_f32_e64 s[26:27], v98, v102
	v_cmp_gt_f32_e64 s[28:29], v99, v103
	ds_read_b128 v[96:99], v91 offset:48
	v_addc_co_u32_e64 v9, s[30:31], v9, 0, s[22:23]
	v_addc_co_u32_e64 v9, s[30:31], v9, 0, s[24:25]
	v_addc_co_u32_e64 v9, s[30:31], v9, 0, s[26:27]
	v_addc_co_u32_e64 v9, s[30:31], v9, 0, s[28:29]
	s_waitcnt lgkmcnt(1)
	v_cmp_lt_i32_e64 s[22:23], 8, v8
	v_cmp_lt_i32_e64 s[24:25], 9, v8
	v_cmp_lt_i32_e64 s[26:27], 10, v8
	v_cmp_lt_i32_e64 s[28:29], 11, v8
	v_cndmask_b32_e64 v100, v90, v104, s[22:23]
	v_cndmask_b32_e64 v101, v90, v104, s[24:25]
	v_cndmask_b32_e64 v102, v90, v104, s[26:27]
	v_cndmask_b32_e64 v103, v90, v104, s[28:29]
	v_cmp_gt_f32_e64 s[22:23], v92, v100
	v_cmp_gt_f32_e64 s[24:25], v93, v101
	v_cmp_gt_f32_e64 s[26:27], v94, v102
	v_cmp_gt_f32_e64 s[28:29], v95, v103
	ds_read_b128 v[92:95], v91 offset:64
	v_addc_co_u32_e64 v9, s[30:31], v9, 0, s[22:23]
	v_addc_co_u32_e64 v9, s[30:31], v9, 0, s[24:25]
	v_addc_co_u32_e64 v9, s[30:31], v9, 0, s[26:27]
	v_addc_co_u32_e64 v9, s[30:31], v9, 0, s[28:29]
	s_waitcnt lgkmcnt(1)
	v_cmp_lt_i32_e64 s[22:23], 12, v8
	v_cmp_lt_i32_e64 s[24:25], 13, v8
	v_cmp_lt_i32_e64 s[26:27], 14, v8
	v_cmp_lt_i32_e64 s[28:29], 15, v8
	v_cndmask_b32_e64 v100, v90, v104, s[22:23]
	v_cndmask_b32_e64 v101, v90, v104, s[24:25]
	v_cndmask_b32_e64 v102, v90, v104, s[26:27]
	v_cndmask_b32_e64 v103, v90, v104, s[28:29]
	v_cmp_gt_f32_e64 s[22:23], v96, v100
	v_cmp_gt_f32_e64 s[24:25], v97, v101
	v_cmp_gt_f32_e64 s[26:27], v98, v102
	v_cmp_gt_f32_e64 s[28:29], v99, v103
	ds_read_b128 v[96:99], v91 offset:80
	v_addc_co_u32_e64 v9, s[30:31], v9, 0, s[22:23]
	v_addc_co_u32_e64 v9, s[30:31], v9, 0, s[24:25]
	v_addc_co_u32_e64 v9, s[30:31], v9, 0, s[26:27]
	v_addc_co_u32_e64 v9, s[30:31], v9, 0, s[28:29]
	s_waitcnt lgkmcnt(1)
	v_cmp_lt_i32_e64 s[22:23], 16, v8
	v_cmp_lt_i32_e64 s[24:25], 17, v8
	v_cmp_lt_i32_e64 s[26:27], 18, v8
	v_cmp_lt_i32_e64 s[28:29], 19, v8
	v_cndmask_b32_e64 v100, v90, v104, s[22:23]
	v_cndmask_b32_e64 v101, v90, v104, s[24:25]
	v_cndmask_b32_e64 v102, v90, v104, s[26:27]
	v_cndmask_b32_e64 v103, v90, v104, s[28:29]
	v_cmp_gt_f32_e64 s[22:23], v92, v100
	v_cmp_gt_f32_e64 s[24:25], v93, v101
	v_cmp_gt_f32_e64 s[26:27], v94, v102
	v_cmp_gt_f32_e64 s[28:29], v95, v103
	ds_read_b128 v[92:95], v91 offset:96
	v_addc_co_u32_e64 v9, s[30:31], v9, 0, s[22:23]
	v_addc_co_u32_e64 v9, s[30:31], v9, 0, s[24:25]
	v_addc_co_u32_e64 v9, s[30:31], v9, 0, s[26:27]
	v_addc_co_u32_e64 v9, s[30:31], v9, 0, s[28:29]
	s_waitcnt lgkmcnt(1)
	v_cmp_lt_i32_e64 s[22:23], 20, v8
	v_cmp_lt_i32_e64 s[24:25], 21, v8
	v_cmp_lt_i32_e64 s[26:27], 22, v8
	v_cmp_lt_i32_e64 s[28:29], 23, v8
	v_cndmask_b32_e64 v100, v90, v104, s[22:23]
	v_cndmask_b32_e64 v101, v90, v104, s[24:25]
	v_cndmask_b32_e64 v102, v90, v104, s[26:27]
	v_cndmask_b32_e64 v103, v90, v104, s[28:29]
	v_cmp_gt_f32_e64 s[22:23], v96, v100
	v_cmp_gt_f32_e64 s[24:25], v97, v101
	v_cmp_gt_f32_e64 s[26:27], v98, v102
	v_cmp_gt_f32_e64 s[28:29], v99, v103
	ds_read_b128 v[96:99], v91 offset:112
	v_addc_co_u32_e64 v9, s[30:31], v9, 0, s[22:23]
	v_addc_co_u32_e64 v9, s[30:31], v9, 0, s[24:25]
	v_addc_co_u32_e64 v9, s[30:31], v9, 0, s[26:27]
	v_addc_co_u32_e64 v9, s[30:31], v9, 0, s[28:29]
	s_waitcnt lgkmcnt(1)
; __device__ __forceinline__ void ph_peer_select(const Params& P, int layer, const h16* Q, int nrows, char* smem) {
;     ...
;     for (int i = tid; i < 64 * 50; i += NTHR) {
;       const int tok = i / 50, c = i % 50;
;       const float v = cd[tok * 52 + c];
;       int rank = 0;
;       for (int j = 0; j < 50; ++j) { const float o = cd[tok * 52 + j]; rank += (o > v || (o == v && j < c)) ? 1 : 0; }
;       if (rank < TOPK) { tv[tok * 16 + rank] = v; tp[tok * 16 + rank] = c; }
;     }
	v_cmp_lt_i32_e64 s[22:23], 24, v8
	v_cmp_lt_i32_e64 s[24:25], 25, v8
	v_cmp_lt_i32_e64 s[26:27], 26, v8
	v_cmp_lt_i32_e64 s[28:29], 27, v8
	v_cndmask_b32_e64 v100, v90, v104, s[22:23]
	v_cndmask_b32_e64 v101, v90, v104, s[24:25]
	v_cndmask_b32_e64 v102, v90, v104, s[26:27]
	v_cndmask_b32_e64 v103, v90, v104, s[28:29]
	v_cmp_gt_f32_e64 s[22:23], v92, v100
	v_cmp_gt_f32_e64 s[24:25], v93, v101
	v_cmp_gt_f32_e64 s[26:27], v94, v102
	v_cmp_gt_f32_e64 s[28:29], v95, v103
	ds_read_b128 v[92:95], v91 offset:128
	v_addc_co_u32_e64 v9, s[30:31], v9, 0, s[22:23]
	v_addc_co_u32_e64 v9, s[30:31], v9, 0, s[24:25]
	v_addc_co_u32_e64 v9, s[30:31], v9, 0, s[26:27]
	v_addc_co_u32_e64 v9, s[30:31], v9, 0, s[28:29]
	s_waitcnt lgkmcnt(1)
	v_cmp_lt_i32_e64 s[22:23], 28, v8
	v_cmp_lt_i32_e64 s[24:25], 29, v8
	v_cmp_lt_i32_e64 s[26:27], 30, v8
	v_cmp_lt_i32_e64 s[28:29], 31, v8
	v_cndmask_b32_e64 v100, v90, v104, s[22:23]
	v_cndmask_b32_e64 v101, v90, v104, s[24:25]
	v_cndmask_b32_e64 v102, v90, v104, s[26:27]
	v_cndmask_b32_e64 v103, v90, v104, s[28:29]
	v_cmp_gt_f32_e64 s[22:23], v96, v100
	v_cmp_gt_f32_e64 s[24:25], v97, v101
	v_cmp_gt_f32_e64 s[26:27], v98, v102
	v_cmp_gt_f32_e64 s[28:29], v99, v103
	ds_read_b128 v[96:99], v91 offset:144
	v_addc_co_u32_e64 v9, s[30:31], v9, 0, s[22:23]
	v_addc_co_u32_e64 v9, s[30:31], v9, 0, s[24:25]
	v_addc_co_u32_e64 v9, s[30:31], v9, 0, s[26:27]
	v_addc_co_u32_e64 v9, s[30:31], v9, 0, s[28:29]
	s_waitcnt lgkmcnt(1)
	v_cmp_lt_i32_e64 s[22:23], 32, v8
	v_cmp_lt_i32_e64 s[24:25], 33, v8
	v_cmp_lt_i32_e64 s[26:27], 34, v8
	v_cmp_lt_i32_e64 s[28:29], 35, v8
	v_cndmask_b32_e64 v100, v90, v104, s[22:23]
	v_cndmask_b32_e64 v101, v90, v104, s[24:25]
	v_cndmask_b32_e64 v102, v90, v104, s[26:27]
	v_cndmask_b32_e64 v103, v90, v104, s[28:29]
	v_cmp_gt_f32_e64 s[22:23], v92, v100
	v_cmp_gt_f32_e64 s[24:25], v93, v101
	v_cmp_gt_f32_e64 s[26:27], v94, v102
	v_cmp_gt_f32_e64 s[28:29], v95, v103
	ds_read_b128 v[92:95], v91 offset:160
	v_addc_co_u32_e64 v9, s[30:31], v9, 0, s[22:23]
	v_addc_co_u32_e64 v9, s[30:31], v9, 0, s[24:25]
	v_addc_co_u32_e64 v9, s[30:31], v9, 0, s[26:27]
	v_addc_co_u32_e64 v9, s[30:31], v9, 0, s[28:29]
	s_waitcnt lgkmcnt(1)
	v_cmp_lt_i32_e64 s[22:23], 36, v8
	v_cmp_lt_i32_e64 s[24:25], 37, v8
	v_cmp_lt_i32_e64 s[26:27], 38, v8
	v_cmp_lt_i32_e64 s[28:29], 39, v8
	v_cndmask_b32_e64 v100, v90, v104, s[22:23]
	v_cndmask_b32_e64 v101, v90, v104, s[24:25]
	v_cndmask_b32_e64 v102, v90, v104, s[26:27]
	v_cndmask_b32_e64 v103, v90, v104, s[28:29]
	v_cmp_gt_f32_e64 s[22:23], v96, v100
	v_cmp_gt_f32_e64 s[24:25], v97, v101
	v_cmp_gt_f32_e64 s[26:27], v98, v102
	v_cmp_gt_f32_e64 s[28:29], v99, v103
	ds_read_b128 v[96:99], v91 offset:176
	v_addc_co_u32_e64 v9, s[30:31], v9, 0, s[22:23]
	v_addc_co_u32_e64 v9, s[30:31], v9, 0, s[24:25]
	v_addc_co_u32_e64 v9, s[30:31], v9, 0, s[26:27]
	v_addc_co_u32_e64 v9, s[30:31], v9, 0, s[28:29]
	s_waitcnt lgkmcnt(1)
	v_cmp_lt_i32_e64 s[22:23], 40, v8
	v_cmp_lt_i32_e64 s[24:25], 41, v8
	v_cmp_lt_i32_e64 s[26:27], 42, v8
	v_cmp_lt_i32_e64 s[28:29], 43, v8
	v_cndmask_b32_e64 v100, v90, v104, s[22:23]
	v_cndmask_b32_e64 v101, v90, v104, s[24:25]
	v_cndmask_b32_e64 v102, v90, v104, s[26:27]
	v_cndmask_b32_e64 v103, v90, v104, s[28:29]
	v_cmp_gt_f32_e64 s[22:23], v92, v100
	v_cmp_gt_f32_e64 s[24:25], v93, v101
	v_cmp_gt_f32_e64 s[26:27], v94, v102
	v_cmp_gt_f32_e64 s[28:29], v95, v103
	ds_read_b64 v[92:93], v91 offset:192
	v_addc_co_u32_e64 v9, s[30:31], v9, 0, s[22:23]
	v_addc_co_u32_e64 v9, s[30:31], v9, 0, s[24:25]
	v_addc_co_u32_e64 v9, s[30:31], v9, 0, s[26:27]
	v_addc_co_u32_e64 v9, s[30:31], v9, 0, s[28:29]
	s_waitcnt lgkmcnt(1)
	v_cmp_lt_i32_e64 s[22:23], 44, v8
	v_cmp_lt_i32_e64 s[24:25], 45, v8
	v_cmp_lt_i32_e64 s[26:27], 46, v8
	v_cmp_lt_i32_e64 s[28:29], 47, v8
	v_cndmask_b32_e64 v100, v90, v104, s[22:23]
	v_cndmask_b32_e64 v101, v90, v104, s[24:25]
	v_cndmask_b32_e64 v102, v90, v104, s[26:27]
	v_cndmask_b32_e64 v103, v90, v104, s[28:29]
	v_cmp_gt_f32_e64 s[22:23], v96, v100
	v_cmp_gt_f32_e64 s[24:25], v97, v101
	v_cmp_gt_f32_e64 s[26:27], v98, v102
	v_cmp_gt_f32_e64 s[28:29], v99, v103
	v_addc_co_u32_e64 v9, s[30:31], v9, 0, s[22:23]
	v_addc_co_u32_e64 v9, s[30:31], v9, 0, s[24:25]
	v_addc_co_u32_e64 v9, s[30:31], v9, 0, s[26:27]
	v_addc_co_u32_e64 v9, s[30:31], v9, 0, s[28:29]
	s_waitcnt lgkmcnt(0)
	v_cmp_lt_i32_e64 s[22:23], 48, v8
	v_cmp_lt_i32_e64 s[24:25], 49, v8
	s_nop 0
	v_cndmask_b32_e64 v100, v90, v104, s[22:23]
	v_cndmask_b32_e64 v101, v90, v104, s[24:25]
	v_cmp_gt_f32_e64 s[22:23], v92, v100
	v_cmp_gt_f32_e64 s[24:25], v93, v101
	s_nop 0
	v_addc_co_u32_e64 v9, s[30:31], v9, 0, s[22:23]
	v_addc_co_u32_e64 v9, s[30:31], v9, 0, s[24:25]
	v_cmp_gt_u32_e32 vcc, 16, v9
	s_and_saveexec_b64 s[4:5], vcc
	s_cbranch_execz .LBB0_1895
	v_lshlrev_b32_e32 v9, 2, v9
	v_lshl_or_b32 v9, v89, 6, v9
	v_add_u32_e32 v9, 0, v9
	v_add_u32_e32 v89, 0x13c00, v9
	v_add_u32_e32 v9, 0x14c00, v9
	ds_write_b32 v89, v90
	ds_write_b32 v9, v8
	s_branch .LBB0_1895

; #define TIDX tid_fn()
; #define RW_LOAD(slot, step) do { const size_t ro_ = (size_t)row_of(step) * RWW; \
;       s_ok[slot] = *(const h16x8*)((p_rec + ro_ * 3) + urec); s_b[slot] = *(const h16x4*)((p_rec + ro_ * 3) + urec + 8); \
;       s_kr[slot] = *(const h16x8*)((p_sh + ro_ * 2) + ush); s_v[slot] = (p_v + ro_)[uvoff]; } while (0)
; template <int VAR>
; __device__ __forceinline__ void ph_rw_scan(const Params& P) {
;     ...
;   const int tid = TIDX, wave = __builtin_amdgcn_readfirstlane(tid / 64), lane = tid % 64;
;     ...
;   const int rl = lane / 16, q = lane % 16;
;   constexpr int NWU = 2 * BATCH * RW_H * 16;
;   for (int wu = blockIdx.x * 4 + wave; wave < 4 && wu < NWU; wu += gridDim.x * 4) {
;     const int rg = wu % 16, hh = (wu / 16) % RW_H, b = (wu / (16 * RW_H)) % BATCH, dir = wu / (16 * RW_H * BATCH);
;     const int vrow = rg * 4 + rl;
;     ...
;     const unsigned g_ = (unsigned)(hh * 16 + q);
;     const unsigned uvoff = (unsigned)(hh * 64 + vrow), urec = g_ * 12u, ush = g_ * 8u;
;     h16x8 s_ok[RW_U], s_kr[RW_U]; h16x4 s_b[RW_U]; h16 s_v[RW_U];
;     auto row_of = [&](int step) -> int {
;       if (step < CTX_LEN) return NL + b * CTX_LEN + (dir == 0 ? step : CTX_LEN - 1 - step);
;       const int s = step - CTX_LEN; return b * SEQ + (dir == 0 ? s : SEQ - 1 - s);
;     };
;     ...
; #pragma unroll
;     for (int uu = 0; uu < RW_U; ++uu) RW_LOAD(uu, uu);
.LBB0_3117:
	s_or_b64 exec, exec, s[6:7]
	s_mov_b64 s[4:5], s[96:97]
	s_waitcnt lgkmcnt(0)
	v_mov_b32_e32 v1, v0
	s_barrier
	v_readfirstlane_b32 s1, v0
	s_lshr_b32 s1, s1, 6
	s_lshl_b32 s0, s2, 2
	s_cmp_gt_u32 s0, 0x3ff
	s_cbranch_scc1 .LBB0_3154
	s_cmp_gt_u32 s1, 3
	s_cbranch_scc1 .Lscan_follow
	s_load_dwordx2 s[4:5], s[96:97], 0x178
	v_and_b32_e32 v1, 63, v0
	v_and_b32_e32 v2, 15, v1
	v_lshrrev_b32_e32 v3, 4, v1
	v_lshlrev_b32_e32 v8, 4, v2
	v_lshlrev_b32_e32 v9, 3, v2
	s_lshl_b32 s30, s1, 10
	v_lshl_add_u32 v46, v1, 4, s30
	s_lshl_b32 s30, s1, 9
	v_lshl_add_u32 v47, v1, 3, s30
	s_mov_b32 s20, 0x22222222
	s_mov_b32 s21, 0x22222222
	s_mov_b32 s22, 0x44444444
	s_mov_b32 s23, 0x44444444
	s_mov_b32 s24, 0x88888888
	s_mov_b32 s25, 0x88888888
	s_waitcnt lgkmcnt(0)
.Lscan_unit:
	s_add_u32 s31, s0, s1
	s_and_b32 s26, s31, 15
	s_bfe_u32 s27, s31, 0x40004
	s_bfe_u32 s28, s31, 0x10008
	s_lshr_b32 s29, s31, 9
	s_lshl_b32 s30, s27, 4
	v_add_u32_e32 v4, s30, v2
	v_mul_u32_u24_e32 v5, 24, v4
	v_lshlrev_b32_e32 v6, 4, v4
	s_lshl_b32 s30, s27, 6
	s_lshl_b32 s31, s26, 2
	s_add_u32 s30, s30, s31
	v_add_u32_e32 v7, s30, v3
	v_lshlrev_b32_e32 v7, 1, v7
	s_cmp_lg_u32 s29, 0
	s_cbranch_scc1 .Lscan_dir1
	s_lshl_b32 s30, s1, 2
	v_add_u32_e32 v39, s30, v3
	v_mul_u32_u24_e32 v48, 0x1800, v39
	v_add_u32_e32 v48, v48, v5
	v_lshlrev_b32_e32 v49, 12, v39
	v_add_u32_e32 v49, v49, v6
	v_lshlrev_b32_e32 v38, 11, v2
	v_add_u32_e32 v38, v38, v7
	s_lshl_b32 s30, s28, 8
	s_add_u32 s30, s30, 0x8000
	s_lshl_b32 s31, s28, 14
	s_mul_i32 s3, s30, 0x1800
	s_add_u32 s6, s4, s3
	s_addc_u32 s7, s5, 0
	s_add_u32 s6, s6, 0x23614000
	s_addc_u32 s7, s7, 0
	s_mul_i32 s3, s30, 0x1000
	s_add_u32 s8, s4, s3
	s_addc_u32 s9, s5, 0
	s_add_u32 s8, s8, 0xbe4c000
	s_addc_u32 s9, s9, 0
	s_mul_i32 s3, s30, 0x800
	s_add_u32 s10, s4, s3
	s_addc_u32 s11, s5, 0
	s_add_u32 s10, s10, 0x3bc14000
	s_addc_u32 s11, s11, 0
	s_mul_i32 s3, s31, 0x1800
	s_add_u32 s14, s4, s3
	s_addc_u32 s15, s5, 0
	s_add_u32 s14, s14, 0x23614000
	s_addc_u32 s15, s15, 0
	s_mul_i32 s3, s31, 0x1000
	s_add_u32 s16, s4, s3
	s_addc_u32 s17, s5, 0
	s_add_u32 s16, s16, 0xbe4c000
	s_addc_u32 s17, s17, 0
	s_mul_i32 s3, s31, 0x800
	s_add_u32 s18, s4, s3
	s_addc_u32 s19, s5, 0
	s_add_u32 s18, s18, 0x3bc14000
	s_addc_u32 s19, s19, 0
	s_mul_i32 s3, s31, 0x800
	s_add_u32 s12, s4, s3
	s_addc_u32 s13, s5, 0
	s_add_u32 s12, s12, 0x160cc000
	s_addc_u32 s13, s13, 0
	v_mov_b32_e32 v10, 0
	v_mov_b32_e32 v11, 0
	v_mov_b32_e32 v12, 0
	v_mov_b32_e32 v13, 0
	s_mov_b32 s29, 0
	global_load_ushort v36, v38, s[10:11]
	s_mov_b32 s26, 0
	s_mov_b32 s27, 10240
	s_mov_b32 s28, 0
	v_add_u32_e32 v40, s26, v8
	v_add_u32_e32 v41, s26, v9
	v_add_u32_e32 v42, s27, v8
	v_add_u32_e32 v43, s27, v9
	v_add_u32_e32 v44, s28, v46
	v_add_u32_e32 v45, s28, v47
	global_load_dwordx4 v[50:53], v48, s[6:7]
	global_load_dwordx2 v[54:55], v48, s[6:7] offset:16
	global_load_dwordx4 v[56:59], v49, s[8:9]
	s_add_u32 s29, s29, 1
	s_cmp_eq_u32 s29, 16
	s_cbranch_scc1 .Lscan_stsw_p0_d0
	s_add_u32 s6, s6, 0x18000
	s_addc_u32 s7, s7, 0
	s_add_u32 s8, s8, 0x10000
	s_addc_u32 s9, s9, 0
	s_branch .Lscan_stdone_p0_d0

.Lscan_stdone_p0_d0:
	s_waitcnt vmcnt(0)
	ds_write_b128 v44, v[50:53]
	ds_write_b128 v44, v[56:59] offset:4096
	ds_write_b64 v45, v[54:55] offset:8192
	s_mov_b32 s28, 10240
	v_add_u32_e32 v40, s26, v8
	v_add_u32_e32 v41, s26, v9
	v_add_u32_e32 v42, s27, v8
	v_add_u32_e32 v43, s27, v9
	v_add_u32_e32 v44, s28, v46
	v_add_u32_e32 v45, s28, v47
	global_load_dwordx4 v[50:53], v48, s[6:7]
	global_load_dwordx2 v[54:55], v48, s[6:7] offset:16
	global_load_dwordx4 v[56:59], v49, s[8:9]
	s_add_u32 s29, s29, 1
	s_cmp_eq_u32 s29, 16
	s_cbranch_scc1 .Lscan_stsw_p1_d0
	s_add_u32 s6, s6, 0x18000
	s_addc_u32 s7, s7, 0
	s_add_u32 s8, s8, 0x10000
	s_addc_u32 s9, s9, 0
	s_branch .Lscan_stdone_p1_d0

.Lscan_stdone_p1_d0:
	s_waitcnt vmcnt(0)
	ds_write_b128 v44, v[50:53]
	ds_write_b128 v44, v[56:59] offset:4096
	ds_write_b64 v45, v[54:55] offset:8192
	s_mov_b32 s28, 20480
	v_add_u32_e32 v40, s26, v8
	v_add_u32_e32 v41, s26, v9
	v_add_u32_e32 v42, s27, v8
	v_add_u32_e32 v43, s27, v9
	v_add_u32_e32 v44, s28, v46
	v_add_u32_e32 v45, s28, v47
	global_load_dwordx4 v[50:53], v48, s[6:7]
	global_load_dwordx2 v[54:55], v48, s[6:7] offset:16
	global_load_dwordx4 v[56:59], v49, s[8:9]
	s_add_u32 s29, s29, 1
	s_cmp_eq_u32 s29, 16
	s_cbranch_scc1 .Lscan_stsw_p2_d0
	s_add_u32 s6, s6, 0x18000
	s_addc_u32 s7, s7, 0
	s_add_u32 s8, s8, 0x10000
	s_addc_u32 s9, s9, 0
	s_branch .Lscan_stdone_p2_d0

; __device__ __forceinline__ float row_sum16(float v) { v += __shfl_xor(v, 1); v += __shfl_xor(v, 2); v += __shfl_xor(v, 4); v += __shfl_xor(v, 8); return v; }
; __device__ __forceinline__ float row_sum16(float v) { v += dppf<0xB1>(v); v += dppf<0x4E>(v); v += dppf<0x124>(v); v += dppf<0x128>(v); return v; }
; #define RW_LOAD(slot, step) do { const size_t ro_ = (size_t)row_of(step) * RWW; \
;       s_ok[slot] = *(const h16x8*)((p_rec + ro_ * 3) + urec); s_b[slot] = *(const h16x4*)((p_rec + ro_ * 3) + urec + 8); \
;       s_kr[slot] = *(const h16x8*)((p_sh + ro_ * 2) + ush); s_v[slot] = (p_v + ro_)[uvoff]; } while (0)
; template <int VAR>
; __device__ __forceinline__ void ph_rw_scan(const Params& P) {
;     ...
; #pragma unroll
;     for (int uu = 0; uu < RW_U; ++uu) RW_LOAD(uu, uu);
;     float S[4] = {0.f, 0.f, 0.f, 0.f};
;     for (int t0 = 0; t0 < RW_NS; t0 += RW_U) {
;       const bool islat = t0 >= CTX_LEN;
; #pragma unroll
;       for (int uu = 0; uu < RW_U; ++uu) {
;         const float vv = (float)s_v[uu];
;         const u32x4 p_ok = __builtin_bit_cast(u32x4, s_ok[uu]), p_kr = __builtin_bit_cast(u32x4, s_kr[uu]);
;         const u32x2 p_bb = __builtin_bit_cast(u32x2, s_b[uu]);
;         const unsigned om0 = p_ok[0], om1 = p_ok[1], kd0 = p_ok[2], kd1 = p_ok[3];
;         const unsigned kk0 = p_kr[0], kk1 = p_kr[1], r0_ = p_kr[2], r1_ = p_kr[3];
;         const unsigned b0_ = p_bb[0], b1_ = p_bb[1];
;         float sa = fmix_lo(S[0], kk0, 0.f); sa = fmix_hi(S[1], kk0, sa);
;         float sb = fmix_lo(S[2], kk1, 0.f); sb = fmix_hi(S[3], kk1, sb);
;         sa = row_sum16(sa + sb);
;         S[0] = fmix_lo(S[0], om0, S[0]); S[1] = fmix_hi(S[1], om0, S[1]); S[2] = fmix_lo(S[2], om1, S[2]); S[3] = fmix_hi(S[3], om1, S[3]);
;         S[0] = fmix_lo(sa, b0_, S[0]); S[1] = fmix_hi(sa, b0_, S[1]); S[2] = fmix_lo(sa, b1_, S[2]); S[3] = fmix_hi(sa, b1_, S[3]);
;         S[0] = fmix_lo(vv, kd0, S[0]); S[1] = fmix_hi(vv, kd0, S[1]); S[2] = fmix_lo(vv, kd1, S[2]); S[3] = fmix_hi(vv, kd1, S[3]);
;         float y = fmix_lo(S[0], r0_, 0.f); y = fmix_hi(S[1], r0_, y);
;         float y2 = fmix_lo(S[2], r1_, 0.f); y2 = fmix_hi(S[3], r1_, y2);
.Lscan_stdone_p2_d0:
	s_waitcnt lgkmcnt(0)
	s_barrier
	ds_read_b128 v[60:63], v40
	ds_read_b128 v[66:69], v40 offset:4096
	ds_read_b64 v[64:65], v41 offset:8192
	ds_read_b128 v[70:73], v40 offset:256
	ds_read_b128 v[76:79], v40 offset:4352
	ds_read_b64 v[74:75], v41 offset:8320
	ds_read_b128 v[80:83], v40 offset:512
	ds_read_b128 v[86:89], v40 offset:4608
	ds_read_b64 v[84:85], v41 offset:8448
	s_mov_b32 s3, 0
	s_waitcnt vmcnt(0)
	s_waitcnt lgkmcnt(6)
.Lscan_loop_d0:
	v_mov_b32_dpp v19, v36 row_newbcast:0 row_mask:0xf bank_mask:0xf
	v_fma_mix_f32 v18, v10, v66, 0 op_sel_hi:[0,1,0]
	v_fma_mix_f32 v14, v10, v60, v10 op_sel_hi:[0,1,0]
	v_fma_mix_f32 v18, v11, v66, v18 op_sel:[0,1,0] op_sel_hi:[0,1,0]
	v_fma_mix_f32 v15, v11, v60, v11 op_sel:[0,1,0] op_sel_hi:[0,1,0]
	v_fma_mix_f32 v18, v12, v67, v18 op_sel_hi:[0,1,0]
	v_fma_mix_f32 v16, v12, v61, v12 op_sel_hi:[0,1,0]
	v_fma_mix_f32 v18, v13, v67, v18 op_sel:[0,1,0] op_sel_hi:[0,1,0]
	v_fma_mix_f32 v17, v13, v61, v13 op_sel:[0,1,0] op_sel_hi:[0,1,0]
	v_fma_mix_f32 v14, v19, v62, v14 op_sel_hi:[1,1,0]
	v_fma_mix_f32 v15, v19, v62, v15 op_sel:[0,1,0] op_sel_hi:[1,1,0]
	v_add_f32_dpp v18, v18, v18 quad_perm:[1,0,3,2] row_mask:0xf bank_mask:0xf bound_ctrl:1
	v_fma_mix_f32 v16, v19, v63, v16 op_sel_hi:[1,1,0]
	v_fma_mix_f32 v17, v19, v63, v17 op_sel:[0,1,0] op_sel_hi:[1,1,0]
	v_add_f32_dpp v18, v18, v18 quad_perm:[2,3,0,1] row_mask:0xf bank_mask:0xf bound_ctrl:1
	v_fma_mix_f32 v35, v10, v98, 0 op_sel_hi:[0,1,0]
	v_fma_mix_f32 v35, v11, v98, v35 op_sel:[0,1,0] op_sel_hi:[0,1,0]
	v_add_f32_dpp v18, v18, v18 row_ror:4 row_mask:0xf bank_mask:0xf bound_ctrl:1
	v_fma_mix_f32 v35, v12, v99, v35 op_sel_hi:[0,1,0]
	v_fma_mix_f32 v35, v13, v99, v35 op_sel:[0,1,0] op_sel_hi:[0,1,0]
	v_add_f32_dpp v18, v18, v18 row_ror:8 row_mask:0xf bank_mask:0xf bound_ctrl:1
	s_waitcnt lgkmcnt(3)
	ds_read_b128 v[90:93], v40 offset:768
	v_fma_mix_f32 v10, v18, v64, v14 op_sel_hi:[0,1,0]
	ds_read_b128 v[96:99], v40 offset:4864
	v_fma_mix_f32 v11, v18, v64, v15 op_sel:[0,1,0] op_sel_hi:[0,1,0]
	ds_read_b64 v[94:95], v41 offset:8576
	v_fma_mix_f32 v12, v18, v65, v16 op_sel_hi:[0,1,0]
	v_fma_mix_f32 v13, v18, v65, v17 op_sel:[0,1,0] op_sel_hi:[0,1,0]
	s_cmp_eq_u32 s3, 15
	s_cbranch_scc1 .Lscan_vsw_d0
	s_add_u32 s10, s10, 0x8000
	s_addc_u32 s11, s11, 0
	s_branch .Lscan_vdone_d0
.Lscan_vsw_d0:
	s_mov_b64 s[10:11], s[18:19]
.Lscan_vdone_d0:
	ds_write_b128 v44, v[50:53]
	ds_write_b128 v44, v[56:59] offset:4096
	ds_write_b64 v45, v[54:55] offset:8192
	global_load_dwordx4 v[50:53], v48, s[6:7]
	global_load_dwordx2 v[54:55], v48, s[6:7] offset:16
	global_load_dwordx4 v[56:59], v49, s[8:9]
	global_load_ushort v37, v38, s[10:11]
	s_add_u32 s29, s29, 1
	s_cmp_eq_u32 s29, 16
	s_cbranch_scc1 .Lscan_stsw_lp_d0
	s_add_u32 s6, s6, 0x18000
	s_addc_u32 s7, s7, 0
	s_add_u32 s8, s8, 0x10000
	s_addc_u32 s9, s9, 0
	s_branch .Lscan_stdone_lp_d0

; __device__ __forceinline__ float row_sum16(float v) { v += __shfl_xor(v, 1); v += __shfl_xor(v, 2); v += __shfl_xor(v, 4); v += __shfl_xor(v, 8); return v; }
; __device__ __forceinline__ float row_sum16(float v) { v += dppf<0xB1>(v); v += dppf<0x4E>(v); v += dppf<0x124>(v); v += dppf<0x128>(v); return v; }
; #define RW_LOAD(slot, step) do { const size_t ro_ = (size_t)row_of(step) * RWW; \
;       s_ok[slot] = *(const h16x8*)((p_rec + ro_ * 3) + urec); s_b[slot] = *(const h16x4*)((p_rec + ro_ * 3) + urec + 8); \
;       s_kr[slot] = *(const h16x8*)((p_sh + ro_ * 2) + ush); s_v[slot] = (p_v + ro_)[uvoff]; } while (0)
; template <int VAR>
; __device__ __forceinline__ void ph_rw_scan(const Params& P) {
;     ...
;         float sa = fmix_lo(S[0], kk0, 0.f); sa = fmix_hi(S[1], kk0, sa);
;         float sb = fmix_lo(S[2], kk1, 0.f); sb = fmix_hi(S[3], kk1, sb);
;         sa = row_sum16(sa + sb);
;         S[0] = fmix_lo(S[0], om0, S[0]); S[1] = fmix_hi(S[1], om0, S[1]); S[2] = fmix_lo(S[2], om1, S[2]); S[3] = fmix_hi(S[3], om1, S[3]);
;         S[0] = fmix_lo(sa, b0_, S[0]); S[1] = fmix_hi(sa, b0_, S[1]); S[2] = fmix_lo(sa, b1_, S[2]); S[3] = fmix_hi(sa, b1_, S[3]);
;         S[0] = fmix_lo(vv, kd0, S[0]); S[1] = fmix_hi(vv, kd0, S[1]); S[2] = fmix_lo(vv, kd1, S[2]); S[3] = fmix_hi(vv, kd1, S[3]);
;         float y = fmix_lo(S[0], r0_, 0.f); y = fmix_hi(S[1], r0_, y);
;         float y2 = fmix_lo(S[2], r1_, 0.f); y2 = fmix_hi(S[3], r1_, y2);
;         y += y2;
;         if (VAR == 0 && islat) {
;           y = row_sum16(y);
;           if (q == 0) yout[((size_t)dir * NL + row_of(t0 + uu)) * RWW + hh * 64 + vrow] = (h16)y;
;         }
;         if (VAR != 0) asm volatile("" :: "v"(y));
;         const int nstep = t0 + uu + RW_U < RW_NS ? t0 + uu + RW_U : RW_NS - 1;
;         if (VAR != 2) RW_LOAD(uu, nstep);
.Lscan_stdone_lp_d0:
	s_cmp_lt_u32 s3, 17
	s_cbranch_scc1 .Lscan_noy_d0
	v_add_f32_dpp v20, v20, v20 row_ror:8 row_mask:0xf bank_mask:0xf bound_ctrl:1
	v_add_f32_dpp v21, v21, v21 row_ror:8 row_mask:0xf bank_mask:0xf bound_ctrl:1
	v_add_f32_dpp v22, v22, v22 row_ror:8 row_mask:0xf bank_mask:0xf bound_ctrl:1
	v_add_f32_dpp v23, v23, v23 row_ror:8 row_mask:0xf bank_mask:0xf bound_ctrl:1
	v_add_f32_dpp v24, v24, v24 row_ror:8 row_mask:0xf bank_mask:0xf bound_ctrl:1
	v_add_f32_dpp v25, v25, v25 row_ror:8 row_mask:0xf bank_mask:0xf bound_ctrl:1
	v_add_f32_dpp v26, v26, v26 row_ror:8 row_mask:0xf bank_mask:0xf bound_ctrl:1
	v_add_f32_dpp v27, v27, v27 row_ror:8 row_mask:0xf bank_mask:0xf bound_ctrl:1
	v_add_f32_dpp v20, v28, v28 row_ror:8 row_mask:0xf bank_mask:0xc bound_ctrl:1
	v_add_f32_dpp v21, v29, v29 row_ror:8 row_mask:0xf bank_mask:0xc bound_ctrl:1
	v_add_f32_dpp v22, v30, v30 row_ror:8 row_mask:0xf bank_mask:0xc bound_ctrl:1
	v_add_f32_dpp v23, v31, v31 row_ror:8 row_mask:0xf bank_mask:0xc bound_ctrl:1
	v_add_f32_dpp v24, v32, v32 row_ror:8 row_mask:0xf bank_mask:0xc bound_ctrl:1
	v_add_f32_dpp v25, v33, v33 row_ror:8 row_mask:0xf bank_mask:0xc bound_ctrl:1
	v_add_f32_dpp v26, v34, v34 row_ror:8 row_mask:0xf bank_mask:0xc bound_ctrl:1
	v_add_f32_dpp v27, v35, v35 row_ror:8 row_mask:0xf bank_mask:0xc bound_ctrl:1
	v_add_f32_dpp v20, v20, v20 row_half_mirror row_mask:0xf bank_mask:0xf bound_ctrl:1
	v_add_f32_dpp v21, v21, v21 row_half_mirror row_mask:0xf bank_mask:0xf bound_ctrl:1
	v_add_f32_dpp v22, v22, v22 row_half_mirror row_mask:0xf bank_mask:0xf bound_ctrl:1
	v_add_f32_dpp v23, v23, v23 row_half_mirror row_mask:0xf bank_mask:0xf bound_ctrl:1
	v_add_f32_dpp v20, v24, v24 row_half_mirror row_mask:0xf bank_mask:0xa bound_ctrl:1
	v_add_f32_dpp v21, v25, v25 row_half_mirror row_mask:0xf bank_mask:0xa bound_ctrl:1
	v_add_f32_dpp v22, v26, v26 row_half_mirror row_mask:0xf bank_mask:0xa bound_ctrl:1
	v_add_f32_dpp v23, v27, v27 row_half_mirror row_mask:0xf bank_mask:0xa bound_ctrl:1
	v_add_f32_dpp v20, v20, v20 quad_perm:[1,0,3,2] row_mask:0xf bank_mask:0xf bound_ctrl:1
	v_add_f32_dpp v21, v21, v21 quad_perm:[1,0,3,2] row_mask:0xf bank_mask:0xf bound_ctrl:1
	v_add_f32_dpp v22, v22, v22 quad_perm:[1,0,3,2] row_mask:0xf bank_mask:0xf bound_ctrl:1
	v_add_f32_dpp v23, v23, v23 quad_perm:[1,0,3,2] row_mask:0xf bank_mask:0xf bound_ctrl:1
	v_add_f32_dpp v20, v20, v20 quad_perm:[2,3,0,1] row_mask:0xf bank_mask:0xf bound_ctrl:1
	v_add_f32_dpp v21, v21, v21 quad_perm:[2,3,0,1] row_mask:0xf bank_mask:0xf bound_ctrl:1
	v_add_f32_dpp v22, v22, v22 quad_perm:[2,3,0,1] row_mask:0xf bank_mask:0xf bound_ctrl:1
	v_add_f32_dpp v23, v23, v23 quad_perm:[2,3,0,1] row_mask:0xf bank_mask:0xf bound_ctrl:1
	v_cndmask_b32_e64 v20, v20, v21, s[20:21]
	v_cndmask_b32_e64 v20, v20, v22, s[22:23]
	v_cndmask_b32_e64 v20, v20, v23, s[24:25]
	v_cvt_f16_f32_e32 v39, v20
	global_store_short v38, v39, s[12:13]
	s_add_u32 s12, s12, 0x8000
	s_addc_u32 s13, s13, 0
.Lscan_noy_d0:
	v_mov_b32_dpp v19, v36 row_newbcast:1 row_mask:0xf bank_mask:0xf
	v_fma_mix_f32 v18, v10, v76, 0 op_sel_hi:[0,1,0]
	v_fma_mix_f32 v14, v10, v70, v10 op_sel_hi:[0,1,0]
	v_fma_mix_f32 v18, v11, v76, v18 op_sel:[0,1,0] op_sel_hi:[0,1,0]
	v_fma_mix_f32 v15, v11, v70, v11 op_sel:[0,1,0] op_sel_hi:[0,1,0]
	v_fma_mix_f32 v18, v12, v77, v18 op_sel_hi:[0,1,0]
	v_fma_mix_f32 v16, v12, v71, v12 op_sel_hi:[0,1,0]
	v_fma_mix_f32 v18, v13, v77, v18 op_sel:[0,1,0] op_sel_hi:[0,1,0]
	v_fma_mix_f32 v17, v13, v71, v13 op_sel:[0,1,0] op_sel_hi:[0,1,0]
	v_fma_mix_f32 v14, v19, v72, v14 op_sel_hi:[1,1,0]
	v_fma_mix_f32 v15, v19, v72, v15 op_sel:[0,1,0] op_sel_hi:[1,1,0]
	v_add_f32_dpp v18, v18, v18 quad_perm:[1,0,3,2] row_mask:0xf bank_mask:0xf bound_ctrl:1
	v_fma_mix_f32 v16, v19, v73, v16 op_sel_hi:[1,1,0]
	v_fma_mix_f32 v17, v19, v73, v17 op_sel:[0,1,0] op_sel_hi:[1,1,0]
	v_add_f32_dpp v18, v18, v18 quad_perm:[2,3,0,1] row_mask:0xf bank_mask:0xf bound_ctrl:1
	v_fma_mix_f32 v20, v10, v68, 0 op_sel_hi:[0,1,0]
	v_fma_mix_f32 v20, v11, v68, v20 op_sel:[0,1,0] op_sel_hi:[0,1,0]
	v_add_f32_dpp v18, v18, v18 row_ror:4 row_mask:0xf bank_mask:0xf bound_ctrl:1
	v_fma_mix_f32 v20, v12, v69, v20 op_sel_hi:[0,1,0]
	v_fma_mix_f32 v20, v13, v69, v20 op_sel:[0,1,0] op_sel_hi:[0,1,0]
	v_add_f32_dpp v18, v18, v18 row_ror:8 row_mask:0xf bank_mask:0xf bound_ctrl:1
	s_waitcnt lgkmcnt(3)
	ds_read_b128 v[60:63], v40 offset:1024
	v_fma_mix_f32 v10, v18, v74, v14 op_sel_hi:[0,1,0]
	ds_read_b128 v[66:69], v40 offset:5120
	v_fma_mix_f32 v11, v18, v74, v15 op_sel:[0,1,0] op_sel_hi:[0,1,0]
	ds_read_b64 v[64:65], v41 offset:8704
	v_fma_mix_f32 v12, v18, v75, v16 op_sel_hi:[0,1,0]
	v_fma_mix_f32 v13, v18, v75, v17 op_sel:[0,1,0] op_sel_hi:[0,1,0]
	v_mov_b32_dpp v19, v36 row_newbcast:2 row_mask:0xf bank_mask:0xf
	v_fma_mix_f32 v18, v10, v86, 0 op_sel_hi:[0,1,0]
	v_fma_mix_f32 v14, v10, v80, v10 op_sel_hi:[0,1,0]
	v_fma_mix_f32 v18, v11, v86, v18 op_sel:[0,1,0] op_sel_hi:[0,1,0]
	v_fma_mix_f32 v15, v11, v80, v11 op_sel:[0,1,0] op_sel_hi:[0,1,0]
	v_fma_mix_f32 v18, v12, v87, v18 op_sel_hi:[0,1,0]
	v_fma_mix_f32 v16, v12, v81, v12 op_sel_hi:[0,1,0]
	v_fma_mix_f32 v18, v13, v87, v18 op_sel:[0,1,0] op_sel_hi:[0,1,0]
	v_fma_mix_f32 v17, v13, v81, v13 op_sel:[0,1,0] op_sel_hi:[0,1,0]
	v_fma_mix_f32 v14, v19, v82, v14 op_sel_hi:[1,1,0]
	v_fma_mix_f32 v15, v19, v82, v15 op_sel:[0,1,0] op_sel_hi:[1,1,0]
	v_add_f32_dpp v18, v18, v18 quad_perm:[1,0,3,2] row_mask:0xf bank_mask:0xf bound_ctrl:1
	v_fma_mix_f32 v16, v19, v83, v16 op_sel_hi:[1,1,0]
	v_fma_mix_f32 v17, v19, v83, v17 op_sel:[0,1,0] op_sel_hi:[1,1,0]
	v_add_f32_dpp v18, v18, v18 quad_perm:[2,3,0,1] row_mask:0xf bank_mask:0xf bound_ctrl:1
	v_fma_mix_f32 v21, v10, v78, 0 op_sel_hi:[0,1,0]
	v_fma_mix_f32 v21, v11, v78, v21 op_sel:[0,1,0] op_sel_hi:[0,1,0]
	v_add_f32_dpp v18, v18, v18 row_ror:4 row_mask:0xf bank_mask:0xf bound_ctrl:1
	v_fma_mix_f32 v21, v12, v79, v21 op_sel_hi:[0,1,0]
	v_fma_mix_f32 v21, v13, v79, v21 op_sel:[0,1,0] op_sel_hi:[0,1,0]
	v_add_f32_dpp v18, v18, v18 row_ror:8 row_mask:0xf bank_mask:0xf bound_ctrl:1
	s_waitcnt lgkmcnt(3)
; __device__ __forceinline__ float row_sum16(float v) { v += __shfl_xor(v, 1); v += __shfl_xor(v, 2); v += __shfl_xor(v, 4); v += __shfl_xor(v, 8); return v; }
; __device__ __forceinline__ float row_sum16(float v) { v += dppf<0xB1>(v); v += dppf<0x4E>(v); v += dppf<0x124>(v); v += dppf<0x128>(v); return v; }
; #define RW_LOAD(slot, step) do { const size_t ro_ = (size_t)row_of(step) * RWW; \
;       s_ok[slot] = *(const h16x8*)((p_rec + ro_ * 3) + urec); s_b[slot] = *(const h16x4*)((p_rec + ro_ * 3) + urec + 8); \
;       s_kr[slot] = *(const h16x8*)((p_sh + ro_ * 2) + ush); s_v[slot] = (p_v + ro_)[uvoff]; } while (0)
; template <int VAR>
; __device__ __forceinline__ void ph_rw_scan(const Params& P) {
;     ...
;       for (int uu = 0; uu < RW_U; ++uu) {
;         const float vv = (float)s_v[uu];
;         const u32x4 p_ok = __builtin_bit_cast(u32x4, s_ok[uu]), p_kr = __builtin_bit_cast(u32x4, s_kr[uu]);
;         const u32x2 p_bb = __builtin_bit_cast(u32x2, s_b[uu]);
;         const unsigned om0 = p_ok[0], om1 = p_ok[1], kd0 = p_ok[2], kd1 = p_ok[3];
;         const unsigned kk0 = p_kr[0], kk1 = p_kr[1], r0_ = p_kr[2], r1_ = p_kr[3];
;         const unsigned b0_ = p_bb[0], b1_ = p_bb[1];
;         float sa = fmix_lo(S[0], kk0, 0.f); sa = fmix_hi(S[1], kk0, sa);
;         float sb = fmix_lo(S[2], kk1, 0.f); sb = fmix_hi(S[3], kk1, sb);
;         sa = row_sum16(sa + sb);
;         S[0] = fmix_lo(S[0], om0, S[0]); S[1] = fmix_hi(S[1], om0, S[1]); S[2] = fmix_lo(S[2], om1, S[2]); S[3] = fmix_hi(S[3], om1, S[3]);
;         S[0] = fmix_lo(sa, b0_, S[0]); S[1] = fmix_hi(sa, b0_, S[1]); S[2] = fmix_lo(sa, b1_, S[2]); S[3] = fmix_hi(sa, b1_, S[3]);
;         S[0] = fmix_lo(vv, kd0, S[0]); S[1] = fmix_hi(vv, kd0, S[1]); S[2] = fmix_lo(vv, kd1, S[2]); S[3] = fmix_hi(vv, kd1, S[3]);
;         float y = fmix_lo(S[0], r0_, 0.f); y = fmix_hi(S[1], r0_, y);
;         float y2 = fmix_lo(S[2], r1_, 0.f); y2 = fmix_hi(S[3], r1_, y2);
;         y += y2;
;         if (VAR == 0 && islat) {
;           y = row_sum16(y);
;           if (q == 0) yout[((size_t)dir * NL + row_of(t0 + uu)) * RWW + hh * 64 + vrow] = (h16)y;
;         }
;         if (VAR != 0) asm volatile("" :: "v"(y));
;         const int nstep = t0 + uu + RW_U < RW_NS ? t0 + uu + RW_U : RW_NS - 1;
;         if (VAR != 2) RW_LOAD(uu, nstep);
	ds_read_b128 v[70:73], v40 offset:1280
	v_fma_mix_f32 v10, v18, v84, v14 op_sel_hi:[0,1,0]
	ds_read_b128 v[76:79], v40 offset:5376
	v_fma_mix_f32 v11, v18, v84, v15 op_sel:[0,1,0] op_sel_hi:[0,1,0]
	ds_read_b64 v[74:75], v41 offset:8832
	v_fma_mix_f32 v12, v18, v85, v16 op_sel_hi:[0,1,0]
	v_fma_mix_f32 v13, v18, v85, v17 op_sel:[0,1,0] op_sel_hi:[0,1,0]
	v_mov_b32_dpp v19, v36 row_newbcast:3 row_mask:0xf bank_mask:0xf
	v_fma_mix_f32 v18, v10, v96, 0 op_sel_hi:[0,1,0]
	v_fma_mix_f32 v14, v10, v90, v10 op_sel_hi:[0,1,0]
	v_fma_mix_f32 v18, v11, v96, v18 op_sel:[0,1,0] op_sel_hi:[0,1,0]
	v_fma_mix_f32 v15, v11, v90, v11 op_sel:[0,1,0] op_sel_hi:[0,1,0]
	v_fma_mix_f32 v18, v12, v97, v18 op_sel_hi:[0,1,0]
	v_fma_mix_f32 v16, v12, v91, v12 op_sel_hi:[0,1,0]
	v_fma_mix_f32 v18, v13, v97, v18 op_sel:[0,1,0] op_sel_hi:[0,1,0]
	v_fma_mix_f32 v17, v13, v91, v13 op_sel:[0,1,0] op_sel_hi:[0,1,0]
	v_fma_mix_f32 v14, v19, v92, v14 op_sel_hi:[1,1,0]
	v_fma_mix_f32 v15, v19, v92, v15 op_sel:[0,1,0] op_sel_hi:[1,1,0]
	v_add_f32_dpp v18, v18, v18 quad_perm:[1,0,3,2] row_mask:0xf bank_mask:0xf bound_ctrl:1
	v_fma_mix_f32 v16, v19, v93, v16 op_sel_hi:[1,1,0]
	v_fma_mix_f32 v17, v19, v93, v17 op_sel:[0,1,0] op_sel_hi:[1,1,0]
	v_add_f32_dpp v18, v18, v18 quad_perm:[2,3,0,1] row_mask:0xf bank_mask:0xf bound_ctrl:1
	v_fma_mix_f32 v22, v10, v88, 0 op_sel_hi:[0,1,0]
	v_fma_mix_f32 v22, v11, v88, v22 op_sel:[0,1,0] op_sel_hi:[0,1,0]
	v_add_f32_dpp v18, v18, v18 row_ror:4 row_mask:0xf bank_mask:0xf bound_ctrl:1
	v_fma_mix_f32 v22, v12, v89, v22 op_sel_hi:[0,1,0]
	v_fma_mix_f32 v22, v13, v89, v22 op_sel:[0,1,0] op_sel_hi:[0,1,0]
	v_add_f32_dpp v18, v18, v18 row_ror:8 row_mask:0xf bank_mask:0xf bound_ctrl:1
	s_waitcnt lgkmcnt(3)
	ds_read_b128 v[80:83], v40 offset:1536
	v_fma_mix_f32 v10, v18, v94, v14 op_sel_hi:[0,1,0]
	ds_read_b128 v[86:89], v40 offset:5632
	v_fma_mix_f32 v11, v18, v94, v15 op_sel:[0,1,0] op_sel_hi:[0,1,0]
	ds_read_b64 v[84:85], v41 offset:8960
	v_fma_mix_f32 v12, v18, v95, v16 op_sel_hi:[0,1,0]
	v_fma_mix_f32 v13, v18, v95, v17 op_sel:[0,1,0] op_sel_hi:[0,1,0]
	v_mov_b32_dpp v19, v36 row_newbcast:4 row_mask:0xf bank_mask:0xf
	v_fma_mix_f32 v18, v10, v66, 0 op_sel_hi:[0,1,0]
	v_fma_mix_f32 v14, v10, v60, v10 op_sel_hi:[0,1,0]
	v_fma_mix_f32 v18, v11, v66, v18 op_sel:[0,1,0] op_sel_hi:[0,1,0]
	v_fma_mix_f32 v15, v11, v60, v11 op_sel:[0,1,0] op_sel_hi:[0,1,0]
	v_fma_mix_f32 v18, v12, v67, v18 op_sel_hi:[0,1,0]
	v_fma_mix_f32 v16, v12, v61, v12 op_sel_hi:[0,1,0]
	v_fma_mix_f32 v18, v13, v67, v18 op_sel:[0,1,0] op_sel_hi:[0,1,0]
	v_fma_mix_f32 v17, v13, v61, v13 op_sel:[0,1,0] op_sel_hi:[0,1,0]
	v_fma_mix_f32 v14, v19, v62, v14 op_sel_hi:[1,1,0]
	v_fma_mix_f32 v15, v19, v62, v15 op_sel:[0,1,0] op_sel_hi:[1,1,0]
	v_add_f32_dpp v18, v18, v18 quad_perm:[1,0,3,2] row_mask:0xf bank_mask:0xf bound_ctrl:1
	v_fma_mix_f32 v16, v19, v63, v16 op_sel_hi:[1,1,0]
	v_fma_mix_f32 v17, v19, v63, v17 op_sel:[0,1,0] op_sel_hi:[1,1,0]
	v_add_f32_dpp v18, v18, v18 quad_perm:[2,3,0,1] row_mask:0xf bank_mask:0xf bound_ctrl:1
	v_fma_mix_f32 v23, v10, v98, 0 op_sel_hi:[0,1,0]
	v_fma_mix_f32 v23, v11, v98, v23 op_sel:[0,1,0] op_sel_hi:[0,1,0]
	v_add_f32_dpp v18, v18, v18 row_ror:4 row_mask:0xf bank_mask:0xf bound_ctrl:1
	v_fma_mix_f32 v23, v12, v99, v23 op_sel_hi:[0,1,0]
	v_fma_mix_f32 v23, v13, v99, v23 op_sel:[0,1,0] op_sel_hi:[0,1,0]
	v_add_f32_dpp v18, v18, v18 row_ror:8 row_mask:0xf bank_mask:0xf bound_ctrl:1
	s_waitcnt lgkmcnt(3)
	ds_read_b128 v[90:93], v40 offset:1792
	v_fma_mix_f32 v10, v18, v64, v14 op_sel_hi:[0,1,0]
	ds_read_b128 v[96:99], v40 offset:5888
	v_fma_mix_f32 v11, v18, v64, v15 op_sel:[0,1,0] op_sel_hi:[0,1,0]
	ds_read_b64 v[94:95], v41 offset:9088
	v_fma_mix_f32 v12, v18, v65, v16 op_sel_hi:[0,1,0]
	v_fma_mix_f32 v13, v18, v65, v17 op_sel:[0,1,0] op_sel_hi:[0,1,0]
	v_mov_b32_dpp v19, v36 row_newbcast:5 row_mask:0xf bank_mask:0xf
	v_fma_mix_f32 v18, v10, v76, 0 op_sel_hi:[0,1,0]
	v_fma_mix_f32 v14, v10, v70, v10 op_sel_hi:[0,1,0]
	v_fma_mix_f32 v18, v11, v76, v18 op_sel:[0,1,0] op_sel_hi:[0,1,0]
	v_fma_mix_f32 v15, v11, v70, v11 op_sel:[0,1,0] op_sel_hi:[0,1,0]
	v_fma_mix_f32 v18, v12, v77, v18 op_sel_hi:[0,1,0]
	v_fma_mix_f32 v16, v12, v71, v12 op_sel_hi:[0,1,0]
	v_fma_mix_f32 v18, v13, v77, v18 op_sel:[0,1,0] op_sel_hi:[0,1,0]
	v_fma_mix_f32 v17, v13, v71, v13 op_sel:[0,1,0] op_sel_hi:[0,1,0]
	v_fma_mix_f32 v14, v19, v72, v14 op_sel_hi:[1,1,0]
	v_fma_mix_f32 v15, v19, v72, v15 op_sel:[0,1,0] op_sel_hi:[1,1,0]
	v_add_f32_dpp v18, v18, v18 quad_perm:[1,0,3,2] row_mask:0xf bank_mask:0xf bound_ctrl:1
	v_fma_mix_f32 v16, v19, v73, v16 op_sel_hi:[1,1,0]
	v_fma_mix_f32 v17, v19, v73, v17 op_sel:[0,1,0] op_sel_hi:[1,1,0]
	v_add_f32_dpp v18, v18, v18 quad_perm:[2,3,0,1] row_mask:0xf bank_mask:0xf bound_ctrl:1
	v_fma_mix_f32 v24, v10, v68, 0 op_sel_hi:[0,1,0]
	v_fma_mix_f32 v24, v11, v68, v24 op_sel:[0,1,0] op_sel_hi:[0,1,0]
	v_add_f32_dpp v18, v18, v18 row_ror:4 row_mask:0xf bank_mask:0xf bound_ctrl:1
	v_fma_mix_f32 v24, v12, v69, v24 op_sel_hi:[0,1,0]
	v_fma_mix_f32 v24, v13, v69, v24 op_sel:[0,1,0] op_sel_hi:[0,1,0]
	v_add_f32_dpp v18, v18, v18 row_ror:8 row_mask:0xf bank_mask:0xf bound_ctrl:1
	s_waitcnt lgkmcnt(3)
; __device__ __forceinline__ float row_sum16(float v) { v += __shfl_xor(v, 1); v += __shfl_xor(v, 2); v += __shfl_xor(v, 4); v += __shfl_xor(v, 8); return v; }
; __device__ __forceinline__ float row_sum16(float v) { v += dppf<0xB1>(v); v += dppf<0x4E>(v); v += dppf<0x124>(v); v += dppf<0x128>(v); return v; }
; #define RW_LOAD(slot, step) do { const size_t ro_ = (size_t)row_of(step) * RWW; \
;       s_ok[slot] = *(const h16x8*)((p_rec + ro_ * 3) + urec); s_b[slot] = *(const h16x4*)((p_rec + ro_ * 3) + urec + 8); \
;       s_kr[slot] = *(const h16x8*)((p_sh + ro_ * 2) + ush); s_v[slot] = (p_v + ro_)[uvoff]; } while (0)
; template <int VAR>
; __device__ __forceinline__ void ph_rw_scan(const Params& P) {
;     ...
;       for (int uu = 0; uu < RW_U; ++uu) {
;         const float vv = (float)s_v[uu];
;         const u32x4 p_ok = __builtin_bit_cast(u32x4, s_ok[uu]), p_kr = __builtin_bit_cast(u32x4, s_kr[uu]);
;         const u32x2 p_bb = __builtin_bit_cast(u32x2, s_b[uu]);
;         const unsigned om0 = p_ok[0], om1 = p_ok[1], kd0 = p_ok[2], kd1 = p_ok[3];
;         const unsigned kk0 = p_kr[0], kk1 = p_kr[1], r0_ = p_kr[2], r1_ = p_kr[3];
;         const unsigned b0_ = p_bb[0], b1_ = p_bb[1];
;         float sa = fmix_lo(S[0], kk0, 0.f); sa = fmix_hi(S[1], kk0, sa);
;         float sb = fmix_lo(S[2], kk1, 0.f); sb = fmix_hi(S[3], kk1, sb);
;         sa = row_sum16(sa + sb);
;         S[0] = fmix_lo(S[0], om0, S[0]); S[1] = fmix_hi(S[1], om0, S[1]); S[2] = fmix_lo(S[2], om1, S[2]); S[3] = fmix_hi(S[3], om1, S[3]);
;         S[0] = fmix_lo(sa, b0_, S[0]); S[1] = fmix_hi(sa, b0_, S[1]); S[2] = fmix_lo(sa, b1_, S[2]); S[3] = fmix_hi(sa, b1_, S[3]);
;         S[0] = fmix_lo(vv, kd0, S[0]); S[1] = fmix_hi(vv, kd0, S[1]); S[2] = fmix_lo(vv, kd1, S[2]); S[3] = fmix_hi(vv, kd1, S[3]);
;         float y = fmix_lo(S[0], r0_, 0.f); y = fmix_hi(S[1], r0_, y);
;         float y2 = fmix_lo(S[2], r1_, 0.f); y2 = fmix_hi(S[3], r1_, y2);
;         y += y2;
;         if (VAR == 0 && islat) {
;           y = row_sum16(y);
;           if (q == 0) yout[((size_t)dir * NL + row_of(t0 + uu)) * RWW + hh * 64 + vrow] = (h16)y;
;         }
;         if (VAR != 0) asm volatile("" :: "v"(y));
;         const int nstep = t0 + uu + RW_U < RW_NS ? t0 + uu + RW_U : RW_NS - 1;
;         if (VAR != 2) RW_LOAD(uu, nstep);
	ds_read_b128 v[60:63], v40 offset:2048
	v_fma_mix_f32 v10, v18, v74, v14 op_sel_hi:[0,1,0]
	ds_read_b128 v[66:69], v40 offset:6144
	v_fma_mix_f32 v11, v18, v74, v15 op_sel:[0,1,0] op_sel_hi:[0,1,0]
	ds_read_b64 v[64:65], v41 offset:9216
	v_fma_mix_f32 v12, v18, v75, v16 op_sel_hi:[0,1,0]
	v_fma_mix_f32 v13, v18, v75, v17 op_sel:[0,1,0] op_sel_hi:[0,1,0]
	v_mov_b32_dpp v19, v36 row_newbcast:6 row_mask:0xf bank_mask:0xf
	v_fma_mix_f32 v18, v10, v86, 0 op_sel_hi:[0,1,0]
	v_fma_mix_f32 v14, v10, v80, v10 op_sel_hi:[0,1,0]
	v_fma_mix_f32 v18, v11, v86, v18 op_sel:[0,1,0] op_sel_hi:[0,1,0]
	v_fma_mix_f32 v15, v11, v80, v11 op_sel:[0,1,0] op_sel_hi:[0,1,0]
	v_fma_mix_f32 v18, v12, v87, v18 op_sel_hi:[0,1,0]
	v_fma_mix_f32 v16, v12, v81, v12 op_sel_hi:[0,1,0]
	v_fma_mix_f32 v18, v13, v87, v18 op_sel:[0,1,0] op_sel_hi:[0,1,0]
	v_fma_mix_f32 v17, v13, v81, v13 op_sel:[0,1,0] op_sel_hi:[0,1,0]
	v_fma_mix_f32 v14, v19, v82, v14 op_sel_hi:[1,1,0]
	v_fma_mix_f32 v15, v19, v82, v15 op_sel:[0,1,0] op_sel_hi:[1,1,0]
	v_add_f32_dpp v18, v18, v18 quad_perm:[1,0,3,2] row_mask:0xf bank_mask:0xf bound_ctrl:1
	v_fma_mix_f32 v16, v19, v83, v16 op_sel_hi:[1,1,0]
	v_fma_mix_f32 v17, v19, v83, v17 op_sel:[0,1,0] op_sel_hi:[1,1,0]
	v_add_f32_dpp v18, v18, v18 quad_perm:[2,3,0,1] row_mask:0xf bank_mask:0xf bound_ctrl:1
	v_fma_mix_f32 v25, v10, v78, 0 op_sel_hi:[0,1,0]
	v_fma_mix_f32 v25, v11, v78, v25 op_sel:[0,1,0] op_sel_hi:[0,1,0]
	v_add_f32_dpp v18, v18, v18 row_ror:4 row_mask:0xf bank_mask:0xf bound_ctrl:1
	v_fma_mix_f32 v25, v12, v79, v25 op_sel_hi:[0,1,0]
	v_fma_mix_f32 v25, v13, v79, v25 op_sel:[0,1,0] op_sel_hi:[0,1,0]
	v_add_f32_dpp v18, v18, v18 row_ror:8 row_mask:0xf bank_mask:0xf bound_ctrl:1
	s_waitcnt lgkmcnt(3)
	ds_read_b128 v[70:73], v40 offset:2304
	v_fma_mix_f32 v10, v18, v84, v14 op_sel_hi:[0,1,0]
	ds_read_b128 v[76:79], v40 offset:6400
	v_fma_mix_f32 v11, v18, v84, v15 op_sel:[0,1,0] op_sel_hi:[0,1,0]
	ds_read_b64 v[74:75], v41 offset:9344
	v_fma_mix_f32 v12, v18, v85, v16 op_sel_hi:[0,1,0]
	v_fma_mix_f32 v13, v18, v85, v17 op_sel:[0,1,0] op_sel_hi:[0,1,0]
	v_mov_b32_dpp v19, v36 row_newbcast:7 row_mask:0xf bank_mask:0xf
	v_fma_mix_f32 v18, v10, v96, 0 op_sel_hi:[0,1,0]
	v_fma_mix_f32 v14, v10, v90, v10 op_sel_hi:[0,1,0]
	v_fma_mix_f32 v18, v11, v96, v18 op_sel:[0,1,0] op_sel_hi:[0,1,0]
	v_fma_mix_f32 v15, v11, v90, v11 op_sel:[0,1,0] op_sel_hi:[0,1,0]
	v_fma_mix_f32 v18, v12, v97, v18 op_sel_hi:[0,1,0]
	v_fma_mix_f32 v16, v12, v91, v12 op_sel_hi:[0,1,0]
	v_fma_mix_f32 v18, v13, v97, v18 op_sel:[0,1,0] op_sel_hi:[0,1,0]
	v_fma_mix_f32 v17, v13, v91, v13 op_sel:[0,1,0] op_sel_hi:[0,1,0]
	v_fma_mix_f32 v14, v19, v92, v14 op_sel_hi:[1,1,0]
	v_fma_mix_f32 v15, v19, v92, v15 op_sel:[0,1,0] op_sel_hi:[1,1,0]
	v_add_f32_dpp v18, v18, v18 quad_perm:[1,0,3,2] row_mask:0xf bank_mask:0xf bound_ctrl:1
	v_fma_mix_f32 v16, v19, v93, v16 op_sel_hi:[1,1,0]
	v_fma_mix_f32 v17, v19, v93, v17 op_sel:[0,1,0] op_sel_hi:[1,1,0]
	v_add_f32_dpp v18, v18, v18 quad_perm:[2,3,0,1] row_mask:0xf bank_mask:0xf bound_ctrl:1
	v_fma_mix_f32 v26, v10, v88, 0 op_sel_hi:[0,1,0]
	v_fma_mix_f32 v26, v11, v88, v26 op_sel:[0,1,0] op_sel_hi:[0,1,0]
	v_add_f32_dpp v18, v18, v18 row_ror:4 row_mask:0xf bank_mask:0xf bound_ctrl:1
	v_fma_mix_f32 v26, v12, v89, v26 op_sel_hi:[0,1,0]
	v_fma_mix_f32 v26, v13, v89, v26 op_sel:[0,1,0] op_sel_hi:[0,1,0]
	v_add_f32_dpp v18, v18, v18 row_ror:8 row_mask:0xf bank_mask:0xf bound_ctrl:1
	s_waitcnt lgkmcnt(3)
	ds_read_b128 v[80:83], v40 offset:2560
	v_fma_mix_f32 v10, v18, v94, v14 op_sel_hi:[0,1,0]
	ds_read_b128 v[86:89], v40 offset:6656
	v_fma_mix_f32 v11, v18, v94, v15 op_sel:[0,1,0] op_sel_hi:[0,1,0]
	ds_read_b64 v[84:85], v41 offset:9472
	v_fma_mix_f32 v12, v18, v95, v16 op_sel_hi:[0,1,0]
	v_fma_mix_f32 v13, v18, v95, v17 op_sel:[0,1,0] op_sel_hi:[0,1,0]
	v_mov_b32_dpp v19, v36 row_newbcast:8 row_mask:0xf bank_mask:0xf
	v_fma_mix_f32 v18, v10, v66, 0 op_sel_hi:[0,1,0]
	v_fma_mix_f32 v14, v10, v60, v10 op_sel_hi:[0,1,0]
	v_fma_mix_f32 v18, v11, v66, v18 op_sel:[0,1,0] op_sel_hi:[0,1,0]
	v_fma_mix_f32 v15, v11, v60, v11 op_sel:[0,1,0] op_sel_hi:[0,1,0]
	v_fma_mix_f32 v18, v12, v67, v18 op_sel_hi:[0,1,0]
	v_fma_mix_f32 v16, v12, v61, v12 op_sel_hi:[0,1,0]
	v_fma_mix_f32 v18, v13, v67, v18 op_sel:[0,1,0] op_sel_hi:[0,1,0]
	v_fma_mix_f32 v17, v13, v61, v13 op_sel:[0,1,0] op_sel_hi:[0,1,0]
	v_fma_mix_f32 v14, v19, v62, v14 op_sel_hi:[1,1,0]
	v_fma_mix_f32 v15, v19, v62, v15 op_sel:[0,1,0] op_sel_hi:[1,1,0]
	v_add_f32_dpp v18, v18, v18 quad_perm:[1,0,3,2] row_mask:0xf bank_mask:0xf bound_ctrl:1
	v_fma_mix_f32 v16, v19, v63, v16 op_sel_hi:[1,1,0]
	v_fma_mix_f32 v17, v19, v63, v17 op_sel:[0,1,0] op_sel_hi:[1,1,0]
	v_add_f32_dpp v18, v18, v18 quad_perm:[2,3,0,1] row_mask:0xf bank_mask:0xf bound_ctrl:1
	v_fma_mix_f32 v27, v10, v98, 0 op_sel_hi:[0,1,0]
	v_fma_mix_f32 v27, v11, v98, v27 op_sel:[0,1,0] op_sel_hi:[0,1,0]
	v_add_f32_dpp v18, v18, v18 row_ror:4 row_mask:0xf bank_mask:0xf bound_ctrl:1
	v_fma_mix_f32 v27, v12, v99, v27 op_sel_hi:[0,1,0]
	v_fma_mix_f32 v27, v13, v99, v27 op_sel:[0,1,0] op_sel_hi:[0,1,0]
	v_add_f32_dpp v18, v18, v18 row_ror:8 row_mask:0xf bank_mask:0xf bound_ctrl:1
	s_waitcnt lgkmcnt(3)
; __device__ __forceinline__ float row_sum16(float v) { v += __shfl_xor(v, 1); v += __shfl_xor(v, 2); v += __shfl_xor(v, 4); v += __shfl_xor(v, 8); return v; }
; __device__ __forceinline__ float row_sum16(float v) { v += dppf<0xB1>(v); v += dppf<0x4E>(v); v += dppf<0x124>(v); v += dppf<0x128>(v); return v; }
; #define RW_LOAD(slot, step) do { const size_t ro_ = (size_t)row_of(step) * RWW; \
;       s_ok[slot] = *(const h16x8*)((p_rec + ro_ * 3) + urec); s_b[slot] = *(const h16x4*)((p_rec + ro_ * 3) + urec + 8); \
;       s_kr[slot] = *(const h16x8*)((p_sh + ro_ * 2) + ush); s_v[slot] = (p_v + ro_)[uvoff]; } while (0)
; template <int VAR>
; __device__ __forceinline__ void ph_rw_scan(const Params& P) {
;     ...
;       for (int uu = 0; uu < RW_U; ++uu) {
;         const float vv = (float)s_v[uu];
;         const u32x4 p_ok = __builtin_bit_cast(u32x4, s_ok[uu]), p_kr = __builtin_bit_cast(u32x4, s_kr[uu]);
;         const u32x2 p_bb = __builtin_bit_cast(u32x2, s_b[uu]);
;         const unsigned om0 = p_ok[0], om1 = p_ok[1], kd0 = p_ok[2], kd1 = p_ok[3];
;         const unsigned kk0 = p_kr[0], kk1 = p_kr[1], r0_ = p_kr[2], r1_ = p_kr[3];
;         const unsigned b0_ = p_bb[0], b1_ = p_bb[1];
;         float sa = fmix_lo(S[0], kk0, 0.f); sa = fmix_hi(S[1], kk0, sa);
;         float sb = fmix_lo(S[2], kk1, 0.f); sb = fmix_hi(S[3], kk1, sb);
;         sa = row_sum16(sa + sb);
;         S[0] = fmix_lo(S[0], om0, S[0]); S[1] = fmix_hi(S[1], om0, S[1]); S[2] = fmix_lo(S[2], om1, S[2]); S[3] = fmix_hi(S[3], om1, S[3]);
;         S[0] = fmix_lo(sa, b0_, S[0]); S[1] = fmix_hi(sa, b0_, S[1]); S[2] = fmix_lo(sa, b1_, S[2]); S[3] = fmix_hi(sa, b1_, S[3]);
;         S[0] = fmix_lo(vv, kd0, S[0]); S[1] = fmix_hi(vv, kd0, S[1]); S[2] = fmix_lo(vv, kd1, S[2]); S[3] = fmix_hi(vv, kd1, S[3]);
;         float y = fmix_lo(S[0], r0_, 0.f); y = fmix_hi(S[1], r0_, y);
;         float y2 = fmix_lo(S[2], r1_, 0.f); y2 = fmix_hi(S[3], r1_, y2);
;         y += y2;
;         if (VAR == 0 && islat) {
;           y = row_sum16(y);
;           if (q == 0) yout[((size_t)dir * NL + row_of(t0 + uu)) * RWW + hh * 64 + vrow] = (h16)y;
;         }
;         if (VAR != 0) asm volatile("" :: "v"(y));
;         const int nstep = t0 + uu + RW_U < RW_NS ? t0 + uu + RW_U : RW_NS - 1;
;         if (VAR != 2) RW_LOAD(uu, nstep);
	ds_read_b128 v[90:93], v40 offset:2816
	v_fma_mix_f32 v10, v18, v64, v14 op_sel_hi:[0,1,0]
	ds_read_b128 v[96:99], v40 offset:6912
	v_fma_mix_f32 v11, v18, v64, v15 op_sel:[0,1,0] op_sel_hi:[0,1,0]
	ds_read_b64 v[94:95], v41 offset:9600
	v_fma_mix_f32 v12, v18, v65, v16 op_sel_hi:[0,1,0]
	v_fma_mix_f32 v13, v18, v65, v17 op_sel:[0,1,0] op_sel_hi:[0,1,0]
	v_mov_b32_dpp v19, v36 row_newbcast:9 row_mask:0xf bank_mask:0xf
	v_fma_mix_f32 v18, v10, v76, 0 op_sel_hi:[0,1,0]
	v_fma_mix_f32 v14, v10, v70, v10 op_sel_hi:[0,1,0]
	v_fma_mix_f32 v18, v11, v76, v18 op_sel:[0,1,0] op_sel_hi:[0,1,0]
	v_fma_mix_f32 v15, v11, v70, v11 op_sel:[0,1,0] op_sel_hi:[0,1,0]
	v_fma_mix_f32 v18, v12, v77, v18 op_sel_hi:[0,1,0]
	v_fma_mix_f32 v16, v12, v71, v12 op_sel_hi:[0,1,0]
	v_fma_mix_f32 v18, v13, v77, v18 op_sel:[0,1,0] op_sel_hi:[0,1,0]
	v_fma_mix_f32 v17, v13, v71, v13 op_sel:[0,1,0] op_sel_hi:[0,1,0]
	v_fma_mix_f32 v14, v19, v72, v14 op_sel_hi:[1,1,0]
	v_fma_mix_f32 v15, v19, v72, v15 op_sel:[0,1,0] op_sel_hi:[1,1,0]
	v_add_f32_dpp v18, v18, v18 quad_perm:[1,0,3,2] row_mask:0xf bank_mask:0xf bound_ctrl:1
	v_fma_mix_f32 v16, v19, v73, v16 op_sel_hi:[1,1,0]
	v_fma_mix_f32 v17, v19, v73, v17 op_sel:[0,1,0] op_sel_hi:[1,1,0]
	v_add_f32_dpp v18, v18, v18 quad_perm:[2,3,0,1] row_mask:0xf bank_mask:0xf bound_ctrl:1
	v_fma_mix_f32 v28, v10, v68, 0 op_sel_hi:[0,1,0]
	v_fma_mix_f32 v28, v11, v68, v28 op_sel:[0,1,0] op_sel_hi:[0,1,0]
	v_add_f32_dpp v18, v18, v18 row_ror:4 row_mask:0xf bank_mask:0xf bound_ctrl:1
	v_fma_mix_f32 v28, v12, v69, v28 op_sel_hi:[0,1,0]
	v_fma_mix_f32 v28, v13, v69, v28 op_sel:[0,1,0] op_sel_hi:[0,1,0]
	v_add_f32_dpp v18, v18, v18 row_ror:8 row_mask:0xf bank_mask:0xf bound_ctrl:1
	s_waitcnt lgkmcnt(3)
	ds_read_b128 v[60:63], v40 offset:3072
	v_fma_mix_f32 v10, v18, v74, v14 op_sel_hi:[0,1,0]
	ds_read_b128 v[66:69], v40 offset:7168
	v_fma_mix_f32 v11, v18, v74, v15 op_sel:[0,1,0] op_sel_hi:[0,1,0]
	ds_read_b64 v[64:65], v41 offset:9728
	v_fma_mix_f32 v12, v18, v75, v16 op_sel_hi:[0,1,0]
	v_fma_mix_f32 v13, v18, v75, v17 op_sel:[0,1,0] op_sel_hi:[0,1,0]
	v_mov_b32_dpp v19, v36 row_newbcast:10 row_mask:0xf bank_mask:0xf
	v_fma_mix_f32 v18, v10, v86, 0 op_sel_hi:[0,1,0]
	v_fma_mix_f32 v14, v10, v80, v10 op_sel_hi:[0,1,0]
	v_fma_mix_f32 v18, v11, v86, v18 op_sel:[0,1,0] op_sel_hi:[0,1,0]
	v_fma_mix_f32 v15, v11, v80, v11 op_sel:[0,1,0] op_sel_hi:[0,1,0]
	v_fma_mix_f32 v18, v12, v87, v18 op_sel_hi:[0,1,0]
	v_fma_mix_f32 v16, v12, v81, v12 op_sel_hi:[0,1,0]
	v_fma_mix_f32 v18, v13, v87, v18 op_sel:[0,1,0] op_sel_hi:[0,1,0]
	v_fma_mix_f32 v17, v13, v81, v13 op_sel:[0,1,0] op_sel_hi:[0,1,0]
	v_fma_mix_f32 v14, v19, v82, v14 op_sel_hi:[1,1,0]
	v_fma_mix_f32 v15, v19, v82, v15 op_sel:[0,1,0] op_sel_hi:[1,1,0]
	v_add_f32_dpp v18, v18, v18 quad_perm:[1,0,3,2] row_mask:0xf bank_mask:0xf bound_ctrl:1
	v_fma_mix_f32 v16, v19, v83, v16 op_sel_hi:[1,1,0]
	v_fma_mix_f32 v17, v19, v83, v17 op_sel:[0,1,0] op_sel_hi:[1,1,0]
	v_add_f32_dpp v18, v18, v18 quad_perm:[2,3,0,1] row_mask:0xf bank_mask:0xf bound_ctrl:1
	v_fma_mix_f32 v29, v10, v78, 0 op_sel_hi:[0,1,0]
	v_fma_mix_f32 v29, v11, v78, v29 op_sel:[0,1,0] op_sel_hi:[0,1,0]
	v_add_f32_dpp v18, v18, v18 row_ror:4 row_mask:0xf bank_mask:0xf bound_ctrl:1
	v_fma_mix_f32 v29, v12, v79, v29 op_sel_hi:[0,1,0]
	v_fma_mix_f32 v29, v13, v79, v29 op_sel:[0,1,0] op_sel_hi:[0,1,0]
	v_add_f32_dpp v18, v18, v18 row_ror:8 row_mask:0xf bank_mask:0xf bound_ctrl:1
	s_waitcnt lgkmcnt(3)
	ds_read_b128 v[70:73], v40 offset:3328
	v_fma_mix_f32 v10, v18, v84, v14 op_sel_hi:[0,1,0]
	ds_read_b128 v[76:79], v40 offset:7424
	v_fma_mix_f32 v11, v18, v84, v15 op_sel:[0,1,0] op_sel_hi:[0,1,0]
	ds_read_b64 v[74:75], v41 offset:9856
	v_fma_mix_f32 v12, v18, v85, v16 op_sel_hi:[0,1,0]
	v_fma_mix_f32 v13, v18, v85, v17 op_sel:[0,1,0] op_sel_hi:[0,1,0]
	v_mov_b32_dpp v19, v36 row_newbcast:11 row_mask:0xf bank_mask:0xf
	v_fma_mix_f32 v18, v10, v96, 0 op_sel_hi:[0,1,0]
	v_fma_mix_f32 v14, v10, v90, v10 op_sel_hi:[0,1,0]
	v_fma_mix_f32 v18, v11, v96, v18 op_sel:[0,1,0] op_sel_hi:[0,1,0]
	v_fma_mix_f32 v15, v11, v90, v11 op_sel:[0,1,0] op_sel_hi:[0,1,0]
	v_fma_mix_f32 v18, v12, v97, v18 op_sel_hi:[0,1,0]
	v_fma_mix_f32 v16, v12, v91, v12 op_sel_hi:[0,1,0]
	v_fma_mix_f32 v18, v13, v97, v18 op_sel:[0,1,0] op_sel_hi:[0,1,0]
	v_fma_mix_f32 v17, v13, v91, v13 op_sel:[0,1,0] op_sel_hi:[0,1,0]
	v_fma_mix_f32 v14, v19, v92, v14 op_sel_hi:[1,1,0]
	v_fma_mix_f32 v15, v19, v92, v15 op_sel:[0,1,0] op_sel_hi:[1,1,0]
	v_add_f32_dpp v18, v18, v18 quad_perm:[1,0,3,2] row_mask:0xf bank_mask:0xf bound_ctrl:1
	v_fma_mix_f32 v16, v19, v93, v16 op_sel_hi:[1,1,0]
	v_fma_mix_f32 v17, v19, v93, v17 op_sel:[0,1,0] op_sel_hi:[1,1,0]
	v_add_f32_dpp v18, v18, v18 quad_perm:[2,3,0,1] row_mask:0xf bank_mask:0xf bound_ctrl:1
	v_fma_mix_f32 v30, v10, v88, 0 op_sel_hi:[0,1,0]
	v_fma_mix_f32 v30, v11, v88, v30 op_sel:[0,1,0] op_sel_hi:[0,1,0]
	v_add_f32_dpp v18, v18, v18 row_ror:4 row_mask:0xf bank_mask:0xf bound_ctrl:1
	v_fma_mix_f32 v30, v12, v89, v30 op_sel_hi:[0,1,0]
	v_fma_mix_f32 v30, v13, v89, v30 op_sel:[0,1,0] op_sel_hi:[0,1,0]
	v_add_f32_dpp v18, v18, v18 row_ror:8 row_mask:0xf bank_mask:0xf bound_ctrl:1
	s_waitcnt lgkmcnt(3)
; __device__ __forceinline__ float row_sum16(float v) { v += __shfl_xor(v, 1); v += __shfl_xor(v, 2); v += __shfl_xor(v, 4); v += __shfl_xor(v, 8); return v; }
; __device__ __forceinline__ float row_sum16(float v) { v += dppf<0xB1>(v); v += dppf<0x4E>(v); v += dppf<0x124>(v); v += dppf<0x128>(v); return v; }
; #define RW_LOAD(slot, step) do { const size_t ro_ = (size_t)row_of(step) * RWW; \
;       s_ok[slot] = *(const h16x8*)((p_rec + ro_ * 3) + urec); s_b[slot] = *(const h16x4*)((p_rec + ro_ * 3) + urec + 8); \
;       s_kr[slot] = *(const h16x8*)((p_sh + ro_ * 2) + ush); s_v[slot] = (p_v + ro_)[uvoff]; } while (0)
; template <int VAR>
; __device__ __forceinline__ void ph_rw_scan(const Params& P) {
;     ...
;       for (int uu = 0; uu < RW_U; ++uu) {
;         const float vv = (float)s_v[uu];
;         const u32x4 p_ok = __builtin_bit_cast(u32x4, s_ok[uu]), p_kr = __builtin_bit_cast(u32x4, s_kr[uu]);
;         const u32x2 p_bb = __builtin_bit_cast(u32x2, s_b[uu]);
;         const unsigned om0 = p_ok[0], om1 = p_ok[1], kd0 = p_ok[2], kd1 = p_ok[3];
;         const unsigned kk0 = p_kr[0], kk1 = p_kr[1], r0_ = p_kr[2], r1_ = p_kr[3];
;         const unsigned b0_ = p_bb[0], b1_ = p_bb[1];
;         float sa = fmix_lo(S[0], kk0, 0.f); sa = fmix_hi(S[1], kk0, sa);
;         float sb = fmix_lo(S[2], kk1, 0.f); sb = fmix_hi(S[3], kk1, sb);
;         sa = row_sum16(sa + sb);
;         S[0] = fmix_lo(S[0], om0, S[0]); S[1] = fmix_hi(S[1], om0, S[1]); S[2] = fmix_lo(S[2], om1, S[2]); S[3] = fmix_hi(S[3], om1, S[3]);
;         S[0] = fmix_lo(sa, b0_, S[0]); S[1] = fmix_hi(sa, b0_, S[1]); S[2] = fmix_lo(sa, b1_, S[2]); S[3] = fmix_hi(sa, b1_, S[3]);
;         S[0] = fmix_lo(vv, kd0, S[0]); S[1] = fmix_hi(vv, kd0, S[1]); S[2] = fmix_lo(vv, kd1, S[2]); S[3] = fmix_hi(vv, kd1, S[3]);
;         float y = fmix_lo(S[0], r0_, 0.f); y = fmix_hi(S[1], r0_, y);
;         float y2 = fmix_lo(S[2], r1_, 0.f); y2 = fmix_hi(S[3], r1_, y2);
;         y += y2;
;         if (VAR == 0 && islat) {
;           y = row_sum16(y);
;           if (q == 0) yout[((size_t)dir * NL + row_of(t0 + uu)) * RWW + hh * 64 + vrow] = (h16)y;
;         }
;         if (VAR != 0) asm volatile("" :: "v"(y));
;         const int nstep = t0 + uu + RW_U < RW_NS ? t0 + uu + RW_U : RW_NS - 1;
;         if (VAR != 2) RW_LOAD(uu, nstep);
	ds_read_b128 v[80:83], v40 offset:3584
	v_fma_mix_f32 v10, v18, v94, v14 op_sel_hi:[0,1,0]
	ds_read_b128 v[86:89], v40 offset:7680
	v_fma_mix_f32 v11, v18, v94, v15 op_sel:[0,1,0] op_sel_hi:[0,1,0]
	ds_read_b64 v[84:85], v41 offset:9984
	v_fma_mix_f32 v12, v18, v95, v16 op_sel_hi:[0,1,0]
	v_fma_mix_f32 v13, v18, v95, v17 op_sel:[0,1,0] op_sel_hi:[0,1,0]
	v_mov_b32_dpp v19, v36 row_newbcast:12 row_mask:0xf bank_mask:0xf
	v_fma_mix_f32 v18, v10, v66, 0 op_sel_hi:[0,1,0]
	v_fma_mix_f32 v14, v10, v60, v10 op_sel_hi:[0,1,0]
	v_fma_mix_f32 v18, v11, v66, v18 op_sel:[0,1,0] op_sel_hi:[0,1,0]
	v_fma_mix_f32 v15, v11, v60, v11 op_sel:[0,1,0] op_sel_hi:[0,1,0]
	v_fma_mix_f32 v18, v12, v67, v18 op_sel_hi:[0,1,0]
	v_fma_mix_f32 v16, v12, v61, v12 op_sel_hi:[0,1,0]
	v_fma_mix_f32 v18, v13, v67, v18 op_sel:[0,1,0] op_sel_hi:[0,1,0]
	v_fma_mix_f32 v17, v13, v61, v13 op_sel:[0,1,0] op_sel_hi:[0,1,0]
	v_fma_mix_f32 v14, v19, v62, v14 op_sel_hi:[1,1,0]
	v_fma_mix_f32 v15, v19, v62, v15 op_sel:[0,1,0] op_sel_hi:[1,1,0]
	v_add_f32_dpp v18, v18, v18 quad_perm:[1,0,3,2] row_mask:0xf bank_mask:0xf bound_ctrl:1
	v_fma_mix_f32 v16, v19, v63, v16 op_sel_hi:[1,1,0]
	v_fma_mix_f32 v17, v19, v63, v17 op_sel:[0,1,0] op_sel_hi:[1,1,0]
	v_add_f32_dpp v18, v18, v18 quad_perm:[2,3,0,1] row_mask:0xf bank_mask:0xf bound_ctrl:1
	v_fma_mix_f32 v31, v10, v98, 0 op_sel_hi:[0,1,0]
	v_fma_mix_f32 v31, v11, v98, v31 op_sel:[0,1,0] op_sel_hi:[0,1,0]
	v_add_f32_dpp v18, v18, v18 row_ror:4 row_mask:0xf bank_mask:0xf bound_ctrl:1
	v_fma_mix_f32 v31, v12, v99, v31 op_sel_hi:[0,1,0]
	v_fma_mix_f32 v31, v13, v99, v31 op_sel:[0,1,0] op_sel_hi:[0,1,0]
	v_add_f32_dpp v18, v18, v18 row_ror:8 row_mask:0xf bank_mask:0xf bound_ctrl:1
	s_waitcnt lgkmcnt(3)
	ds_read_b128 v[90:93], v40 offset:3840
	v_fma_mix_f32 v10, v18, v64, v14 op_sel_hi:[0,1,0]
	ds_read_b128 v[96:99], v40 offset:7936
	v_fma_mix_f32 v11, v18, v64, v15 op_sel:[0,1,0] op_sel_hi:[0,1,0]
	ds_read_b64 v[94:95], v41 offset:10112
	v_fma_mix_f32 v12, v18, v65, v16 op_sel_hi:[0,1,0]
	v_fma_mix_f32 v13, v18, v65, v17 op_sel:[0,1,0] op_sel_hi:[0,1,0]
	v_mov_b32_dpp v19, v36 row_newbcast:13 row_mask:0xf bank_mask:0xf
	v_fma_mix_f32 v18, v10, v76, 0 op_sel_hi:[0,1,0]
	v_fma_mix_f32 v14, v10, v70, v10 op_sel_hi:[0,1,0]
	v_fma_mix_f32 v18, v11, v76, v18 op_sel:[0,1,0] op_sel_hi:[0,1,0]
	v_fma_mix_f32 v15, v11, v70, v11 op_sel:[0,1,0] op_sel_hi:[0,1,0]
	v_fma_mix_f32 v18, v12, v77, v18 op_sel_hi:[0,1,0]
	v_fma_mix_f32 v16, v12, v71, v12 op_sel_hi:[0,1,0]
	v_fma_mix_f32 v18, v13, v77, v18 op_sel:[0,1,0] op_sel_hi:[0,1,0]
	v_fma_mix_f32 v17, v13, v71, v13 op_sel:[0,1,0] op_sel_hi:[0,1,0]
	v_fma_mix_f32 v14, v19, v72, v14 op_sel_hi:[1,1,0]
	v_fma_mix_f32 v15, v19, v72, v15 op_sel:[0,1,0] op_sel_hi:[1,1,0]
	v_add_f32_dpp v18, v18, v18 quad_perm:[1,0,3,2] row_mask:0xf bank_mask:0xf bound_ctrl:1
	v_fma_mix_f32 v16, v19, v73, v16 op_sel_hi:[1,1,0]
	v_fma_mix_f32 v17, v19, v73, v17 op_sel:[0,1,0] op_sel_hi:[1,1,0]
	v_add_f32_dpp v18, v18, v18 quad_perm:[2,3,0,1] row_mask:0xf bank_mask:0xf bound_ctrl:1
	v_fma_mix_f32 v32, v10, v68, 0 op_sel_hi:[0,1,0]
	v_fma_mix_f32 v32, v11, v68, v32 op_sel:[0,1,0] op_sel_hi:[0,1,0]
	v_add_f32_dpp v18, v18, v18 row_ror:4 row_mask:0xf bank_mask:0xf bound_ctrl:1
	v_fma_mix_f32 v32, v12, v69, v32 op_sel_hi:[0,1,0]
	v_fma_mix_f32 v32, v13, v69, v32 op_sel:[0,1,0] op_sel_hi:[0,1,0]
	v_add_f32_dpp v18, v18, v18 row_ror:8 row_mask:0xf bank_mask:0xf bound_ctrl:1
	s_waitcnt lgkmcnt(3)
	ds_read_b128 v[60:63], v42
	v_fma_mix_f32 v10, v18, v74, v14 op_sel_hi:[0,1,0]
	ds_read_b128 v[66:69], v42 offset:4096
	v_fma_mix_f32 v11, v18, v74, v15 op_sel:[0,1,0] op_sel_hi:[0,1,0]
	ds_read_b64 v[64:65], v43 offset:8192
	v_fma_mix_f32 v12, v18, v75, v16 op_sel_hi:[0,1,0]
	v_fma_mix_f32 v13, v18, v75, v17 op_sel:[0,1,0] op_sel_hi:[0,1,0]
	v_mov_b32_dpp v19, v36 row_newbcast:14 row_mask:0xf bank_mask:0xf
	v_fma_mix_f32 v18, v10, v86, 0 op_sel_hi:[0,1,0]
	v_fma_mix_f32 v14, v10, v80, v10 op_sel_hi:[0,1,0]
	v_fma_mix_f32 v18, v11, v86, v18 op_sel:[0,1,0] op_sel_hi:[0,1,0]
	v_fma_mix_f32 v15, v11, v80, v11 op_sel:[0,1,0] op_sel_hi:[0,1,0]
	v_fma_mix_f32 v18, v12, v87, v18 op_sel_hi:[0,1,0]
	v_fma_mix_f32 v16, v12, v81, v12 op_sel_hi:[0,1,0]
	v_fma_mix_f32 v18, v13, v87, v18 op_sel:[0,1,0] op_sel_hi:[0,1,0]
	v_fma_mix_f32 v17, v13, v81, v13 op_sel:[0,1,0] op_sel_hi:[0,1,0]
	v_fma_mix_f32 v14, v19, v82, v14 op_sel_hi:[1,1,0]
	v_fma_mix_f32 v15, v19, v82, v15 op_sel:[0,1,0] op_sel_hi:[1,1,0]
	v_add_f32_dpp v18, v18, v18 quad_perm:[1,0,3,2] row_mask:0xf bank_mask:0xf bound_ctrl:1
	v_fma_mix_f32 v16, v19, v83, v16 op_sel_hi:[1,1,0]
	v_fma_mix_f32 v17, v19, v83, v17 op_sel:[0,1,0] op_sel_hi:[1,1,0]
	v_add_f32_dpp v18, v18, v18 quad_perm:[2,3,0,1] row_mask:0xf bank_mask:0xf bound_ctrl:1
	v_fma_mix_f32 v33, v10, v78, 0 op_sel_hi:[0,1,0]
	v_fma_mix_f32 v33, v11, v78, v33 op_sel:[0,1,0] op_sel_hi:[0,1,0]
	v_add_f32_dpp v18, v18, v18 row_ror:4 row_mask:0xf bank_mask:0xf bound_ctrl:1
	v_fma_mix_f32 v33, v12, v79, v33 op_sel_hi:[0,1,0]
	v_fma_mix_f32 v33, v13, v79, v33 op_sel:[0,1,0] op_sel_hi:[0,1,0]
	v_add_f32_dpp v18, v18, v18 row_ror:8 row_mask:0xf bank_mask:0xf bound_ctrl:1
	s_waitcnt lgkmcnt(3)
; __device__ __forceinline__ float row_sum16(float v) { v += __shfl_xor(v, 1); v += __shfl_xor(v, 2); v += __shfl_xor(v, 4); v += __shfl_xor(v, 8); return v; }
; __device__ __forceinline__ float row_sum16(float v) { v += dppf<0xB1>(v); v += dppf<0x4E>(v); v += dppf<0x124>(v); v += dppf<0x128>(v); return v; }
; #define RW_LOAD(slot, step) do { const size_t ro_ = (size_t)row_of(step) * RWW; \
;       s_ok[slot] = *(const h16x8*)((p_rec + ro_ * 3) + urec); s_b[slot] = *(const h16x4*)((p_rec + ro_ * 3) + urec + 8); \
;       s_kr[slot] = *(const h16x8*)((p_sh + ro_ * 2) + ush); s_v[slot] = (p_v + ro_)[uvoff]; } while (0)
; template <int VAR>
; __device__ __forceinline__ void ph_rw_scan(const Params& P) {
;     ...
;         float sa = fmix_lo(S[0], kk0, 0.f); sa = fmix_hi(S[1], kk0, sa);
;         float sb = fmix_lo(S[2], kk1, 0.f); sb = fmix_hi(S[3], kk1, sb);
;         sa = row_sum16(sa + sb);
;         S[0] = fmix_lo(S[0], om0, S[0]); S[1] = fmix_hi(S[1], om0, S[1]); S[2] = fmix_lo(S[2], om1, S[2]); S[3] = fmix_hi(S[3], om1, S[3]);
;         S[0] = fmix_lo(sa, b0_, S[0]); S[1] = fmix_hi(sa, b0_, S[1]); S[2] = fmix_lo(sa, b1_, S[2]); S[3] = fmix_hi(sa, b1_, S[3]);
;         S[0] = fmix_lo(vv, kd0, S[0]); S[1] = fmix_hi(vv, kd0, S[1]); S[2] = fmix_lo(vv, kd1, S[2]); S[3] = fmix_hi(vv, kd1, S[3]);
;         float y = fmix_lo(S[0], r0_, 0.f); y = fmix_hi(S[1], r0_, y);
;         float y2 = fmix_lo(S[2], r1_, 0.f); y2 = fmix_hi(S[3], r1_, y2);
;         y += y2;
;         if (VAR == 0 && islat) {
;           y = row_sum16(y);
;           if (q == 0) yout[((size_t)dir * NL + row_of(t0 + uu)) * RWW + hh * 64 + vrow] = (h16)y;
;         }
;         if (VAR != 0) asm volatile("" :: "v"(y));
;         const int nstep = t0 + uu + RW_U < RW_NS ? t0 + uu + RW_U : RW_NS - 1;
;         if (VAR != 2) RW_LOAD(uu, nstep);
	ds_read_b128 v[70:73], v42 offset:256
	v_fma_mix_f32 v10, v18, v84, v14 op_sel_hi:[0,1,0]
	ds_read_b128 v[76:79], v42 offset:4352
	v_fma_mix_f32 v11, v18, v84, v15 op_sel:[0,1,0] op_sel_hi:[0,1,0]
	ds_read_b64 v[74:75], v43 offset:8320
	v_fma_mix_f32 v12, v18, v85, v16 op_sel_hi:[0,1,0]
	v_fma_mix_f32 v13, v18, v85, v17 op_sel:[0,1,0] op_sel_hi:[0,1,0]
	v_mov_b32_dpp v19, v36 row_newbcast:15 row_mask:0xf bank_mask:0xf
	v_fma_mix_f32 v18, v10, v96, 0 op_sel_hi:[0,1,0]
	v_fma_mix_f32 v14, v10, v90, v10 op_sel_hi:[0,1,0]
	v_fma_mix_f32 v18, v11, v96, v18 op_sel:[0,1,0] op_sel_hi:[0,1,0]
	v_fma_mix_f32 v15, v11, v90, v11 op_sel:[0,1,0] op_sel_hi:[0,1,0]
	v_fma_mix_f32 v18, v12, v97, v18 op_sel_hi:[0,1,0]
	v_fma_mix_f32 v16, v12, v91, v12 op_sel_hi:[0,1,0]
	v_fma_mix_f32 v18, v13, v97, v18 op_sel:[0,1,0] op_sel_hi:[0,1,0]
	v_fma_mix_f32 v17, v13, v91, v13 op_sel:[0,1,0] op_sel_hi:[0,1,0]
	v_fma_mix_f32 v14, v19, v92, v14 op_sel_hi:[1,1,0]
	v_fma_mix_f32 v15, v19, v92, v15 op_sel:[0,1,0] op_sel_hi:[1,1,0]
	v_add_f32_dpp v18, v18, v18 quad_perm:[1,0,3,2] row_mask:0xf bank_mask:0xf bound_ctrl:1
	v_fma_mix_f32 v16, v19, v93, v16 op_sel_hi:[1,1,0]
	v_fma_mix_f32 v17, v19, v93, v17 op_sel:[0,1,0] op_sel_hi:[1,1,0]
	v_add_f32_dpp v18, v18, v18 quad_perm:[2,3,0,1] row_mask:0xf bank_mask:0xf bound_ctrl:1
	v_fma_mix_f32 v34, v10, v88, 0 op_sel_hi:[0,1,0]
	v_fma_mix_f32 v34, v11, v88, v34 op_sel:[0,1,0] op_sel_hi:[0,1,0]
	v_add_f32_dpp v18, v18, v18 row_ror:4 row_mask:0xf bank_mask:0xf bound_ctrl:1
	v_fma_mix_f32 v34, v12, v89, v34 op_sel_hi:[0,1,0]
	v_fma_mix_f32 v34, v13, v89, v34 op_sel:[0,1,0] op_sel_hi:[0,1,0]
	v_add_f32_dpp v18, v18, v18 row_ror:8 row_mask:0xf bank_mask:0xf bound_ctrl:1
	s_waitcnt lgkmcnt(3)
	ds_read_b128 v[80:83], v42 offset:512
	v_fma_mix_f32 v10, v18, v94, v14 op_sel_hi:[0,1,0]
	ds_read_b128 v[86:89], v42 offset:4608
	v_fma_mix_f32 v11, v18, v94, v15 op_sel:[0,1,0] op_sel_hi:[0,1,0]
	ds_read_b64 v[84:85], v43 offset:8448
	v_fma_mix_f32 v12, v18, v95, v16 op_sel_hi:[0,1,0]
	v_fma_mix_f32 v13, v18, v95, v17 op_sel:[0,1,0] op_sel_hi:[0,1,0]
	s_waitcnt vmcnt(0)
	v_mov_b32_e32 v36, v37
	s_mov_b32 s30, s26
	s_mov_b32 s26, s27
	s_mov_b32 s27, s28
	s_mov_b32 s28, s30
	v_add_u32_e32 v40, s26, v8
	v_add_u32_e32 v41, s26, v9
	v_add_u32_e32 v42, s27, v8
	v_add_u32_e32 v43, s27, v9
	v_add_u32_e32 v44, s28, v46
	v_add_u32_e32 v45, s28, v47
	s_barrier
	s_add_u32 s3, s3, 1
	s_cmp_lt_u32 s3, 0x410
	s_cbranch_scc1 .Lscan_loop_d0
	v_fma_mix_f32 v35, v10, v98, 0 op_sel_hi:[0,1,0]
	v_fma_mix_f32 v35, v11, v98, v35 op_sel:[0,1,0] op_sel_hi:[0,1,0]
	v_fma_mix_f32 v35, v12, v99, v35 op_sel_hi:[0,1,0]
	v_fma_mix_f32 v35, v13, v99, v35 op_sel:[0,1,0] op_sel_hi:[0,1,0]
	s_nop 1
	v_add_f32_dpp v20, v20, v20 row_ror:8 row_mask:0xf bank_mask:0xf bound_ctrl:1
	v_add_f32_dpp v21, v21, v21 row_ror:8 row_mask:0xf bank_mask:0xf bound_ctrl:1
	v_add_f32_dpp v22, v22, v22 row_ror:8 row_mask:0xf bank_mask:0xf bound_ctrl:1
	v_add_f32_dpp v23, v23, v23 row_ror:8 row_mask:0xf bank_mask:0xf bound_ctrl:1
	v_add_f32_dpp v24, v24, v24 row_ror:8 row_mask:0xf bank_mask:0xf bound_ctrl:1
	v_add_f32_dpp v25, v25, v25 row_ror:8 row_mask:0xf bank_mask:0xf bound_ctrl:1
	v_add_f32_dpp v26, v26, v26 row_ror:8 row_mask:0xf bank_mask:0xf bound_ctrl:1
	v_add_f32_dpp v27, v27, v27 row_ror:8 row_mask:0xf bank_mask:0xf bound_ctrl:1
	v_add_f32_dpp v20, v28, v28 row_ror:8 row_mask:0xf bank_mask:0xc bound_ctrl:1
	v_add_f32_dpp v21, v29, v29 row_ror:8 row_mask:0xf bank_mask:0xc bound_ctrl:1
	v_add_f32_dpp v22, v30, v30 row_ror:8 row_mask:0xf bank_mask:0xc bound_ctrl:1
	v_add_f32_dpp v23, v31, v31 row_ror:8 row_mask:0xf bank_mask:0xc bound_ctrl:1
	v_add_f32_dpp v24, v32, v32 row_ror:8 row_mask:0xf bank_mask:0xc bound_ctrl:1
	v_add_f32_dpp v25, v33, v33 row_ror:8 row_mask:0xf bank_mask:0xc bound_ctrl:1
	v_add_f32_dpp v26, v34, v34 row_ror:8 row_mask:0xf bank_mask:0xc bound_ctrl:1
	v_add_f32_dpp v27, v35, v35 row_ror:8 row_mask:0xf bank_mask:0xc bound_ctrl:1
	v_add_f32_dpp v20, v20, v20 row_half_mirror row_mask:0xf bank_mask:0xf bound_ctrl:1
	v_add_f32_dpp v21, v21, v21 row_half_mirror row_mask:0xf bank_mask:0xf bound_ctrl:1
	v_add_f32_dpp v22, v22, v22 row_half_mirror row_mask:0xf bank_mask:0xf bound_ctrl:1
	v_add_f32_dpp v23, v23, v23 row_half_mirror row_mask:0xf bank_mask:0xf bound_ctrl:1
	v_add_f32_dpp v20, v24, v24 row_half_mirror row_mask:0xf bank_mask:0xa bound_ctrl:1
	v_add_f32_dpp v21, v25, v25 row_half_mirror row_mask:0xf bank_mask:0xa bound_ctrl:1
	v_add_f32_dpp v22, v26, v26 row_half_mirror row_mask:0xf bank_mask:0xa bound_ctrl:1
	v_add_f32_dpp v23, v27, v27 row_half_mirror row_mask:0xf bank_mask:0xa bound_ctrl:1
	v_add_f32_dpp v20, v20, v20 quad_perm:[1,0,3,2] row_mask:0xf bank_mask:0xf bound_ctrl:1
	v_add_f32_dpp v21, v21, v21 quad_perm:[1,0,3,2] row_mask:0xf bank_mask:0xf bound_ctrl:1
	v_add_f32_dpp v22, v22, v22 quad_perm:[1,0,3,2] row_mask:0xf bank_mask:0xf bound_ctrl:1
	v_add_f32_dpp v23, v23, v23 quad_perm:[1,0,3,2] row_mask:0xf bank_mask:0xf bound_ctrl:1
	v_add_f32_dpp v20, v20, v20 quad_perm:[2,3,0,1] row_mask:0xf bank_mask:0xf bound_ctrl:1
	v_add_f32_dpp v21, v21, v21 quad_perm:[2,3,0,1] row_mask:0xf bank_mask:0xf bound_ctrl:1
	v_add_f32_dpp v22, v22, v22 quad_perm:[2,3,0,1] row_mask:0xf bank_mask:0xf bound_ctrl:1
	v_add_f32_dpp v23, v23, v23 quad_perm:[2,3,0,1] row_mask:0xf bank_mask:0xf bound_ctrl:1
	v_cndmask_b32_e64 v20, v20, v21, s[20:21]
	v_cndmask_b32_e64 v20, v20, v22, s[22:23]
	v_cndmask_b32_e64 v20, v20, v23, s[24:25]
	v_cvt_f16_f32_e32 v39, v20
	global_store_short v38, v39, s[12:13]
	s_add_u32 s12, s12, 0x8000
	s_addc_u32 s13, s13, 0
	s_waitcnt vmcnt(0) lgkmcnt(0)
	s_branch .Lscan_next
; #define RW_LOAD(slot, step) do { const size_t ro_ = (size_t)row_of(step) * RWW; \
;       s_ok[slot] = *(const h16x8*)((p_rec + ro_ * 3) + urec); s_b[slot] = *(const h16x4*)((p_rec + ro_ * 3) + urec + 8); \
;       s_kr[slot] = *(const h16x8*)((p_sh + ro_ * 2) + ush); s_v[slot] = (p_v + ro_)[uvoff]; } while (0)
; template <int VAR>
; __device__ __forceinline__ void ph_rw_scan(const Params& P) {
;     ...
;     const int rg = wu % 16, hh = (wu / 16) % RW_H, b = (wu / (16 * RW_H)) % BATCH, dir = wu / (16 * RW_H * BATCH);
;     const int vrow = rg * 4 + rl;
;     ...
;     const unsigned g_ = (unsigned)(hh * 16 + q);
;     const unsigned uvoff = (unsigned)(hh * 64 + vrow), urec = g_ * 12u, ush = g_ * 8u;
;     h16x8 s_ok[RW_U], s_kr[RW_U]; h16x4 s_b[RW_U]; h16 s_v[RW_U];
;     auto row_of = [&](int step) -> int {
;       if (step < CTX_LEN) return NL + b * CTX_LEN + (dir == 0 ? step : CTX_LEN - 1 - step);
;       const int s = step - CTX_LEN; return b * SEQ + (dir == 0 ? s : SEQ - 1 - s);
;     };
;     ...
; #pragma unroll
;     for (int uu = 0; uu < RW_U; ++uu) RW_LOAD(uu, uu);
.Lscan_dir1:
	s_lshl_b32 s30, s1, 2
	v_add_u32_e32 v39, s30, v3
	v_sub_u32_e32 v39, 15, v39
	v_mul_u32_u24_e32 v48, 0x1800, v39
	v_add_u32_e32 v48, v48, v5
	v_lshlrev_b32_e32 v49, 12, v39
	v_add_u32_e32 v49, v49, v6
	v_sub_u32_e32 v39, 15, v2
	v_lshlrev_b32_e32 v38, 11, v39
	v_add_u32_e32 v38, v38, v7
	s_lshl_b32 s30, s28, 8
	s_add_u32 s30, s30, 0x80f0
	s_lshl_b32 s31, s28, 14
	s_add_u32 s31, s31, 0x3ff0
	s_mul_i32 s3, s30, 0x1800
	s_add_u32 s6, s4, s3
	s_addc_u32 s7, s5, 0
	s_add_u32 s6, s6, 0x2f914000
	s_addc_u32 s7, s7, 0
	s_mul_i32 s3, s30, 0x1000
	s_add_u32 s8, s4, s3
	s_addc_u32 s9, s5, 0
	s_add_u32 s8, s8, 0xbe4c000
	s_addc_u32 s9, s9, 0
	s_mul_i32 s3, s30, 0x800
	s_add_u32 s10, s4, s3
	s_addc_u32 s11, s5, 0
	s_add_u32 s10, s10, 0x3bc14000
	s_addc_u32 s11, s11, 0
	s_mul_i32 s3, s31, 0x1800
	s_add_u32 s14, s4, s3
	s_addc_u32 s15, s5, 0
	s_add_u32 s14, s14, 0x2f914000
	s_addc_u32 s15, s15, 0
	s_mul_i32 s3, s31, 0x1000
	s_add_u32 s16, s4, s3
	s_addc_u32 s17, s5, 0
	s_add_u32 s16, s16, 0xbe4c000
	s_addc_u32 s17, s17, 0
	s_mul_i32 s3, s31, 0x800
	s_add_u32 s18, s4, s3
	s_addc_u32 s19, s5, 0
	s_add_u32 s18, s18, 0x3bc14000
	s_addc_u32 s19, s19, 0
	s_mul_i32 s3, s31, 0x800
	s_add_u32 s12, s4, s3
	s_addc_u32 s13, s5, 0
	s_add_u32 s12, s12, 0x1a0cc000
	s_addc_u32 s13, s13, 0
	v_mov_b32_e32 v10, 0
	v_mov_b32_e32 v11, 0
	v_mov_b32_e32 v12, 0
	v_mov_b32_e32 v13, 0
	s_mov_b32 s29, 0
	global_load_ushort v36, v38, s[10:11]
	s_mov_b32 s26, 0
	s_mov_b32 s27, 10240
	s_mov_b32 s28, 0
	v_add_u32_e32 v40, s26, v8
	v_add_u32_e32 v41, s26, v9
	v_add_u32_e32 v42, s27, v8
	v_add_u32_e32 v43, s27, v9
	v_add_u32_e32 v44, s28, v46
	v_add_u32_e32 v45, s28, v47
	global_load_dwordx4 v[50:53], v48, s[6:7]
	global_load_dwordx2 v[54:55], v48, s[6:7] offset:16
	global_load_dwordx4 v[56:59], v49, s[8:9]
	s_add_u32 s29, s29, 1
	s_cmp_eq_u32 s29, 16
	s_cbranch_scc1 .Lscan_stsw_p0_d1
	s_sub_u32 s6, s6, 0x18000
	s_subb_u32 s7, s7, 0
	s_sub_u32 s8, s8, 0x10000
	s_subb_u32 s9, s9, 0
	s_branch .Lscan_stdone_p0_d1

; #define RW_LOAD(slot, step) do { const size_t ro_ = (size_t)row_of(step) * RWW; \
;       s_ok[slot] = *(const h16x8*)((p_rec + ro_ * 3) + urec); s_b[slot] = *(const h16x4*)((p_rec + ro_ * 3) + urec + 8); \
;       s_kr[slot] = *(const h16x8*)((p_sh + ro_ * 2) + ush); s_v[slot] = (p_v + ro_)[uvoff]; } while (0)
; template <int VAR>
; __device__ __forceinline__ void ph_rw_scan(const Params& P) {
;     ...
; #pragma unroll
;     for (int uu = 0; uu < RW_U; ++uu) RW_LOAD(uu, uu);
.Lscan_stdone_p0_d1:
	s_waitcnt vmcnt(0)
	ds_write_b128 v44, v[50:53]
	ds_write_b128 v44, v[56:59] offset:4096
	ds_write_b64 v45, v[54:55] offset:8192
	s_mov_b32 s28, 10240
	v_add_u32_e32 v40, s26, v8
	v_add_u32_e32 v41, s26, v9
	v_add_u32_e32 v42, s27, v8
	v_add_u32_e32 v43, s27, v9
	v_add_u32_e32 v44, s28, v46
	v_add_u32_e32 v45, s28, v47
	global_load_dwordx4 v[50:53], v48, s[6:7]
	global_load_dwordx2 v[54:55], v48, s[6:7] offset:16
	global_load_dwordx4 v[56:59], v49, s[8:9]
	s_add_u32 s29, s29, 1
	s_cmp_eq_u32 s29, 16
	s_cbranch_scc1 .Lscan_stsw_p1_d1
	s_sub_u32 s6, s6, 0x18000
	s_subb_u32 s7, s7, 0
	s_sub_u32 s8, s8, 0x10000
	s_subb_u32 s9, s9, 0
	s_branch .Lscan_stdone_p1_d1

; #define RW_LOAD(slot, step) do { const size_t ro_ = (size_t)row_of(step) * RWW; \
;       s_ok[slot] = *(const h16x8*)((p_rec + ro_ * 3) + urec); s_b[slot] = *(const h16x4*)((p_rec + ro_ * 3) + urec + 8); \
;       s_kr[slot] = *(const h16x8*)((p_sh + ro_ * 2) + ush); s_v[slot] = (p_v + ro_)[uvoff]; } while (0)
; template <int VAR>
; __device__ __forceinline__ void ph_rw_scan(const Params& P) {
;     ...
; #pragma unroll
;     for (int uu = 0; uu < RW_U; ++uu) RW_LOAD(uu, uu);
.Lscan_stdone_p1_d1:
	s_waitcnt vmcnt(0)
	ds_write_b128 v44, v[50:53]
	ds_write_b128 v44, v[56:59] offset:4096
	ds_write_b64 v45, v[54:55] offset:8192
	s_mov_b32 s28, 20480
	v_add_u32_e32 v40, s26, v8
	v_add_u32_e32 v41, s26, v9
	v_add_u32_e32 v42, s27, v8
	v_add_u32_e32 v43, s27, v9
	v_add_u32_e32 v44, s28, v46
	v_add_u32_e32 v45, s28, v47
	global_load_dwordx4 v[50:53], v48, s[6:7]
	global_load_dwordx2 v[54:55], v48, s[6:7] offset:16
	global_load_dwordx4 v[56:59], v49, s[8:9]
	s_add_u32 s29, s29, 1
	s_cmp_eq_u32 s29, 16
	s_cbranch_scc1 .Lscan_stsw_p2_d1
	s_sub_u32 s6, s6, 0x18000
	s_subb_u32 s7, s7, 0
	s_sub_u32 s8, s8, 0x10000
	s_subb_u32 s9, s9, 0
	s_branch .Lscan_stdone_p2_d1

; __device__ __forceinline__ float row_sum16(float v) { v += __shfl_xor(v, 1); v += __shfl_xor(v, 2); v += __shfl_xor(v, 4); v += __shfl_xor(v, 8); return v; }
; __device__ __forceinline__ float row_sum16(float v) { v += dppf<0xB1>(v); v += dppf<0x4E>(v); v += dppf<0x124>(v); v += dppf<0x128>(v); return v; }
; #define RW_LOAD(slot, step) do { const size_t ro_ = (size_t)row_of(step) * RWW; \
;       s_ok[slot] = *(const h16x8*)((p_rec + ro_ * 3) + urec); s_b[slot] = *(const h16x4*)((p_rec + ro_ * 3) + urec + 8); \
;       s_kr[slot] = *(const h16x8*)((p_sh + ro_ * 2) + ush); s_v[slot] = (p_v + ro_)[uvoff]; } while (0)
; template <int VAR>
; __device__ __forceinline__ void ph_rw_scan(const Params& P) {
;     ...
;       for (int uu = 0; uu < RW_U; ++uu) {
;         const float vv = (float)s_v[uu];
;         const u32x4 p_ok = __builtin_bit_cast(u32x4, s_ok[uu]), p_kr = __builtin_bit_cast(u32x4, s_kr[uu]);
;         const u32x2 p_bb = __builtin_bit_cast(u32x2, s_b[uu]);
;         const unsigned om0 = p_ok[0], om1 = p_ok[1], kd0 = p_ok[2], kd1 = p_ok[3];
;         const unsigned kk0 = p_kr[0], kk1 = p_kr[1], r0_ = p_kr[2], r1_ = p_kr[3];
;         const unsigned b0_ = p_bb[0], b1_ = p_bb[1];
;         float sa = fmix_lo(S[0], kk0, 0.f); sa = fmix_hi(S[1], kk0, sa);
;         float sb = fmix_lo(S[2], kk1, 0.f); sb = fmix_hi(S[3], kk1, sb);
;         sa = row_sum16(sa + sb);
;         S[0] = fmix_lo(S[0], om0, S[0]); S[1] = fmix_hi(S[1], om0, S[1]); S[2] = fmix_lo(S[2], om1, S[2]); S[3] = fmix_hi(S[3], om1, S[3]);
;         S[0] = fmix_lo(sa, b0_, S[0]); S[1] = fmix_hi(sa, b0_, S[1]); S[2] = fmix_lo(sa, b1_, S[2]); S[3] = fmix_hi(sa, b1_, S[3]);
;         S[0] = fmix_lo(vv, kd0, S[0]); S[1] = fmix_hi(vv, kd0, S[1]); S[2] = fmix_lo(vv, kd1, S[2]); S[3] = fmix_hi(vv, kd1, S[3]);
;         float y = fmix_lo(S[0], r0_, 0.f); y = fmix_hi(S[1], r0_, y);
;         float y2 = fmix_lo(S[2], r1_, 0.f); y2 = fmix_hi(S[3], r1_, y2);
;         y += y2;
;         if (VAR == 0 && islat) {
;           y = row_sum16(y);
;           if (q == 0) yout[((size_t)dir * NL + row_of(t0 + uu)) * RWW + hh * 64 + vrow] = (h16)y;
;         }
;         if (VAR != 0) asm volatile("" :: "v"(y));
;         const int nstep = t0 + uu + RW_U < RW_NS ? t0 + uu + RW_U : RW_NS - 1;
;         if (VAR != 2) RW_LOAD(uu, nstep);
.Lscan_loop_d1:
	v_mov_b32_dpp v19, v36 row_newbcast:0 row_mask:0xf bank_mask:0xf
	v_fma_mix_f32 v18, v10, v66, 0 op_sel_hi:[0,1,0]
	v_fma_mix_f32 v14, v10, v60, v10 op_sel_hi:[0,1,0]
	v_fma_mix_f32 v18, v11, v66, v18 op_sel:[0,1,0] op_sel_hi:[0,1,0]
	v_fma_mix_f32 v15, v11, v60, v11 op_sel:[0,1,0] op_sel_hi:[0,1,0]
	v_fma_mix_f32 v18, v12, v67, v18 op_sel_hi:[0,1,0]
	v_fma_mix_f32 v16, v12, v61, v12 op_sel_hi:[0,1,0]
	v_fma_mix_f32 v18, v13, v67, v18 op_sel:[0,1,0] op_sel_hi:[0,1,0]
	v_fma_mix_f32 v17, v13, v61, v13 op_sel:[0,1,0] op_sel_hi:[0,1,0]
	v_fma_mix_f32 v14, v19, v62, v14 op_sel_hi:[1,1,0]
	v_fma_mix_f32 v15, v19, v62, v15 op_sel:[0,1,0] op_sel_hi:[1,1,0]
	v_add_f32_dpp v18, v18, v18 quad_perm:[1,0,3,2] row_mask:0xf bank_mask:0xf bound_ctrl:1
	v_fma_mix_f32 v16, v19, v63, v16 op_sel_hi:[1,1,0]
	v_fma_mix_f32 v17, v19, v63, v17 op_sel:[0,1,0] op_sel_hi:[1,1,0]
	v_add_f32_dpp v18, v18, v18 quad_perm:[2,3,0,1] row_mask:0xf bank_mask:0xf bound_ctrl:1
	v_fma_mix_f32 v35, v10, v98, 0 op_sel_hi:[0,1,0]
	v_fma_mix_f32 v35, v11, v98, v35 op_sel:[0,1,0] op_sel_hi:[0,1,0]
	v_add_f32_dpp v18, v18, v18 row_ror:4 row_mask:0xf bank_mask:0xf bound_ctrl:1
	v_fma_mix_f32 v35, v12, v99, v35 op_sel_hi:[0,1,0]
	v_fma_mix_f32 v35, v13, v99, v35 op_sel:[0,1,0] op_sel_hi:[0,1,0]
	v_add_f32_dpp v18, v18, v18 row_ror:8 row_mask:0xf bank_mask:0xf bound_ctrl:1
	s_waitcnt lgkmcnt(3)
	ds_read_b128 v[90:93], v40 offset:768
	v_fma_mix_f32 v10, v18, v64, v14 op_sel_hi:[0,1,0]
	ds_read_b128 v[96:99], v40 offset:4864
	v_fma_mix_f32 v11, v18, v64, v15 op_sel:[0,1,0] op_sel_hi:[0,1,0]
	ds_read_b64 v[94:95], v41 offset:8576
	v_fma_mix_f32 v12, v18, v65, v16 op_sel_hi:[0,1,0]
	v_fma_mix_f32 v13, v18, v65, v17 op_sel:[0,1,0] op_sel_hi:[0,1,0]
	s_cmp_eq_u32 s3, 15
	s_cbranch_scc1 .Lscan_vsw_d1
	s_sub_u32 s10, s10, 0x8000
	s_subb_u32 s11, s11, 0
	s_branch .Lscan_vdone_d1

.Lscan_vdone_d1:
	ds_write_b128 v44, v[50:53]
	ds_write_b128 v44, v[56:59] offset:4096
	ds_write_b64 v45, v[54:55] offset:8192
	global_load_dwordx4 v[50:53], v48, s[6:7]
	global_load_dwordx2 v[54:55], v48, s[6:7] offset:16
	global_load_dwordx4 v[56:59], v49, s[8:9]
	global_load_ushort v37, v38, s[10:11]
	s_add_u32 s29, s29, 1
	s_cmp_eq_u32 s29, 16
	s_cbranch_scc1 .Lscan_stsw_lp_d1
	s_sub_u32 s6, s6, 0x18000
	s_subb_u32 s7, s7, 0
	s_sub_u32 s8, s8, 0x10000
	s_subb_u32 s9, s9, 0
	s_branch .Lscan_stdone_lp_d1

; __device__ __forceinline__ float row_sum16(float v) { v += __shfl_xor(v, 1); v += __shfl_xor(v, 2); v += __shfl_xor(v, 4); v += __shfl_xor(v, 8); return v; }
; __device__ __forceinline__ float row_sum16(float v) { v += dppf<0xB1>(v); v += dppf<0x4E>(v); v += dppf<0x124>(v); v += dppf<0x128>(v); return v; }
; #define RW_LOAD(slot, step) do { const size_t ro_ = (size_t)row_of(step) * RWW; \
;       s_ok[slot] = *(const h16x8*)((p_rec + ro_ * 3) + urec); s_b[slot] = *(const h16x4*)((p_rec + ro_ * 3) + urec + 8); \
;       s_kr[slot] = *(const h16x8*)((p_sh + ro_ * 2) + ush); s_v[slot] = (p_v + ro_)[uvoff]; } while (0)
; template <int VAR>
; __device__ __forceinline__ void ph_rw_scan(const Params& P) {
;     ...
;       for (int uu = 0; uu < RW_U; ++uu) {
;         const float vv = (float)s_v[uu];
;         const u32x4 p_ok = __builtin_bit_cast(u32x4, s_ok[uu]), p_kr = __builtin_bit_cast(u32x4, s_kr[uu]);
;         const u32x2 p_bb = __builtin_bit_cast(u32x2, s_b[uu]);
;         const unsigned om0 = p_ok[0], om1 = p_ok[1], kd0 = p_ok[2], kd1 = p_ok[3];
;         const unsigned kk0 = p_kr[0], kk1 = p_kr[1], r0_ = p_kr[2], r1_ = p_kr[3];
;         const unsigned b0_ = p_bb[0], b1_ = p_bb[1];
;         float sa = fmix_lo(S[0], kk0, 0.f); sa = fmix_hi(S[1], kk0, sa);
;         float sb = fmix_lo(S[2], kk1, 0.f); sb = fmix_hi(S[3], kk1, sb);
;         sa = row_sum16(sa + sb);
;         S[0] = fmix_lo(S[0], om0, S[0]); S[1] = fmix_hi(S[1], om0, S[1]); S[2] = fmix_lo(S[2], om1, S[2]); S[3] = fmix_hi(S[3], om1, S[3]);
;         S[0] = fmix_lo(sa, b0_, S[0]); S[1] = fmix_hi(sa, b0_, S[1]); S[2] = fmix_lo(sa, b1_, S[2]); S[3] = fmix_hi(sa, b1_, S[3]);
;         S[0] = fmix_lo(vv, kd0, S[0]); S[1] = fmix_hi(vv, kd0, S[1]); S[2] = fmix_lo(vv, kd1, S[2]); S[3] = fmix_hi(vv, kd1, S[3]);
;         float y = fmix_lo(S[0], r0_, 0.f); y = fmix_hi(S[1], r0_, y);
;         float y2 = fmix_lo(S[2], r1_, 0.f); y2 = fmix_hi(S[3], r1_, y2);
;         y += y2;
;         if (VAR == 0 && islat) {
;           y = row_sum16(y);
;           if (q == 0) yout[((size_t)dir * NL + row_of(t0 + uu)) * RWW + hh * 64 + vrow] = (h16)y;
;         }
;         if (VAR != 0) asm volatile("" :: "v"(y));
;         const int nstep = t0 + uu + RW_U < RW_NS ? t0 + uu + RW_U : RW_NS - 1;
;         if (VAR != 2) RW_LOAD(uu, nstep);
.Lscan_stdone_lp_d1:
	s_cmp_lt_u32 s3, 17
	s_cbranch_scc1 .Lscan_noy_d1
	v_add_f32_dpp v20, v20, v20 row_ror:8 row_mask:0xf bank_mask:0xf bound_ctrl:1
	v_add_f32_dpp v21, v21, v21 row_ror:8 row_mask:0xf bank_mask:0xf bound_ctrl:1
	v_add_f32_dpp v22, v22, v22 row_ror:8 row_mask:0xf bank_mask:0xf bound_ctrl:1
	v_add_f32_dpp v23, v23, v23 row_ror:8 row_mask:0xf bank_mask:0xf bound_ctrl:1
	v_add_f32_dpp v24, v24, v24 row_ror:8 row_mask:0xf bank_mask:0xf bound_ctrl:1
	v_add_f32_dpp v25, v25, v25 row_ror:8 row_mask:0xf bank_mask:0xf bound_ctrl:1
	v_add_f32_dpp v26, v26, v26 row_ror:8 row_mask:0xf bank_mask:0xf bound_ctrl:1
	v_add_f32_dpp v27, v27, v27 row_ror:8 row_mask:0xf bank_mask:0xf bound_ctrl:1
	v_add_f32_dpp v20, v28, v28 row_ror:8 row_mask:0xf bank_mask:0xc bound_ctrl:1
	v_add_f32_dpp v21, v29, v29 row_ror:8 row_mask:0xf bank_mask:0xc bound_ctrl:1
	v_add_f32_dpp v22, v30, v30 row_ror:8 row_mask:0xf bank_mask:0xc bound_ctrl:1
	v_add_f32_dpp v23, v31, v31 row_ror:8 row_mask:0xf bank_mask:0xc bound_ctrl:1
	v_add_f32_dpp v24, v32, v32 row_ror:8 row_mask:0xf bank_mask:0xc bound_ctrl:1
	v_add_f32_dpp v25, v33, v33 row_ror:8 row_mask:0xf bank_mask:0xc bound_ctrl:1
	v_add_f32_dpp v26, v34, v34 row_ror:8 row_mask:0xf bank_mask:0xc bound_ctrl:1
	v_add_f32_dpp v27, v35, v35 row_ror:8 row_mask:0xf bank_mask:0xc bound_ctrl:1
	v_add_f32_dpp v20, v20, v20 row_half_mirror row_mask:0xf bank_mask:0xf bound_ctrl:1
	v_add_f32_dpp v21, v21, v21 row_half_mirror row_mask:0xf bank_mask:0xf bound_ctrl:1
	v_add_f32_dpp v22, v22, v22 row_half_mirror row_mask:0xf bank_mask:0xf bound_ctrl:1
	v_add_f32_dpp v23, v23, v23 row_half_mirror row_mask:0xf bank_mask:0xf bound_ctrl:1
	v_add_f32_dpp v20, v24, v24 row_half_mirror row_mask:0xf bank_mask:0xa bound_ctrl:1
	v_add_f32_dpp v21, v25, v25 row_half_mirror row_mask:0xf bank_mask:0xa bound_ctrl:1
	v_add_f32_dpp v22, v26, v26 row_half_mirror row_mask:0xf bank_mask:0xa bound_ctrl:1
	v_add_f32_dpp v23, v27, v27 row_half_mirror row_mask:0xf bank_mask:0xa bound_ctrl:1
	v_add_f32_dpp v20, v20, v20 quad_perm:[1,0,3,2] row_mask:0xf bank_mask:0xf bound_ctrl:1
	v_add_f32_dpp v21, v21, v21 quad_perm:[1,0,3,2] row_mask:0xf bank_mask:0xf bound_ctrl:1
	v_add_f32_dpp v22, v22, v22 quad_perm:[1,0,3,2] row_mask:0xf bank_mask:0xf bound_ctrl:1
	v_add_f32_dpp v23, v23, v23 quad_perm:[1,0,3,2] row_mask:0xf bank_mask:0xf bound_ctrl:1
	v_add_f32_dpp v20, v20, v20 quad_perm:[2,3,0,1] row_mask:0xf bank_mask:0xf bound_ctrl:1
	v_add_f32_dpp v21, v21, v21 quad_perm:[2,3,0,1] row_mask:0xf bank_mask:0xf bound_ctrl:1
	v_add_f32_dpp v22, v22, v22 quad_perm:[2,3,0,1] row_mask:0xf bank_mask:0xf bound_ctrl:1
	v_add_f32_dpp v23, v23, v23 quad_perm:[2,3,0,1] row_mask:0xf bank_mask:0xf bound_ctrl:1
	v_cndmask_b32_e64 v20, v20, v21, s[20:21]
	v_cndmask_b32_e64 v20, v20, v22, s[22:23]
	v_cndmask_b32_e64 v20, v20, v23, s[24:25]
	v_cvt_f16_f32_e32 v39, v20
	global_store_short v38, v39, s[12:13]
	s_sub_u32 s12, s12, 0x8000
	s_subb_u32 s13, s13, 0
.Lscan_noy_d1:
	v_mov_b32_dpp v19, v36 row_newbcast:1 row_mask:0xf bank_mask:0xf
	v_fma_mix_f32 v18, v10, v76, 0 op_sel_hi:[0,1,0]
	v_fma_mix_f32 v14, v10, v70, v10 op_sel_hi:[0,1,0]
	v_fma_mix_f32 v18, v11, v76, v18 op_sel:[0,1,0] op_sel_hi:[0,1,0]
	v_fma_mix_f32 v15, v11, v70, v11 op_sel:[0,1,0] op_sel_hi:[0,1,0]
	v_fma_mix_f32 v18, v12, v77, v18 op_sel_hi:[0,1,0]
	v_fma_mix_f32 v16, v12, v71, v12 op_sel_hi:[0,1,0]
	v_fma_mix_f32 v18, v13, v77, v18 op_sel:[0,1,0] op_sel_hi:[0,1,0]
	v_fma_mix_f32 v17, v13, v71, v13 op_sel:[0,1,0] op_sel_hi:[0,1,0]
	v_fma_mix_f32 v14, v19, v72, v14 op_sel_hi:[1,1,0]
	v_fma_mix_f32 v15, v19, v72, v15 op_sel:[0,1,0] op_sel_hi:[1,1,0]
	v_add_f32_dpp v18, v18, v18 quad_perm:[1,0,3,2] row_mask:0xf bank_mask:0xf bound_ctrl:1
	v_fma_mix_f32 v16, v19, v73, v16 op_sel_hi:[1,1,0]
	v_fma_mix_f32 v17, v19, v73, v17 op_sel:[0,1,0] op_sel_hi:[1,1,0]
	v_add_f32_dpp v18, v18, v18 quad_perm:[2,3,0,1] row_mask:0xf bank_mask:0xf bound_ctrl:1
	v_fma_mix_f32 v20, v10, v68, 0 op_sel_hi:[0,1,0]
	v_fma_mix_f32 v20, v11, v68, v20 op_sel:[0,1,0] op_sel_hi:[0,1,0]
	v_add_f32_dpp v18, v18, v18 row_ror:4 row_mask:0xf bank_mask:0xf bound_ctrl:1
	v_fma_mix_f32 v20, v12, v69, v20 op_sel_hi:[0,1,0]
	v_fma_mix_f32 v20, v13, v69, v20 op_sel:[0,1,0] op_sel_hi:[0,1,0]
	v_add_f32_dpp v18, v18, v18 row_ror:8 row_mask:0xf bank_mask:0xf bound_ctrl:1
	s_waitcnt lgkmcnt(3)
	ds_read_b128 v[60:63], v40 offset:1024
	v_fma_mix_f32 v10, v18, v74, v14 op_sel_hi:[0,1,0]
	ds_read_b128 v[66:69], v40 offset:5120
	v_fma_mix_f32 v11, v18, v74, v15 op_sel:[0,1,0] op_sel_hi:[0,1,0]
	ds_read_b64 v[64:65], v41 offset:8704
	v_fma_mix_f32 v12, v18, v75, v16 op_sel_hi:[0,1,0]
	v_fma_mix_f32 v13, v18, v75, v17 op_sel:[0,1,0] op_sel_hi:[0,1,0]
	v_mov_b32_dpp v19, v36 row_newbcast:2 row_mask:0xf bank_mask:0xf
	v_fma_mix_f32 v18, v10, v86, 0 op_sel_hi:[0,1,0]
	v_fma_mix_f32 v14, v10, v80, v10 op_sel_hi:[0,1,0]
	v_fma_mix_f32 v18, v11, v86, v18 op_sel:[0,1,0] op_sel_hi:[0,1,0]
	v_fma_mix_f32 v15, v11, v80, v11 op_sel:[0,1,0] op_sel_hi:[0,1,0]
	v_fma_mix_f32 v18, v12, v87, v18 op_sel_hi:[0,1,0]
	v_fma_mix_f32 v16, v12, v81, v12 op_sel_hi:[0,1,0]
	v_fma_mix_f32 v18, v13, v87, v18 op_sel:[0,1,0] op_sel_hi:[0,1,0]
	v_fma_mix_f32 v17, v13, v81, v13 op_sel:[0,1,0] op_sel_hi:[0,1,0]
	v_fma_mix_f32 v14, v19, v82, v14 op_sel_hi:[1,1,0]
	v_fma_mix_f32 v15, v19, v82, v15 op_sel:[0,1,0] op_sel_hi:[1,1,0]
	v_add_f32_dpp v18, v18, v18 quad_perm:[1,0,3,2] row_mask:0xf bank_mask:0xf bound_ctrl:1
	v_fma_mix_f32 v16, v19, v83, v16 op_sel_hi:[1,1,0]
	v_fma_mix_f32 v17, v19, v83, v17 op_sel:[0,1,0] op_sel_hi:[1,1,0]
	v_add_f32_dpp v18, v18, v18 quad_perm:[2,3,0,1] row_mask:0xf bank_mask:0xf bound_ctrl:1
	v_fma_mix_f32 v21, v10, v78, 0 op_sel_hi:[0,1,0]
	v_fma_mix_f32 v21, v11, v78, v21 op_sel:[0,1,0] op_sel_hi:[0,1,0]
	v_add_f32_dpp v18, v18, v18 row_ror:4 row_mask:0xf bank_mask:0xf bound_ctrl:1
	v_fma_mix_f32 v21, v12, v79, v21 op_sel_hi:[0,1,0]
	v_fma_mix_f32 v21, v13, v79, v21 op_sel:[0,1,0] op_sel_hi:[0,1,0]
	v_add_f32_dpp v18, v18, v18 row_ror:8 row_mask:0xf bank_mask:0xf bound_ctrl:1
	s_waitcnt lgkmcnt(3)
; __device__ __forceinline__ float row_sum16(float v) { v += __shfl_xor(v, 1); v += __shfl_xor(v, 2); v += __shfl_xor(v, 4); v += __shfl_xor(v, 8); return v; }
; __device__ __forceinline__ float row_sum16(float v) { v += dppf<0xB1>(v); v += dppf<0x4E>(v); v += dppf<0x124>(v); v += dppf<0x128>(v); return v; }
; #define RW_LOAD(slot, step) do { const size_t ro_ = (size_t)row_of(step) * RWW; \
;       s_ok[slot] = *(const h16x8*)((p_rec + ro_ * 3) + urec); s_b[slot] = *(const h16x4*)((p_rec + ro_ * 3) + urec + 8); \
;       s_kr[slot] = *(const h16x8*)((p_sh + ro_ * 2) + ush); s_v[slot] = (p_v + ro_)[uvoff]; } while (0)
; template <int VAR>
; __device__ __forceinline__ void ph_rw_scan(const Params& P) {
;     ...
;       for (int uu = 0; uu < RW_U; ++uu) {
;         const float vv = (float)s_v[uu];
;         const u32x4 p_ok = __builtin_bit_cast(u32x4, s_ok[uu]), p_kr = __builtin_bit_cast(u32x4, s_kr[uu]);
;         const u32x2 p_bb = __builtin_bit_cast(u32x2, s_b[uu]);
;         const unsigned om0 = p_ok[0], om1 = p_ok[1], kd0 = p_ok[2], kd1 = p_ok[3];
;         const unsigned kk0 = p_kr[0], kk1 = p_kr[1], r0_ = p_kr[2], r1_ = p_kr[3];
;         const unsigned b0_ = p_bb[0], b1_ = p_bb[1];
;         float sa = fmix_lo(S[0], kk0, 0.f); sa = fmix_hi(S[1], kk0, sa);
;         float sb = fmix_lo(S[2], kk1, 0.f); sb = fmix_hi(S[3], kk1, sb);
;         sa = row_sum16(sa + sb);
;         S[0] = fmix_lo(S[0], om0, S[0]); S[1] = fmix_hi(S[1], om0, S[1]); S[2] = fmix_lo(S[2], om1, S[2]); S[3] = fmix_hi(S[3], om1, S[3]);
;         S[0] = fmix_lo(sa, b0_, S[0]); S[1] = fmix_hi(sa, b0_, S[1]); S[2] = fmix_lo(sa, b1_, S[2]); S[3] = fmix_hi(sa, b1_, S[3]);
;         S[0] = fmix_lo(vv, kd0, S[0]); S[1] = fmix_hi(vv, kd0, S[1]); S[2] = fmix_lo(vv, kd1, S[2]); S[3] = fmix_hi(vv, kd1, S[3]);
;         float y = fmix_lo(S[0], r0_, 0.f); y = fmix_hi(S[1], r0_, y);
;         float y2 = fmix_lo(S[2], r1_, 0.f); y2 = fmix_hi(S[3], r1_, y2);
;         y += y2;
;         if (VAR == 0 && islat) {
;           y = row_sum16(y);
;           if (q == 0) yout[((size_t)dir * NL + row_of(t0 + uu)) * RWW + hh * 64 + vrow] = (h16)y;
;         }
;         if (VAR != 0) asm volatile("" :: "v"(y));
;         const int nstep = t0 + uu + RW_U < RW_NS ? t0 + uu + RW_U : RW_NS - 1;
;         if (VAR != 2) RW_LOAD(uu, nstep);
	ds_read_b128 v[70:73], v40 offset:1280
	v_fma_mix_f32 v10, v18, v84, v14 op_sel_hi:[0,1,0]
	ds_read_b128 v[76:79], v40 offset:5376
	v_fma_mix_f32 v11, v18, v84, v15 op_sel:[0,1,0] op_sel_hi:[0,1,0]
	ds_read_b64 v[74:75], v41 offset:8832
	v_fma_mix_f32 v12, v18, v85, v16 op_sel_hi:[0,1,0]
	v_fma_mix_f32 v13, v18, v85, v17 op_sel:[0,1,0] op_sel_hi:[0,1,0]
	v_mov_b32_dpp v19, v36 row_newbcast:3 row_mask:0xf bank_mask:0xf
	v_fma_mix_f32 v18, v10, v96, 0 op_sel_hi:[0,1,0]
	v_fma_mix_f32 v14, v10, v90, v10 op_sel_hi:[0,1,0]
	v_fma_mix_f32 v18, v11, v96, v18 op_sel:[0,1,0] op_sel_hi:[0,1,0]
	v_fma_mix_f32 v15, v11, v90, v11 op_sel:[0,1,0] op_sel_hi:[0,1,0]
	v_fma_mix_f32 v18, v12, v97, v18 op_sel_hi:[0,1,0]
	v_fma_mix_f32 v16, v12, v91, v12 op_sel_hi:[0,1,0]
	v_fma_mix_f32 v18, v13, v97, v18 op_sel:[0,1,0] op_sel_hi:[0,1,0]
	v_fma_mix_f32 v17, v13, v91, v13 op_sel:[0,1,0] op_sel_hi:[0,1,0]
	v_fma_mix_f32 v14, v19, v92, v14 op_sel_hi:[1,1,0]
	v_fma_mix_f32 v15, v19, v92, v15 op_sel:[0,1,0] op_sel_hi:[1,1,0]
	v_add_f32_dpp v18, v18, v18 quad_perm:[1,0,3,2] row_mask:0xf bank_mask:0xf bound_ctrl:1
	v_fma_mix_f32 v16, v19, v93, v16 op_sel_hi:[1,1,0]
	v_fma_mix_f32 v17, v19, v93, v17 op_sel:[0,1,0] op_sel_hi:[1,1,0]
	v_add_f32_dpp v18, v18, v18 quad_perm:[2,3,0,1] row_mask:0xf bank_mask:0xf bound_ctrl:1
	v_fma_mix_f32 v22, v10, v88, 0 op_sel_hi:[0,1,0]
	v_fma_mix_f32 v22, v11, v88, v22 op_sel:[0,1,0] op_sel_hi:[0,1,0]
	v_add_f32_dpp v18, v18, v18 row_ror:4 row_mask:0xf bank_mask:0xf bound_ctrl:1
	v_fma_mix_f32 v22, v12, v89, v22 op_sel_hi:[0,1,0]
	v_fma_mix_f32 v22, v13, v89, v22 op_sel:[0,1,0] op_sel_hi:[0,1,0]
	v_add_f32_dpp v18, v18, v18 row_ror:8 row_mask:0xf bank_mask:0xf bound_ctrl:1
	s_waitcnt lgkmcnt(3)
	ds_read_b128 v[80:83], v40 offset:1536
	v_fma_mix_f32 v10, v18, v94, v14 op_sel_hi:[0,1,0]
	ds_read_b128 v[86:89], v40 offset:5632
	v_fma_mix_f32 v11, v18, v94, v15 op_sel:[0,1,0] op_sel_hi:[0,1,0]
	ds_read_b64 v[84:85], v41 offset:8960
	v_fma_mix_f32 v12, v18, v95, v16 op_sel_hi:[0,1,0]
	v_fma_mix_f32 v13, v18, v95, v17 op_sel:[0,1,0] op_sel_hi:[0,1,0]
	v_mov_b32_dpp v19, v36 row_newbcast:4 row_mask:0xf bank_mask:0xf
	v_fma_mix_f32 v18, v10, v66, 0 op_sel_hi:[0,1,0]
	v_fma_mix_f32 v14, v10, v60, v10 op_sel_hi:[0,1,0]
	v_fma_mix_f32 v18, v11, v66, v18 op_sel:[0,1,0] op_sel_hi:[0,1,0]
	v_fma_mix_f32 v15, v11, v60, v11 op_sel:[0,1,0] op_sel_hi:[0,1,0]
	v_fma_mix_f32 v18, v12, v67, v18 op_sel_hi:[0,1,0]
	v_fma_mix_f32 v16, v12, v61, v12 op_sel_hi:[0,1,0]
	v_fma_mix_f32 v18, v13, v67, v18 op_sel:[0,1,0] op_sel_hi:[0,1,0]
	v_fma_mix_f32 v17, v13, v61, v13 op_sel:[0,1,0] op_sel_hi:[0,1,0]
	v_fma_mix_f32 v14, v19, v62, v14 op_sel_hi:[1,1,0]
	v_fma_mix_f32 v15, v19, v62, v15 op_sel:[0,1,0] op_sel_hi:[1,1,0]
	v_add_f32_dpp v18, v18, v18 quad_perm:[1,0,3,2] row_mask:0xf bank_mask:0xf bound_ctrl:1
	v_fma_mix_f32 v16, v19, v63, v16 op_sel_hi:[1,1,0]
	v_fma_mix_f32 v17, v19, v63, v17 op_sel:[0,1,0] op_sel_hi:[1,1,0]
	v_add_f32_dpp v18, v18, v18 quad_perm:[2,3,0,1] row_mask:0xf bank_mask:0xf bound_ctrl:1
	v_fma_mix_f32 v23, v10, v98, 0 op_sel_hi:[0,1,0]
	v_fma_mix_f32 v23, v11, v98, v23 op_sel:[0,1,0] op_sel_hi:[0,1,0]
	v_add_f32_dpp v18, v18, v18 row_ror:4 row_mask:0xf bank_mask:0xf bound_ctrl:1
	v_fma_mix_f32 v23, v12, v99, v23 op_sel_hi:[0,1,0]
	v_fma_mix_f32 v23, v13, v99, v23 op_sel:[0,1,0] op_sel_hi:[0,1,0]
	v_add_f32_dpp v18, v18, v18 row_ror:8 row_mask:0xf bank_mask:0xf bound_ctrl:1
	s_waitcnt lgkmcnt(3)
	ds_read_b128 v[90:93], v40 offset:1792
	v_fma_mix_f32 v10, v18, v64, v14 op_sel_hi:[0,1,0]
	ds_read_b128 v[96:99], v40 offset:5888
	v_fma_mix_f32 v11, v18, v64, v15 op_sel:[0,1,0] op_sel_hi:[0,1,0]
	ds_read_b64 v[94:95], v41 offset:9088
	v_fma_mix_f32 v12, v18, v65, v16 op_sel_hi:[0,1,0]
	v_fma_mix_f32 v13, v18, v65, v17 op_sel:[0,1,0] op_sel_hi:[0,1,0]
	v_mov_b32_dpp v19, v36 row_newbcast:5 row_mask:0xf bank_mask:0xf
	v_fma_mix_f32 v18, v10, v76, 0 op_sel_hi:[0,1,0]
	v_fma_mix_f32 v14, v10, v70, v10 op_sel_hi:[0,1,0]
	v_fma_mix_f32 v18, v11, v76, v18 op_sel:[0,1,0] op_sel_hi:[0,1,0]
	v_fma_mix_f32 v15, v11, v70, v11 op_sel:[0,1,0] op_sel_hi:[0,1,0]
	v_fma_mix_f32 v18, v12, v77, v18 op_sel_hi:[0,1,0]
	v_fma_mix_f32 v16, v12, v71, v12 op_sel_hi:[0,1,0]
	v_fma_mix_f32 v18, v13, v77, v18 op_sel:[0,1,0] op_sel_hi:[0,1,0]
	v_fma_mix_f32 v17, v13, v71, v13 op_sel:[0,1,0] op_sel_hi:[0,1,0]
	v_fma_mix_f32 v14, v19, v72, v14 op_sel_hi:[1,1,0]
	v_fma_mix_f32 v15, v19, v72, v15 op_sel:[0,1,0] op_sel_hi:[1,1,0]
	v_add_f32_dpp v18, v18, v18 quad_perm:[1,0,3,2] row_mask:0xf bank_mask:0xf bound_ctrl:1
	v_fma_mix_f32 v16, v19, v73, v16 op_sel_hi:[1,1,0]
	v_fma_mix_f32 v17, v19, v73, v17 op_sel:[0,1,0] op_sel_hi:[1,1,0]
	v_add_f32_dpp v18, v18, v18 quad_perm:[2,3,0,1] row_mask:0xf bank_mask:0xf bound_ctrl:1
	v_fma_mix_f32 v24, v10, v68, 0 op_sel_hi:[0,1,0]
	v_fma_mix_f32 v24, v11, v68, v24 op_sel:[0,1,0] op_sel_hi:[0,1,0]
	v_add_f32_dpp v18, v18, v18 row_ror:4 row_mask:0xf bank_mask:0xf bound_ctrl:1
	v_fma_mix_f32 v24, v12, v69, v24 op_sel_hi:[0,1,0]
	v_fma_mix_f32 v24, v13, v69, v24 op_sel:[0,1,0] op_sel_hi:[0,1,0]
	v_add_f32_dpp v18, v18, v18 row_ror:8 row_mask:0xf bank_mask:0xf bound_ctrl:1
	s_waitcnt lgkmcnt(3)
; __device__ __forceinline__ float row_sum16(float v) { v += __shfl_xor(v, 1); v += __shfl_xor(v, 2); v += __shfl_xor(v, 4); v += __shfl_xor(v, 8); return v; }
; __device__ __forceinline__ float row_sum16(float v) { v += dppf<0xB1>(v); v += dppf<0x4E>(v); v += dppf<0x124>(v); v += dppf<0x128>(v); return v; }
; #define RW_LOAD(slot, step) do { const size_t ro_ = (size_t)row_of(step) * RWW; \
;       s_ok[slot] = *(const h16x8*)((p_rec + ro_ * 3) + urec); s_b[slot] = *(const h16x4*)((p_rec + ro_ * 3) + urec + 8); \
;       s_kr[slot] = *(const h16x8*)((p_sh + ro_ * 2) + ush); s_v[slot] = (p_v + ro_)[uvoff]; } while (0)
; template <int VAR>
; __device__ __forceinline__ void ph_rw_scan(const Params& P) {
;     ...
;       for (int uu = 0; uu < RW_U; ++uu) {
;         const float vv = (float)s_v[uu];
;         const u32x4 p_ok = __builtin_bit_cast(u32x4, s_ok[uu]), p_kr = __builtin_bit_cast(u32x4, s_kr[uu]);
;         const u32x2 p_bb = __builtin_bit_cast(u32x2, s_b[uu]);
;         const unsigned om0 = p_ok[0], om1 = p_ok[1], kd0 = p_ok[2], kd1 = p_ok[3];
;         const unsigned kk0 = p_kr[0], kk1 = p_kr[1], r0_ = p_kr[2], r1_ = p_kr[3];
;         const unsigned b0_ = p_bb[0], b1_ = p_bb[1];
;         float sa = fmix_lo(S[0], kk0, 0.f); sa = fmix_hi(S[1], kk0, sa);
;         float sb = fmix_lo(S[2], kk1, 0.f); sb = fmix_hi(S[3], kk1, sb);
;         sa = row_sum16(sa + sb);
;         S[0] = fmix_lo(S[0], om0, S[0]); S[1] = fmix_hi(S[1], om0, S[1]); S[2] = fmix_lo(S[2], om1, S[2]); S[3] = fmix_hi(S[3], om1, S[3]);
;         S[0] = fmix_lo(sa, b0_, S[0]); S[1] = fmix_hi(sa, b0_, S[1]); S[2] = fmix_lo(sa, b1_, S[2]); S[3] = fmix_hi(sa, b1_, S[3]);
;         S[0] = fmix_lo(vv, kd0, S[0]); S[1] = fmix_hi(vv, kd0, S[1]); S[2] = fmix_lo(vv, kd1, S[2]); S[3] = fmix_hi(vv, kd1, S[3]);
;         float y = fmix_lo(S[0], r0_, 0.f); y = fmix_hi(S[1], r0_, y);
;         float y2 = fmix_lo(S[2], r1_, 0.f); y2 = fmix_hi(S[3], r1_, y2);
;         y += y2;
;         if (VAR == 0 && islat) {
;           y = row_sum16(y);
;           if (q == 0) yout[((size_t)dir * NL + row_of(t0 + uu)) * RWW + hh * 64 + vrow] = (h16)y;
;         }
;         if (VAR != 0) asm volatile("" :: "v"(y));
;         const int nstep = t0 + uu + RW_U < RW_NS ? t0 + uu + RW_U : RW_NS - 1;
;         if (VAR != 2) RW_LOAD(uu, nstep);
	ds_read_b128 v[60:63], v40 offset:2048
	v_fma_mix_f32 v10, v18, v74, v14 op_sel_hi:[0,1,0]
	ds_read_b128 v[66:69], v40 offset:6144
	v_fma_mix_f32 v11, v18, v74, v15 op_sel:[0,1,0] op_sel_hi:[0,1,0]
	ds_read_b64 v[64:65], v41 offset:9216
	v_fma_mix_f32 v12, v18, v75, v16 op_sel_hi:[0,1,0]
	v_fma_mix_f32 v13, v18, v75, v17 op_sel:[0,1,0] op_sel_hi:[0,1,0]
	v_mov_b32_dpp v19, v36 row_newbcast:6 row_mask:0xf bank_mask:0xf
	v_fma_mix_f32 v18, v10, v86, 0 op_sel_hi:[0,1,0]
	v_fma_mix_f32 v14, v10, v80, v10 op_sel_hi:[0,1,0]
	v_fma_mix_f32 v18, v11, v86, v18 op_sel:[0,1,0] op_sel_hi:[0,1,0]
	v_fma_mix_f32 v15, v11, v80, v11 op_sel:[0,1,0] op_sel_hi:[0,1,0]
	v_fma_mix_f32 v18, v12, v87, v18 op_sel_hi:[0,1,0]
	v_fma_mix_f32 v16, v12, v81, v12 op_sel_hi:[0,1,0]
	v_fma_mix_f32 v18, v13, v87, v18 op_sel:[0,1,0] op_sel_hi:[0,1,0]
	v_fma_mix_f32 v17, v13, v81, v13 op_sel:[0,1,0] op_sel_hi:[0,1,0]
	v_fma_mix_f32 v14, v19, v82, v14 op_sel_hi:[1,1,0]
	v_fma_mix_f32 v15, v19, v82, v15 op_sel:[0,1,0] op_sel_hi:[1,1,0]
	v_add_f32_dpp v18, v18, v18 quad_perm:[1,0,3,2] row_mask:0xf bank_mask:0xf bound_ctrl:1
	v_fma_mix_f32 v16, v19, v83, v16 op_sel_hi:[1,1,0]
	v_fma_mix_f32 v17, v19, v83, v17 op_sel:[0,1,0] op_sel_hi:[1,1,0]
	v_add_f32_dpp v18, v18, v18 quad_perm:[2,3,0,1] row_mask:0xf bank_mask:0xf bound_ctrl:1
	v_fma_mix_f32 v25, v10, v78, 0 op_sel_hi:[0,1,0]
	v_fma_mix_f32 v25, v11, v78, v25 op_sel:[0,1,0] op_sel_hi:[0,1,0]
	v_add_f32_dpp v18, v18, v18 row_ror:4 row_mask:0xf bank_mask:0xf bound_ctrl:1
	v_fma_mix_f32 v25, v12, v79, v25 op_sel_hi:[0,1,0]
	v_fma_mix_f32 v25, v13, v79, v25 op_sel:[0,1,0] op_sel_hi:[0,1,0]
	v_add_f32_dpp v18, v18, v18 row_ror:8 row_mask:0xf bank_mask:0xf bound_ctrl:1
	s_waitcnt lgkmcnt(3)
	ds_read_b128 v[70:73], v40 offset:2304
	v_fma_mix_f32 v10, v18, v84, v14 op_sel_hi:[0,1,0]
	ds_read_b128 v[76:79], v40 offset:6400
	v_fma_mix_f32 v11, v18, v84, v15 op_sel:[0,1,0] op_sel_hi:[0,1,0]
	ds_read_b64 v[74:75], v41 offset:9344
	v_fma_mix_f32 v12, v18, v85, v16 op_sel_hi:[0,1,0]
	v_fma_mix_f32 v13, v18, v85, v17 op_sel:[0,1,0] op_sel_hi:[0,1,0]
	v_mov_b32_dpp v19, v36 row_newbcast:7 row_mask:0xf bank_mask:0xf
	v_fma_mix_f32 v18, v10, v96, 0 op_sel_hi:[0,1,0]
	v_fma_mix_f32 v14, v10, v90, v10 op_sel_hi:[0,1,0]
	v_fma_mix_f32 v18, v11, v96, v18 op_sel:[0,1,0] op_sel_hi:[0,1,0]
	v_fma_mix_f32 v15, v11, v90, v11 op_sel:[0,1,0] op_sel_hi:[0,1,0]
	v_fma_mix_f32 v18, v12, v97, v18 op_sel_hi:[0,1,0]
	v_fma_mix_f32 v16, v12, v91, v12 op_sel_hi:[0,1,0]
	v_fma_mix_f32 v18, v13, v97, v18 op_sel:[0,1,0] op_sel_hi:[0,1,0]
	v_fma_mix_f32 v17, v13, v91, v13 op_sel:[0,1,0] op_sel_hi:[0,1,0]
	v_fma_mix_f32 v14, v19, v92, v14 op_sel_hi:[1,1,0]
	v_fma_mix_f32 v15, v19, v92, v15 op_sel:[0,1,0] op_sel_hi:[1,1,0]
	v_add_f32_dpp v18, v18, v18 quad_perm:[1,0,3,2] row_mask:0xf bank_mask:0xf bound_ctrl:1
	v_fma_mix_f32 v16, v19, v93, v16 op_sel_hi:[1,1,0]
	v_fma_mix_f32 v17, v19, v93, v17 op_sel:[0,1,0] op_sel_hi:[1,1,0]
	v_add_f32_dpp v18, v18, v18 quad_perm:[2,3,0,1] row_mask:0xf bank_mask:0xf bound_ctrl:1
	v_fma_mix_f32 v26, v10, v88, 0 op_sel_hi:[0,1,0]
	v_fma_mix_f32 v26, v11, v88, v26 op_sel:[0,1,0] op_sel_hi:[0,1,0]
	v_add_f32_dpp v18, v18, v18 row_ror:4 row_mask:0xf bank_mask:0xf bound_ctrl:1
	v_fma_mix_f32 v26, v12, v89, v26 op_sel_hi:[0,1,0]
	v_fma_mix_f32 v26, v13, v89, v26 op_sel:[0,1,0] op_sel_hi:[0,1,0]
	v_add_f32_dpp v18, v18, v18 row_ror:8 row_mask:0xf bank_mask:0xf bound_ctrl:1
	s_waitcnt lgkmcnt(3)
	ds_read_b128 v[80:83], v40 offset:2560
	v_fma_mix_f32 v10, v18, v94, v14 op_sel_hi:[0,1,0]
	ds_read_b128 v[86:89], v40 offset:6656
	v_fma_mix_f32 v11, v18, v94, v15 op_sel:[0,1,0] op_sel_hi:[0,1,0]
	ds_read_b64 v[84:85], v41 offset:9472
	v_fma_mix_f32 v12, v18, v95, v16 op_sel_hi:[0,1,0]
	v_fma_mix_f32 v13, v18, v95, v17 op_sel:[0,1,0] op_sel_hi:[0,1,0]
	v_mov_b32_dpp v19, v36 row_newbcast:8 row_mask:0xf bank_mask:0xf
	v_fma_mix_f32 v18, v10, v66, 0 op_sel_hi:[0,1,0]
	v_fma_mix_f32 v14, v10, v60, v10 op_sel_hi:[0,1,0]
	v_fma_mix_f32 v18, v11, v66, v18 op_sel:[0,1,0] op_sel_hi:[0,1,0]
	v_fma_mix_f32 v15, v11, v60, v11 op_sel:[0,1,0] op_sel_hi:[0,1,0]
	v_fma_mix_f32 v18, v12, v67, v18 op_sel_hi:[0,1,0]
	v_fma_mix_f32 v16, v12, v61, v12 op_sel_hi:[0,1,0]
	v_fma_mix_f32 v18, v13, v67, v18 op_sel:[0,1,0] op_sel_hi:[0,1,0]
	v_fma_mix_f32 v17, v13, v61, v13 op_sel:[0,1,0] op_sel_hi:[0,1,0]
	v_fma_mix_f32 v14, v19, v62, v14 op_sel_hi:[1,1,0]
	v_fma_mix_f32 v15, v19, v62, v15 op_sel:[0,1,0] op_sel_hi:[1,1,0]
	v_add_f32_dpp v18, v18, v18 quad_perm:[1,0,3,2] row_mask:0xf bank_mask:0xf bound_ctrl:1
	v_fma_mix_f32 v16, v19, v63, v16 op_sel_hi:[1,1,0]
	v_fma_mix_f32 v17, v19, v63, v17 op_sel:[0,1,0] op_sel_hi:[1,1,0]
	v_add_f32_dpp v18, v18, v18 quad_perm:[2,3,0,1] row_mask:0xf bank_mask:0xf bound_ctrl:1
	v_fma_mix_f32 v27, v10, v98, 0 op_sel_hi:[0,1,0]
	v_fma_mix_f32 v27, v11, v98, v27 op_sel:[0,1,0] op_sel_hi:[0,1,0]
	v_add_f32_dpp v18, v18, v18 row_ror:4 row_mask:0xf bank_mask:0xf bound_ctrl:1
	v_fma_mix_f32 v27, v12, v99, v27 op_sel_hi:[0,1,0]
	v_fma_mix_f32 v27, v13, v99, v27 op_sel:[0,1,0] op_sel_hi:[0,1,0]
	v_add_f32_dpp v18, v18, v18 row_ror:8 row_mask:0xf bank_mask:0xf bound_ctrl:1
	s_waitcnt lgkmcnt(3)
; __device__ __forceinline__ float row_sum16(float v) { v += __shfl_xor(v, 1); v += __shfl_xor(v, 2); v += __shfl_xor(v, 4); v += __shfl_xor(v, 8); return v; }
; __device__ __forceinline__ float row_sum16(float v) { v += dppf<0xB1>(v); v += dppf<0x4E>(v); v += dppf<0x124>(v); v += dppf<0x128>(v); return v; }
; #define RW_LOAD(slot, step) do { const size_t ro_ = (size_t)row_of(step) * RWW; \
;       s_ok[slot] = *(const h16x8*)((p_rec + ro_ * 3) + urec); s_b[slot] = *(const h16x4*)((p_rec + ro_ * 3) + urec + 8); \
;       s_kr[slot] = *(const h16x8*)((p_sh + ro_ * 2) + ush); s_v[slot] = (p_v + ro_)[uvoff]; } while (0)
; template <int VAR>
; __device__ __forceinline__ void ph_rw_scan(const Params& P) {
;     ...
;       for (int uu = 0; uu < RW_U; ++uu) {
;         const float vv = (float)s_v[uu];
;         const u32x4 p_ok = __builtin_bit_cast(u32x4, s_ok[uu]), p_kr = __builtin_bit_cast(u32x4, s_kr[uu]);
;         const u32x2 p_bb = __builtin_bit_cast(u32x2, s_b[uu]);
;         const unsigned om0 = p_ok[0], om1 = p_ok[1], kd0 = p_ok[2], kd1 = p_ok[3];
;         const unsigned kk0 = p_kr[0], kk1 = p_kr[1], r0_ = p_kr[2], r1_ = p_kr[3];
;         const unsigned b0_ = p_bb[0], b1_ = p_bb[1];
;         float sa = fmix_lo(S[0], kk0, 0.f); sa = fmix_hi(S[1], kk0, sa);
;         float sb = fmix_lo(S[2], kk1, 0.f); sb = fmix_hi(S[3], kk1, sb);
;         sa = row_sum16(sa + sb);
;         S[0] = fmix_lo(S[0], om0, S[0]); S[1] = fmix_hi(S[1], om0, S[1]); S[2] = fmix_lo(S[2], om1, S[2]); S[3] = fmix_hi(S[3], om1, S[3]);
;         S[0] = fmix_lo(sa, b0_, S[0]); S[1] = fmix_hi(sa, b0_, S[1]); S[2] = fmix_lo(sa, b1_, S[2]); S[3] = fmix_hi(sa, b1_, S[3]);
;         S[0] = fmix_lo(vv, kd0, S[0]); S[1] = fmix_hi(vv, kd0, S[1]); S[2] = fmix_lo(vv, kd1, S[2]); S[3] = fmix_hi(vv, kd1, S[3]);
;         float y = fmix_lo(S[0], r0_, 0.f); y = fmix_hi(S[1], r0_, y);
;         float y2 = fmix_lo(S[2], r1_, 0.f); y2 = fmix_hi(S[3], r1_, y2);
;         y += y2;
;         if (VAR == 0 && islat) {
;           y = row_sum16(y);
;           if (q == 0) yout[((size_t)dir * NL + row_of(t0 + uu)) * RWW + hh * 64 + vrow] = (h16)y;
;         }
;         if (VAR != 0) asm volatile("" :: "v"(y));
;         const int nstep = t0 + uu + RW_U < RW_NS ? t0 + uu + RW_U : RW_NS - 1;
;         if (VAR != 2) RW_LOAD(uu, nstep);
	ds_read_b128 v[90:93], v40 offset:2816
	v_fma_mix_f32 v10, v18, v64, v14 op_sel_hi:[0,1,0]
	ds_read_b128 v[96:99], v40 offset:6912
	v_fma_mix_f32 v11, v18, v64, v15 op_sel:[0,1,0] op_sel_hi:[0,1,0]
	ds_read_b64 v[94:95], v41 offset:9600
	v_fma_mix_f32 v12, v18, v65, v16 op_sel_hi:[0,1,0]
	v_fma_mix_f32 v13, v18, v65, v17 op_sel:[0,1,0] op_sel_hi:[0,1,0]
	v_mov_b32_dpp v19, v36 row_newbcast:9 row_mask:0xf bank_mask:0xf
	v_fma_mix_f32 v18, v10, v76, 0 op_sel_hi:[0,1,0]
	v_fma_mix_f32 v14, v10, v70, v10 op_sel_hi:[0,1,0]
	v_fma_mix_f32 v18, v11, v76, v18 op_sel:[0,1,0] op_sel_hi:[0,1,0]
	v_fma_mix_f32 v15, v11, v70, v11 op_sel:[0,1,0] op_sel_hi:[0,1,0]
	v_fma_mix_f32 v18, v12, v77, v18 op_sel_hi:[0,1,0]
	v_fma_mix_f32 v16, v12, v71, v12 op_sel_hi:[0,1,0]
	v_fma_mix_f32 v18, v13, v77, v18 op_sel:[0,1,0] op_sel_hi:[0,1,0]
	v_fma_mix_f32 v17, v13, v71, v13 op_sel:[0,1,0] op_sel_hi:[0,1,0]
	v_fma_mix_f32 v14, v19, v72, v14 op_sel_hi:[1,1,0]
	v_fma_mix_f32 v15, v19, v72, v15 op_sel:[0,1,0] op_sel_hi:[1,1,0]
	v_add_f32_dpp v18, v18, v18 quad_perm:[1,0,3,2] row_mask:0xf bank_mask:0xf bound_ctrl:1
	v_fma_mix_f32 v16, v19, v73, v16 op_sel_hi:[1,1,0]
	v_fma_mix_f32 v17, v19, v73, v17 op_sel:[0,1,0] op_sel_hi:[1,1,0]
	v_add_f32_dpp v18, v18, v18 quad_perm:[2,3,0,1] row_mask:0xf bank_mask:0xf bound_ctrl:1
	v_fma_mix_f32 v28, v10, v68, 0 op_sel_hi:[0,1,0]
	v_fma_mix_f32 v28, v11, v68, v28 op_sel:[0,1,0] op_sel_hi:[0,1,0]
	v_add_f32_dpp v18, v18, v18 row_ror:4 row_mask:0xf bank_mask:0xf bound_ctrl:1
	v_fma_mix_f32 v28, v12, v69, v28 op_sel_hi:[0,1,0]
	v_fma_mix_f32 v28, v13, v69, v28 op_sel:[0,1,0] op_sel_hi:[0,1,0]
	v_add_f32_dpp v18, v18, v18 row_ror:8 row_mask:0xf bank_mask:0xf bound_ctrl:1
	s_waitcnt lgkmcnt(3)
	ds_read_b128 v[60:63], v40 offset:3072
	v_fma_mix_f32 v10, v18, v74, v14 op_sel_hi:[0,1,0]
	ds_read_b128 v[66:69], v40 offset:7168
	v_fma_mix_f32 v11, v18, v74, v15 op_sel:[0,1,0] op_sel_hi:[0,1,0]
	ds_read_b64 v[64:65], v41 offset:9728
	v_fma_mix_f32 v12, v18, v75, v16 op_sel_hi:[0,1,0]
	v_fma_mix_f32 v13, v18, v75, v17 op_sel:[0,1,0] op_sel_hi:[0,1,0]
	v_mov_b32_dpp v19, v36 row_newbcast:10 row_mask:0xf bank_mask:0xf
	v_fma_mix_f32 v18, v10, v86, 0 op_sel_hi:[0,1,0]
	v_fma_mix_f32 v14, v10, v80, v10 op_sel_hi:[0,1,0]
	v_fma_mix_f32 v18, v11, v86, v18 op_sel:[0,1,0] op_sel_hi:[0,1,0]
	v_fma_mix_f32 v15, v11, v80, v11 op_sel:[0,1,0] op_sel_hi:[0,1,0]
	v_fma_mix_f32 v18, v12, v87, v18 op_sel_hi:[0,1,0]
	v_fma_mix_f32 v16, v12, v81, v12 op_sel_hi:[0,1,0]
	v_fma_mix_f32 v18, v13, v87, v18 op_sel:[0,1,0] op_sel_hi:[0,1,0]
	v_fma_mix_f32 v17, v13, v81, v13 op_sel:[0,1,0] op_sel_hi:[0,1,0]
	v_fma_mix_f32 v14, v19, v82, v14 op_sel_hi:[1,1,0]
	v_fma_mix_f32 v15, v19, v82, v15 op_sel:[0,1,0] op_sel_hi:[1,1,0]
	v_add_f32_dpp v18, v18, v18 quad_perm:[1,0,3,2] row_mask:0xf bank_mask:0xf bound_ctrl:1
	v_fma_mix_f32 v16, v19, v83, v16 op_sel_hi:[1,1,0]
	v_fma_mix_f32 v17, v19, v83, v17 op_sel:[0,1,0] op_sel_hi:[1,1,0]
	v_add_f32_dpp v18, v18, v18 quad_perm:[2,3,0,1] row_mask:0xf bank_mask:0xf bound_ctrl:1
	v_fma_mix_f32 v29, v10, v78, 0 op_sel_hi:[0,1,0]
	v_fma_mix_f32 v29, v11, v78, v29 op_sel:[0,1,0] op_sel_hi:[0,1,0]
	v_add_f32_dpp v18, v18, v18 row_ror:4 row_mask:0xf bank_mask:0xf bound_ctrl:1
	v_fma_mix_f32 v29, v12, v79, v29 op_sel_hi:[0,1,0]
	v_fma_mix_f32 v29, v13, v79, v29 op_sel:[0,1,0] op_sel_hi:[0,1,0]
	v_add_f32_dpp v18, v18, v18 row_ror:8 row_mask:0xf bank_mask:0xf bound_ctrl:1
	s_waitcnt lgkmcnt(3)
	ds_read_b128 v[70:73], v40 offset:3328
	v_fma_mix_f32 v10, v18, v84, v14 op_sel_hi:[0,1,0]
	ds_read_b128 v[76:79], v40 offset:7424
	v_fma_mix_f32 v11, v18, v84, v15 op_sel:[0,1,0] op_sel_hi:[0,1,0]
	ds_read_b64 v[74:75], v41 offset:9856
	v_fma_mix_f32 v12, v18, v85, v16 op_sel_hi:[0,1,0]
	v_fma_mix_f32 v13, v18, v85, v17 op_sel:[0,1,0] op_sel_hi:[0,1,0]
	v_mov_b32_dpp v19, v36 row_newbcast:11 row_mask:0xf bank_mask:0xf
	v_fma_mix_f32 v18, v10, v96, 0 op_sel_hi:[0,1,0]
	v_fma_mix_f32 v14, v10, v90, v10 op_sel_hi:[0,1,0]
	v_fma_mix_f32 v18, v11, v96, v18 op_sel:[0,1,0] op_sel_hi:[0,1,0]
	v_fma_mix_f32 v15, v11, v90, v11 op_sel:[0,1,0] op_sel_hi:[0,1,0]
	v_fma_mix_f32 v18, v12, v97, v18 op_sel_hi:[0,1,0]
	v_fma_mix_f32 v16, v12, v91, v12 op_sel_hi:[0,1,0]
	v_fma_mix_f32 v18, v13, v97, v18 op_sel:[0,1,0] op_sel_hi:[0,1,0]
	v_fma_mix_f32 v17, v13, v91, v13 op_sel:[0,1,0] op_sel_hi:[0,1,0]
	v_fma_mix_f32 v14, v19, v92, v14 op_sel_hi:[1,1,0]
	v_fma_mix_f32 v15, v19, v92, v15 op_sel:[0,1,0] op_sel_hi:[1,1,0]
	v_add_f32_dpp v18, v18, v18 quad_perm:[1,0,3,2] row_mask:0xf bank_mask:0xf bound_ctrl:1
	v_fma_mix_f32 v16, v19, v93, v16 op_sel_hi:[1,1,0]
	v_fma_mix_f32 v17, v19, v93, v17 op_sel:[0,1,0] op_sel_hi:[1,1,0]
	v_add_f32_dpp v18, v18, v18 quad_perm:[2,3,0,1] row_mask:0xf bank_mask:0xf bound_ctrl:1
	v_fma_mix_f32 v30, v10, v88, 0 op_sel_hi:[0,1,0]
	v_fma_mix_f32 v30, v11, v88, v30 op_sel:[0,1,0] op_sel_hi:[0,1,0]
	v_add_f32_dpp v18, v18, v18 row_ror:4 row_mask:0xf bank_mask:0xf bound_ctrl:1
	v_fma_mix_f32 v30, v12, v89, v30 op_sel_hi:[0,1,0]
	v_fma_mix_f32 v30, v13, v89, v30 op_sel:[0,1,0] op_sel_hi:[0,1,0]
	v_add_f32_dpp v18, v18, v18 row_ror:8 row_mask:0xf bank_mask:0xf bound_ctrl:1
	s_waitcnt lgkmcnt(3)
; __device__ __forceinline__ float row_sum16(float v) { v += __shfl_xor(v, 1); v += __shfl_xor(v, 2); v += __shfl_xor(v, 4); v += __shfl_xor(v, 8); return v; }
; __device__ __forceinline__ float row_sum16(float v) { v += dppf<0xB1>(v); v += dppf<0x4E>(v); v += dppf<0x124>(v); v += dppf<0x128>(v); return v; }
; #define RW_LOAD(slot, step) do { const size_t ro_ = (size_t)row_of(step) * RWW; \
;       s_ok[slot] = *(const h16x8*)((p_rec + ro_ * 3) + urec); s_b[slot] = *(const h16x4*)((p_rec + ro_ * 3) + urec + 8); \
;       s_kr[slot] = *(const h16x8*)((p_sh + ro_ * 2) + ush); s_v[slot] = (p_v + ro_)[uvoff]; } while (0)
; template <int VAR>
; __device__ __forceinline__ void ph_rw_scan(const Params& P) {
;     ...
;       for (int uu = 0; uu < RW_U; ++uu) {
;         const float vv = (float)s_v[uu];
;         const u32x4 p_ok = __builtin_bit_cast(u32x4, s_ok[uu]), p_kr = __builtin_bit_cast(u32x4, s_kr[uu]);
;         const u32x2 p_bb = __builtin_bit_cast(u32x2, s_b[uu]);
;         const unsigned om0 = p_ok[0], om1 = p_ok[1], kd0 = p_ok[2], kd1 = p_ok[3];
;         const unsigned kk0 = p_kr[0], kk1 = p_kr[1], r0_ = p_kr[2], r1_ = p_kr[3];
;         const unsigned b0_ = p_bb[0], b1_ = p_bb[1];
;         float sa = fmix_lo(S[0], kk0, 0.f); sa = fmix_hi(S[1], kk0, sa);
;         float sb = fmix_lo(S[2], kk1, 0.f); sb = fmix_hi(S[3], kk1, sb);
;         sa = row_sum16(sa + sb);
;         S[0] = fmix_lo(S[0], om0, S[0]); S[1] = fmix_hi(S[1], om0, S[1]); S[2] = fmix_lo(S[2], om1, S[2]); S[3] = fmix_hi(S[3], om1, S[3]);
;         S[0] = fmix_lo(sa, b0_, S[0]); S[1] = fmix_hi(sa, b0_, S[1]); S[2] = fmix_lo(sa, b1_, S[2]); S[3] = fmix_hi(sa, b1_, S[3]);
;         S[0] = fmix_lo(vv, kd0, S[0]); S[1] = fmix_hi(vv, kd0, S[1]); S[2] = fmix_lo(vv, kd1, S[2]); S[3] = fmix_hi(vv, kd1, S[3]);
;         float y = fmix_lo(S[0], r0_, 0.f); y = fmix_hi(S[1], r0_, y);
;         float y2 = fmix_lo(S[2], r1_, 0.f); y2 = fmix_hi(S[3], r1_, y2);
;         y += y2;
;         if (VAR == 0 && islat) {
;           y = row_sum16(y);
;           if (q == 0) yout[((size_t)dir * NL + row_of(t0 + uu)) * RWW + hh * 64 + vrow] = (h16)y;
;         }
;         if (VAR != 0) asm volatile("" :: "v"(y));
;         const int nstep = t0 + uu + RW_U < RW_NS ? t0 + uu + RW_U : RW_NS - 1;
;         if (VAR != 2) RW_LOAD(uu, nstep);
	ds_read_b128 v[80:83], v40 offset:3584
	v_fma_mix_f32 v10, v18, v94, v14 op_sel_hi:[0,1,0]
	ds_read_b128 v[86:89], v40 offset:7680
	v_fma_mix_f32 v11, v18, v94, v15 op_sel:[0,1,0] op_sel_hi:[0,1,0]
	ds_read_b64 v[84:85], v41 offset:9984
	v_fma_mix_f32 v12, v18, v95, v16 op_sel_hi:[0,1,0]
	v_fma_mix_f32 v13, v18, v95, v17 op_sel:[0,1,0] op_sel_hi:[0,1,0]
	v_mov_b32_dpp v19, v36 row_newbcast:12 row_mask:0xf bank_mask:0xf
	v_fma_mix_f32 v18, v10, v66, 0 op_sel_hi:[0,1,0]
	v_fma_mix_f32 v14, v10, v60, v10 op_sel_hi:[0,1,0]
	v_fma_mix_f32 v18, v11, v66, v18 op_sel:[0,1,0] op_sel_hi:[0,1,0]
	v_fma_mix_f32 v15, v11, v60, v11 op_sel:[0,1,0] op_sel_hi:[0,1,0]
	v_fma_mix_f32 v18, v12, v67, v18 op_sel_hi:[0,1,0]
	v_fma_mix_f32 v16, v12, v61, v12 op_sel_hi:[0,1,0]
	v_fma_mix_f32 v18, v13, v67, v18 op_sel:[0,1,0] op_sel_hi:[0,1,0]
	v_fma_mix_f32 v17, v13, v61, v13 op_sel:[0,1,0] op_sel_hi:[0,1,0]
	v_fma_mix_f32 v14, v19, v62, v14 op_sel_hi:[1,1,0]
	v_fma_mix_f32 v15, v19, v62, v15 op_sel:[0,1,0] op_sel_hi:[1,1,0]
	v_add_f32_dpp v18, v18, v18 quad_perm:[1,0,3,2] row_mask:0xf bank_mask:0xf bound_ctrl:1
	v_fma_mix_f32 v16, v19, v63, v16 op_sel_hi:[1,1,0]
	v_fma_mix_f32 v17, v19, v63, v17 op_sel:[0,1,0] op_sel_hi:[1,1,0]
	v_add_f32_dpp v18, v18, v18 quad_perm:[2,3,0,1] row_mask:0xf bank_mask:0xf bound_ctrl:1
	v_fma_mix_f32 v31, v10, v98, 0 op_sel_hi:[0,1,0]
	v_fma_mix_f32 v31, v11, v98, v31 op_sel:[0,1,0] op_sel_hi:[0,1,0]
	v_add_f32_dpp v18, v18, v18 row_ror:4 row_mask:0xf bank_mask:0xf bound_ctrl:1
	v_fma_mix_f32 v31, v12, v99, v31 op_sel_hi:[0,1,0]
	v_fma_mix_f32 v31, v13, v99, v31 op_sel:[0,1,0] op_sel_hi:[0,1,0]
	v_add_f32_dpp v18, v18, v18 row_ror:8 row_mask:0xf bank_mask:0xf bound_ctrl:1
	s_waitcnt lgkmcnt(3)
	ds_read_b128 v[90:93], v40 offset:3840
	v_fma_mix_f32 v10, v18, v64, v14 op_sel_hi:[0,1,0]
	ds_read_b128 v[96:99], v40 offset:7936
	v_fma_mix_f32 v11, v18, v64, v15 op_sel:[0,1,0] op_sel_hi:[0,1,0]
	ds_read_b64 v[94:95], v41 offset:10112
	v_fma_mix_f32 v12, v18, v65, v16 op_sel_hi:[0,1,0]
	v_fma_mix_f32 v13, v18, v65, v17 op_sel:[0,1,0] op_sel_hi:[0,1,0]
	v_mov_b32_dpp v19, v36 row_newbcast:13 row_mask:0xf bank_mask:0xf
	v_fma_mix_f32 v18, v10, v76, 0 op_sel_hi:[0,1,0]
	v_fma_mix_f32 v14, v10, v70, v10 op_sel_hi:[0,1,0]
	v_fma_mix_f32 v18, v11, v76, v18 op_sel:[0,1,0] op_sel_hi:[0,1,0]
	v_fma_mix_f32 v15, v11, v70, v11 op_sel:[0,1,0] op_sel_hi:[0,1,0]
	v_fma_mix_f32 v18, v12, v77, v18 op_sel_hi:[0,1,0]
	v_fma_mix_f32 v16, v12, v71, v12 op_sel_hi:[0,1,0]
	v_fma_mix_f32 v18, v13, v77, v18 op_sel:[0,1,0] op_sel_hi:[0,1,0]
	v_fma_mix_f32 v17, v13, v71, v13 op_sel:[0,1,0] op_sel_hi:[0,1,0]
	v_fma_mix_f32 v14, v19, v72, v14 op_sel_hi:[1,1,0]
	v_fma_mix_f32 v15, v19, v72, v15 op_sel:[0,1,0] op_sel_hi:[1,1,0]
	v_add_f32_dpp v18, v18, v18 quad_perm:[1,0,3,2] row_mask:0xf bank_mask:0xf bound_ctrl:1
	v_fma_mix_f32 v16, v19, v73, v16 op_sel_hi:[1,1,0]
	v_fma_mix_f32 v17, v19, v73, v17 op_sel:[0,1,0] op_sel_hi:[1,1,0]
	v_add_f32_dpp v18, v18, v18 quad_perm:[2,3,0,1] row_mask:0xf bank_mask:0xf bound_ctrl:1
	v_fma_mix_f32 v32, v10, v68, 0 op_sel_hi:[0,1,0]
	v_fma_mix_f32 v32, v11, v68, v32 op_sel:[0,1,0] op_sel_hi:[0,1,0]
	v_add_f32_dpp v18, v18, v18 row_ror:4 row_mask:0xf bank_mask:0xf bound_ctrl:1
	v_fma_mix_f32 v32, v12, v69, v32 op_sel_hi:[0,1,0]
	v_fma_mix_f32 v32, v13, v69, v32 op_sel:[0,1,0] op_sel_hi:[0,1,0]
	v_add_f32_dpp v18, v18, v18 row_ror:8 row_mask:0xf bank_mask:0xf bound_ctrl:1
	s_waitcnt lgkmcnt(3)
	ds_read_b128 v[60:63], v42
	v_fma_mix_f32 v10, v18, v74, v14 op_sel_hi:[0,1,0]
	ds_read_b128 v[66:69], v42 offset:4096
	v_fma_mix_f32 v11, v18, v74, v15 op_sel:[0,1,0] op_sel_hi:[0,1,0]
	ds_read_b64 v[64:65], v43 offset:8192
	v_fma_mix_f32 v12, v18, v75, v16 op_sel_hi:[0,1,0]
	v_fma_mix_f32 v13, v18, v75, v17 op_sel:[0,1,0] op_sel_hi:[0,1,0]
	v_mov_b32_dpp v19, v36 row_newbcast:14 row_mask:0xf bank_mask:0xf
	v_fma_mix_f32 v18, v10, v86, 0 op_sel_hi:[0,1,0]
	v_fma_mix_f32 v14, v10, v80, v10 op_sel_hi:[0,1,0]
	v_fma_mix_f32 v18, v11, v86, v18 op_sel:[0,1,0] op_sel_hi:[0,1,0]
	v_fma_mix_f32 v15, v11, v80, v11 op_sel:[0,1,0] op_sel_hi:[0,1,0]
	v_fma_mix_f32 v18, v12, v87, v18 op_sel_hi:[0,1,0]
	v_fma_mix_f32 v16, v12, v81, v12 op_sel_hi:[0,1,0]
	v_fma_mix_f32 v18, v13, v87, v18 op_sel:[0,1,0] op_sel_hi:[0,1,0]
	v_fma_mix_f32 v17, v13, v81, v13 op_sel:[0,1,0] op_sel_hi:[0,1,0]
	v_fma_mix_f32 v14, v19, v82, v14 op_sel_hi:[1,1,0]
	v_fma_mix_f32 v15, v19, v82, v15 op_sel:[0,1,0] op_sel_hi:[1,1,0]
	v_add_f32_dpp v18, v18, v18 quad_perm:[1,0,3,2] row_mask:0xf bank_mask:0xf bound_ctrl:1
	v_fma_mix_f32 v16, v19, v83, v16 op_sel_hi:[1,1,0]
	v_fma_mix_f32 v17, v19, v83, v17 op_sel:[0,1,0] op_sel_hi:[1,1,0]
	v_add_f32_dpp v18, v18, v18 quad_perm:[2,3,0,1] row_mask:0xf bank_mask:0xf bound_ctrl:1
	v_fma_mix_f32 v33, v10, v78, 0 op_sel_hi:[0,1,0]
	v_fma_mix_f32 v33, v11, v78, v33 op_sel:[0,1,0] op_sel_hi:[0,1,0]
	v_add_f32_dpp v18, v18, v18 row_ror:4 row_mask:0xf bank_mask:0xf bound_ctrl:1
	v_fma_mix_f32 v33, v12, v79, v33 op_sel_hi:[0,1,0]
	v_fma_mix_f32 v33, v13, v79, v33 op_sel:[0,1,0] op_sel_hi:[0,1,0]
	v_add_f32_dpp v18, v18, v18 row_ror:8 row_mask:0xf bank_mask:0xf bound_ctrl:1
	s_waitcnt lgkmcnt(3)
; __device__ __forceinline__ float row_sum16(float v) { v += __shfl_xor(v, 1); v += __shfl_xor(v, 2); v += __shfl_xor(v, 4); v += __shfl_xor(v, 8); return v; }
; __device__ __forceinline__ float row_sum16(float v) { v += dppf<0xB1>(v); v += dppf<0x4E>(v); v += dppf<0x124>(v); v += dppf<0x128>(v); return v; }
; #define RW_LOAD(slot, step) do { const size_t ro_ = (size_t)row_of(step) * RWW; \
;       s_ok[slot] = *(const h16x8*)((p_rec + ro_ * 3) + urec); s_b[slot] = *(const h16x4*)((p_rec + ro_ * 3) + urec + 8); \
;       s_kr[slot] = *(const h16x8*)((p_sh + ro_ * 2) + ush); s_v[slot] = (p_v + ro_)[uvoff]; } while (0)
; template <int VAR>
; __device__ __forceinline__ void ph_rw_scan(const Params& P) {
;     ...
;   for (int wu = blockIdx.x * 4 + wave; wave < 4 && wu < NWU; wu += gridDim.x * 4) {
;     ...
;         float sa = fmix_lo(S[0], kk0, 0.f); sa = fmix_hi(S[1], kk0, sa);
;         float sb = fmix_lo(S[2], kk1, 0.f); sb = fmix_hi(S[3], kk1, sb);
;         sa = row_sum16(sa + sb);
;         S[0] = fmix_lo(S[0], om0, S[0]); S[1] = fmix_hi(S[1], om0, S[1]); S[2] = fmix_lo(S[2], om1, S[2]); S[3] = fmix_hi(S[3], om1, S[3]);
;         S[0] = fmix_lo(sa, b0_, S[0]); S[1] = fmix_hi(sa, b0_, S[1]); S[2] = fmix_lo(sa, b1_, S[2]); S[3] = fmix_hi(sa, b1_, S[3]);
;         S[0] = fmix_lo(vv, kd0, S[0]); S[1] = fmix_hi(vv, kd0, S[1]); S[2] = fmix_lo(vv, kd1, S[2]); S[3] = fmix_hi(vv, kd1, S[3]);
;         float y = fmix_lo(S[0], r0_, 0.f); y = fmix_hi(S[1], r0_, y);
;         float y2 = fmix_lo(S[2], r1_, 0.f); y2 = fmix_hi(S[3], r1_, y2);
;         y += y2;
;         if (VAR == 0 && islat) {
;           y = row_sum16(y);
;           if (q == 0) yout[((size_t)dir * NL + row_of(t0 + uu)) * RWW + hh * 64 + vrow] = (h16)y;
;         }
;         if (VAR != 0) asm volatile("" :: "v"(y));
;         const int nstep = t0 + uu + RW_U < RW_NS ? t0 + uu + RW_U : RW_NS - 1;
;         if (VAR != 2) RW_LOAD(uu, nstep);
;       }
;     }
;     if (VAR != 0) asm volatile("" :: "v"(S[0]), "v"(S[1]), "v"(S[2]), "v"(S[3]));
	ds_read_b128 v[70:73], v42 offset:256
	v_fma_mix_f32 v10, v18, v84, v14 op_sel_hi:[0,1,0]
	ds_read_b128 v[76:79], v42 offset:4352
	v_fma_mix_f32 v11, v18, v84, v15 op_sel:[0,1,0] op_sel_hi:[0,1,0]
	ds_read_b64 v[74:75], v43 offset:8320
	v_fma_mix_f32 v12, v18, v85, v16 op_sel_hi:[0,1,0]
	v_fma_mix_f32 v13, v18, v85, v17 op_sel:[0,1,0] op_sel_hi:[0,1,0]
	v_mov_b32_dpp v19, v36 row_newbcast:15 row_mask:0xf bank_mask:0xf
	v_fma_mix_f32 v18, v10, v96, 0 op_sel_hi:[0,1,0]
	v_fma_mix_f32 v14, v10, v90, v10 op_sel_hi:[0,1,0]
	v_fma_mix_f32 v18, v11, v96, v18 op_sel:[0,1,0] op_sel_hi:[0,1,0]
	v_fma_mix_f32 v15, v11, v90, v11 op_sel:[0,1,0] op_sel_hi:[0,1,0]
	v_fma_mix_f32 v18, v12, v97, v18 op_sel_hi:[0,1,0]
	v_fma_mix_f32 v16, v12, v91, v12 op_sel_hi:[0,1,0]
	v_fma_mix_f32 v18, v13, v97, v18 op_sel:[0,1,0] op_sel_hi:[0,1,0]
	v_fma_mix_f32 v17, v13, v91, v13 op_sel:[0,1,0] op_sel_hi:[0,1,0]
	v_fma_mix_f32 v14, v19, v92, v14 op_sel_hi:[1,1,0]
	v_fma_mix_f32 v15, v19, v92, v15 op_sel:[0,1,0] op_sel_hi:[1,1,0]
	v_add_f32_dpp v18, v18, v18 quad_perm:[1,0,3,2] row_mask:0xf bank_mask:0xf bound_ctrl:1
	v_fma_mix_f32 v16, v19, v93, v16 op_sel_hi:[1,1,0]
	v_fma_mix_f32 v17, v19, v93, v17 op_sel:[0,1,0] op_sel_hi:[1,1,0]
	v_add_f32_dpp v18, v18, v18 quad_perm:[2,3,0,1] row_mask:0xf bank_mask:0xf bound_ctrl:1
	v_fma_mix_f32 v34, v10, v88, 0 op_sel_hi:[0,1,0]
	v_fma_mix_f32 v34, v11, v88, v34 op_sel:[0,1,0] op_sel_hi:[0,1,0]
	v_add_f32_dpp v18, v18, v18 row_ror:4 row_mask:0xf bank_mask:0xf bound_ctrl:1
	v_fma_mix_f32 v34, v12, v89, v34 op_sel_hi:[0,1,0]
	v_fma_mix_f32 v34, v13, v89, v34 op_sel:[0,1,0] op_sel_hi:[0,1,0]
	v_add_f32_dpp v18, v18, v18 row_ror:8 row_mask:0xf bank_mask:0xf bound_ctrl:1
	s_waitcnt lgkmcnt(3)
	ds_read_b128 v[80:83], v42 offset:512
	v_fma_mix_f32 v10, v18, v94, v14 op_sel_hi:[0,1,0]
	ds_read_b128 v[86:89], v42 offset:4608
	v_fma_mix_f32 v11, v18, v94, v15 op_sel:[0,1,0] op_sel_hi:[0,1,0]
	ds_read_b64 v[84:85], v43 offset:8448
	v_fma_mix_f32 v12, v18, v95, v16 op_sel_hi:[0,1,0]
	v_fma_mix_f32 v13, v18, v95, v17 op_sel:[0,1,0] op_sel_hi:[0,1,0]
	s_waitcnt vmcnt(0)
	v_mov_b32_e32 v36, v37
	s_mov_b32 s30, s26
	s_mov_b32 s26, s27
	s_mov_b32 s27, s28
	s_mov_b32 s28, s30
	v_add_u32_e32 v40, s26, v8
	v_add_u32_e32 v41, s26, v9
	v_add_u32_e32 v42, s27, v8
	v_add_u32_e32 v43, s27, v9
	v_add_u32_e32 v44, s28, v46
	v_add_u32_e32 v45, s28, v47
	s_barrier
	s_add_u32 s3, s3, 1
	s_cmp_lt_u32 s3, 0x410
	s_cbranch_scc1 .Lscan_loop_d1
	v_fma_mix_f32 v35, v10, v98, 0 op_sel_hi:[0,1,0]
	v_fma_mix_f32 v35, v11, v98, v35 op_sel:[0,1,0] op_sel_hi:[0,1,0]
	v_fma_mix_f32 v35, v12, v99, v35 op_sel_hi:[0,1,0]
	v_fma_mix_f32 v35, v13, v99, v35 op_sel:[0,1,0] op_sel_hi:[0,1,0]
	s_nop 1
	v_add_f32_dpp v20, v20, v20 row_ror:8 row_mask:0xf bank_mask:0xf bound_ctrl:1
	v_add_f32_dpp v21, v21, v21 row_ror:8 row_mask:0xf bank_mask:0xf bound_ctrl:1
	v_add_f32_dpp v22, v22, v22 row_ror:8 row_mask:0xf bank_mask:0xf bound_ctrl:1
	v_add_f32_dpp v23, v23, v23 row_ror:8 row_mask:0xf bank_mask:0xf bound_ctrl:1
	v_add_f32_dpp v24, v24, v24 row_ror:8 row_mask:0xf bank_mask:0xf bound_ctrl:1
	v_add_f32_dpp v25, v25, v25 row_ror:8 row_mask:0xf bank_mask:0xf bound_ctrl:1
	v_add_f32_dpp v26, v26, v26 row_ror:8 row_mask:0xf bank_mask:0xf bound_ctrl:1
	v_add_f32_dpp v27, v27, v27 row_ror:8 row_mask:0xf bank_mask:0xf bound_ctrl:1
	v_add_f32_dpp v20, v28, v28 row_ror:8 row_mask:0xf bank_mask:0xc bound_ctrl:1
	v_add_f32_dpp v21, v29, v29 row_ror:8 row_mask:0xf bank_mask:0xc bound_ctrl:1
	v_add_f32_dpp v22, v30, v30 row_ror:8 row_mask:0xf bank_mask:0xc bound_ctrl:1
	v_add_f32_dpp v23, v31, v31 row_ror:8 row_mask:0xf bank_mask:0xc bound_ctrl:1
	v_add_f32_dpp v24, v32, v32 row_ror:8 row_mask:0xf bank_mask:0xc bound_ctrl:1
	v_add_f32_dpp v25, v33, v33 row_ror:8 row_mask:0xf bank_mask:0xc bound_ctrl:1
	v_add_f32_dpp v26, v34, v34 row_ror:8 row_mask:0xf bank_mask:0xc bound_ctrl:1
	v_add_f32_dpp v27, v35, v35 row_ror:8 row_mask:0xf bank_mask:0xc bound_ctrl:1
	v_add_f32_dpp v20, v20, v20 row_half_mirror row_mask:0xf bank_mask:0xf bound_ctrl:1
	v_add_f32_dpp v21, v21, v21 row_half_mirror row_mask:0xf bank_mask:0xf bound_ctrl:1
	v_add_f32_dpp v22, v22, v22 row_half_mirror row_mask:0xf bank_mask:0xf bound_ctrl:1
	v_add_f32_dpp v23, v23, v23 row_half_mirror row_mask:0xf bank_mask:0xf bound_ctrl:1
	v_add_f32_dpp v20, v24, v24 row_half_mirror row_mask:0xf bank_mask:0xa bound_ctrl:1
	v_add_f32_dpp v21, v25, v25 row_half_mirror row_mask:0xf bank_mask:0xa bound_ctrl:1
	v_add_f32_dpp v22, v26, v26 row_half_mirror row_mask:0xf bank_mask:0xa bound_ctrl:1
	v_add_f32_dpp v23, v27, v27 row_half_mirror row_mask:0xf bank_mask:0xa bound_ctrl:1
	v_add_f32_dpp v20, v20, v20 quad_perm:[1,0,3,2] row_mask:0xf bank_mask:0xf bound_ctrl:1
	v_add_f32_dpp v21, v21, v21 quad_perm:[1,0,3,2] row_mask:0xf bank_mask:0xf bound_ctrl:1
	v_add_f32_dpp v22, v22, v22 quad_perm:[1,0,3,2] row_mask:0xf bank_mask:0xf bound_ctrl:1
	v_add_f32_dpp v23, v23, v23 quad_perm:[1,0,3,2] row_mask:0xf bank_mask:0xf bound_ctrl:1
	v_add_f32_dpp v20, v20, v20 quad_perm:[2,3,0,1] row_mask:0xf bank_mask:0xf bound_ctrl:1
	v_add_f32_dpp v21, v21, v21 quad_perm:[2,3,0,1] row_mask:0xf bank_mask:0xf bound_ctrl:1
	v_add_f32_dpp v22, v22, v22 quad_perm:[2,3,0,1] row_mask:0xf bank_mask:0xf bound_ctrl:1
	v_add_f32_dpp v23, v23, v23 quad_perm:[2,3,0,1] row_mask:0xf bank_mask:0xf bound_ctrl:1
	v_cndmask_b32_e64 v20, v20, v21, s[20:21]
	v_cndmask_b32_e64 v20, v20, v22, s[22:23]
	v_cndmask_b32_e64 v20, v20, v23, s[24:25]
	v_cvt_f16_f32_e32 v39, v20
	global_store_short v38, v39, s[12:13]
	s_sub_u32 s12, s12, 0x8000
	s_subb_u32 s13, s13, 0
	s_waitcnt vmcnt(0) lgkmcnt(0)
	s_branch .Lscan_next
.Lscan_next:
	s_lshl_b32 s30, s84, 2
	s_add_u32 s0, s0, s30
	s_cmp_lt_u32 s0, 0x400
	s_cbranch_scc1 .Lscan_unit
	s_branch .LBB0_3154
.Lscan_follow:
	s_movk_i32 s3, 0x411
.Lscan_follow_bar:
	s_barrier
	s_sub_u32 s3, s3, 1
	s_cmp_lg_u32 s3, 0
	s_cbranch_scc1 .Lscan_follow_bar
	s_lshl_b32 s30, s84, 2
	s_add_u32 s0, s0, s30
	s_cmp_lt_u32 s0, 0x400
	s_cbranch_scc1 .Lscan_follow

; __device__ __forceinline__ void ph_peer_select(const Params& P, int layer, const h16* Q, int nrows, char* smem) {
;     ...
;     for (int i = tid; i < 64 * 50; i += NTHR) {
;       const int tok = i / 50, c = i % 50;
;       const float v = cd[tok * 52 + c];
;       int rank = 0;
;       for (int j = 0; j < 50; ++j) { const float o = cd[tok * 52 + j]; rank += (o > v || (o == v && j < c)) ? 1 : 0; }
;       if (rank < TOPK) { tv[tok * 16 + rank] = v; tp[tok * 16 + rank] = c; }
;     }
.LBB0_3610:
	v_mul_hi_i32 v8, v6, s47
	v_lshrrev_b32_e32 v9, 31, v8
	v_ashrrev_i32_e32 v8, 4, v8
	v_add_u32_e32 v89, v8, v9
	v_mul_lo_u32 v8, v89, s52
	v_add_u32_e32 v8, 0, v8
	v_add_u32_e32 v91, 0x10800, v8
	v_lshl_add_u32 v8, v89, 3, v88
	ds_read_b32 v90, v8
	ds_read_b128 v[92:95], v91
	v_mad_u64_u32 v[8:9], s[4:5], v89, s51, v[6:7]
	ds_read_b128 v[96:99], v91 offset:16
	v_mov_b32_e32 v9, 0
	s_waitcnt lgkmcnt(2)
	v_cmp_lt_f32_e64 s[22:23], 0, v90
	v_cmp_eq_f32_e64 s[24:25], 0, v90
	v_bfrev_b32_e32 v100, 1
	v_or_b32_e32 v100, 1, v100
	v_cndmask_b32_e64 v104, 1, -1, s[22:23]
	v_add_u32_e32 v104, v90, v104
	v_cndmask_b32_e64 v104, v104, v100, s[24:25]
	s_waitcnt lgkmcnt(1)
	v_cmp_lt_i32_e64 s[22:23], 0, v8
	v_cmp_lt_i32_e64 s[24:25], 1, v8
	v_cmp_lt_i32_e64 s[26:27], 2, v8
	v_cmp_lt_i32_e64 s[28:29], 3, v8
	v_cndmask_b32_e64 v100, v90, v104, s[22:23]
	v_cndmask_b32_e64 v101, v90, v104, s[24:25]
	v_cndmask_b32_e64 v102, v90, v104, s[26:27]
	v_cndmask_b32_e64 v103, v90, v104, s[28:29]
	v_cmp_gt_f32_e64 s[22:23], v92, v100
	v_cmp_gt_f32_e64 s[24:25], v93, v101
	v_cmp_gt_f32_e64 s[26:27], v94, v102
	v_cmp_gt_f32_e64 s[28:29], v95, v103
	ds_read_b128 v[92:95], v91 offset:32
	v_addc_co_u32_e64 v9, s[30:31], v9, 0, s[22:23]
	v_addc_co_u32_e64 v9, s[30:31], v9, 0, s[24:25]
	v_addc_co_u32_e64 v9, s[30:31], v9, 0, s[26:27]
	v_addc_co_u32_e64 v9, s[30:31], v9, 0, s[28:29]
	s_waitcnt lgkmcnt(1)
	v_cmp_lt_i32_e64 s[22:23], 4, v8
	v_cmp_lt_i32_e64 s[24:25], 5, v8
	v_cmp_lt_i32_e64 s[26:27], 6, v8
	v_cmp_lt_i32_e64 s[28:29], 7, v8
	v_cndmask_b32_e64 v100, v90, v104, s[22:23]
	v_cndmask_b32_e64 v101, v90, v104, s[24:25]
	v_cndmask_b32_e64 v102, v90, v104, s[26:27]
	v_cndmask_b32_e64 v103, v90, v104, s[28:29]
	v_cmp_gt_f32_e64 s[22:23], v96, v100
	v_cmp_gt_f32_e64 s[24:25], v97, v101
	v_cmp_gt_f32_e64 s[26:27], v98, v102
	v_cmp_gt_f32_e64 s[28:29], v99, v103
	ds_read_b128 v[96:99], v91 offset:48
	v_addc_co_u32_e64 v9, s[30:31], v9, 0, s[22:23]
	v_addc_co_u32_e64 v9, s[30:31], v9, 0, s[24:25]
	v_addc_co_u32_e64 v9, s[30:31], v9, 0, s[26:27]
	v_addc_co_u32_e64 v9, s[30:31], v9, 0, s[28:29]
	s_waitcnt lgkmcnt(1)
	v_cmp_lt_i32_e64 s[22:23], 8, v8
	v_cmp_lt_i32_e64 s[24:25], 9, v8
	v_cmp_lt_i32_e64 s[26:27], 10, v8
	v_cmp_lt_i32_e64 s[28:29], 11, v8
	v_cndmask_b32_e64 v100, v90, v104, s[22:23]
	v_cndmask_b32_e64 v101, v90, v104, s[24:25]
	v_cndmask_b32_e64 v102, v90, v104, s[26:27]
	v_cndmask_b32_e64 v103, v90, v104, s[28:29]
	v_cmp_gt_f32_e64 s[22:23], v92, v100
	v_cmp_gt_f32_e64 s[24:25], v93, v101
	v_cmp_gt_f32_e64 s[26:27], v94, v102
	v_cmp_gt_f32_e64 s[28:29], v95, v103
	ds_read_b128 v[92:95], v91 offset:64
	v_addc_co_u32_e64 v9, s[30:31], v9, 0, s[22:23]
	v_addc_co_u32_e64 v9, s[30:31], v9, 0, s[24:25]
	v_addc_co_u32_e64 v9, s[30:31], v9, 0, s[26:27]
	v_addc_co_u32_e64 v9, s[30:31], v9, 0, s[28:29]
	s_waitcnt lgkmcnt(1)
	v_cmp_lt_i32_e64 s[22:23], 12, v8
	v_cmp_lt_i32_e64 s[24:25], 13, v8
	v_cmp_lt_i32_e64 s[26:27], 14, v8
	v_cmp_lt_i32_e64 s[28:29], 15, v8
	v_cndmask_b32_e64 v100, v90, v104, s[22:23]
	v_cndmask_b32_e64 v101, v90, v104, s[24:25]
	v_cndmask_b32_e64 v102, v90, v104, s[26:27]
	v_cndmask_b32_e64 v103, v90, v104, s[28:29]
	v_cmp_gt_f32_e64 s[22:23], v96, v100
	v_cmp_gt_f32_e64 s[24:25], v97, v101
	v_cmp_gt_f32_e64 s[26:27], v98, v102
	v_cmp_gt_f32_e64 s[28:29], v99, v103
	ds_read_b128 v[96:99], v91 offset:80
	v_addc_co_u32_e64 v9, s[30:31], v9, 0, s[22:23]
	v_addc_co_u32_e64 v9, s[30:31], v9, 0, s[24:25]
	v_addc_co_u32_e64 v9, s[30:31], v9, 0, s[26:27]
	v_addc_co_u32_e64 v9, s[30:31], v9, 0, s[28:29]
	s_waitcnt lgkmcnt(1)
	v_cmp_lt_i32_e64 s[22:23], 16, v8
	v_cmp_lt_i32_e64 s[24:25], 17, v8
	v_cmp_lt_i32_e64 s[26:27], 18, v8
	v_cmp_lt_i32_e64 s[28:29], 19, v8
	v_cndmask_b32_e64 v100, v90, v104, s[22:23]
	v_cndmask_b32_e64 v101, v90, v104, s[24:25]
	v_cndmask_b32_e64 v102, v90, v104, s[26:27]
	v_cndmask_b32_e64 v103, v90, v104, s[28:29]
	v_cmp_gt_f32_e64 s[22:23], v92, v100
	v_cmp_gt_f32_e64 s[24:25], v93, v101
	v_cmp_gt_f32_e64 s[26:27], v94, v102
	v_cmp_gt_f32_e64 s[28:29], v95, v103
	ds_read_b128 v[92:95], v91 offset:96
	v_addc_co_u32_e64 v9, s[30:31], v9, 0, s[22:23]
	v_addc_co_u32_e64 v9, s[30:31], v9, 0, s[24:25]
	v_addc_co_u32_e64 v9, s[30:31], v9, 0, s[26:27]
	v_addc_co_u32_e64 v9, s[30:31], v9, 0, s[28:29]
	s_waitcnt lgkmcnt(1)
	v_cmp_lt_i32_e64 s[22:23], 20, v8
	v_cmp_lt_i32_e64 s[24:25], 21, v8
	v_cmp_lt_i32_e64 s[26:27], 22, v8
	v_cmp_lt_i32_e64 s[28:29], 23, v8
	v_cndmask_b32_e64 v100, v90, v104, s[22:23]
	v_cndmask_b32_e64 v101, v90, v104, s[24:25]
	v_cndmask_b32_e64 v102, v90, v104, s[26:27]
	v_cndmask_b32_e64 v103, v90, v104, s[28:29]
	v_cmp_gt_f32_e64 s[22:23], v96, v100
	v_cmp_gt_f32_e64 s[24:25], v97, v101
	v_cmp_gt_f32_e64 s[26:27], v98, v102
	v_cmp_gt_f32_e64 s[28:29], v99, v103
	ds_read_b128 v[96:99], v91 offset:112
	v_addc_co_u32_e64 v9, s[30:31], v9, 0, s[22:23]
	v_addc_co_u32_e64 v9, s[30:31], v9, 0, s[24:25]
	v_addc_co_u32_e64 v9, s[30:31], v9, 0, s[26:27]
	v_addc_co_u32_e64 v9, s[30:31], v9, 0, s[28:29]
	s_waitcnt lgkmcnt(1)
; __device__ __forceinline__ void ph_peer_select(const Params& P, int layer, const h16* Q, int nrows, char* smem) {
;     ...
;     for (int i = tid; i < 64 * 50; i += NTHR) {
;       const int tok = i / 50, c = i % 50;
;       const float v = cd[tok * 52 + c];
;       int rank = 0;
;       for (int j = 0; j < 50; ++j) { const float o = cd[tok * 52 + j]; rank += (o > v || (o == v && j < c)) ? 1 : 0; }
;       if (rank < TOPK) { tv[tok * 16 + rank] = v; tp[tok * 16 + rank] = c; }
;     }
	v_cmp_lt_i32_e64 s[22:23], 24, v8
	v_cmp_lt_i32_e64 s[24:25], 25, v8
	v_cmp_lt_i32_e64 s[26:27], 26, v8
	v_cmp_lt_i32_e64 s[28:29], 27, v8
	v_cndmask_b32_e64 v100, v90, v104, s[22:23]
	v_cndmask_b32_e64 v101, v90, v104, s[24:25]
	v_cndmask_b32_e64 v102, v90, v104, s[26:27]
	v_cndmask_b32_e64 v103, v90, v104, s[28:29]
	v_cmp_gt_f32_e64 s[22:23], v92, v100
	v_cmp_gt_f32_e64 s[24:25], v93, v101
	v_cmp_gt_f32_e64 s[26:27], v94, v102
	v_cmp_gt_f32_e64 s[28:29], v95, v103
	ds_read_b128 v[92:95], v91 offset:128
	v_addc_co_u32_e64 v9, s[30:31], v9, 0, s[22:23]
	v_addc_co_u32_e64 v9, s[30:31], v9, 0, s[24:25]
	v_addc_co_u32_e64 v9, s[30:31], v9, 0, s[26:27]
	v_addc_co_u32_e64 v9, s[30:31], v9, 0, s[28:29]
	s_waitcnt lgkmcnt(1)
	v_cmp_lt_i32_e64 s[22:23], 28, v8
	v_cmp_lt_i32_e64 s[24:25], 29, v8
	v_cmp_lt_i32_e64 s[26:27], 30, v8
	v_cmp_lt_i32_e64 s[28:29], 31, v8
	v_cndmask_b32_e64 v100, v90, v104, s[22:23]
	v_cndmask_b32_e64 v101, v90, v104, s[24:25]
	v_cndmask_b32_e64 v102, v90, v104, s[26:27]
	v_cndmask_b32_e64 v103, v90, v104, s[28:29]
	v_cmp_gt_f32_e64 s[22:23], v96, v100
	v_cmp_gt_f32_e64 s[24:25], v97, v101
	v_cmp_gt_f32_e64 s[26:27], v98, v102
	v_cmp_gt_f32_e64 s[28:29], v99, v103
	ds_read_b128 v[96:99], v91 offset:144
	v_addc_co_u32_e64 v9, s[30:31], v9, 0, s[22:23]
	v_addc_co_u32_e64 v9, s[30:31], v9, 0, s[24:25]
	v_addc_co_u32_e64 v9, s[30:31], v9, 0, s[26:27]
	v_addc_co_u32_e64 v9, s[30:31], v9, 0, s[28:29]
	s_waitcnt lgkmcnt(1)
	v_cmp_lt_i32_e64 s[22:23], 32, v8
	v_cmp_lt_i32_e64 s[24:25], 33, v8
	v_cmp_lt_i32_e64 s[26:27], 34, v8
	v_cmp_lt_i32_e64 s[28:29], 35, v8
	v_cndmask_b32_e64 v100, v90, v104, s[22:23]
	v_cndmask_b32_e64 v101, v90, v104, s[24:25]
	v_cndmask_b32_e64 v102, v90, v104, s[26:27]
	v_cndmask_b32_e64 v103, v90, v104, s[28:29]
	v_cmp_gt_f32_e64 s[22:23], v92, v100
	v_cmp_gt_f32_e64 s[24:25], v93, v101
	v_cmp_gt_f32_e64 s[26:27], v94, v102
	v_cmp_gt_f32_e64 s[28:29], v95, v103
	ds_read_b128 v[92:95], v91 offset:160
	v_addc_co_u32_e64 v9, s[30:31], v9, 0, s[22:23]
	v_addc_co_u32_e64 v9, s[30:31], v9, 0, s[24:25]
	v_addc_co_u32_e64 v9, s[30:31], v9, 0, s[26:27]
	v_addc_co_u32_e64 v9, s[30:31], v9, 0, s[28:29]
	s_waitcnt lgkmcnt(1)
	v_cmp_lt_i32_e64 s[22:23], 36, v8
	v_cmp_lt_i32_e64 s[24:25], 37, v8
	v_cmp_lt_i32_e64 s[26:27], 38, v8
	v_cmp_lt_i32_e64 s[28:29], 39, v8
	v_cndmask_b32_e64 v100, v90, v104, s[22:23]
	v_cndmask_b32_e64 v101, v90, v104, s[24:25]
	v_cndmask_b32_e64 v102, v90, v104, s[26:27]
	v_cndmask_b32_e64 v103, v90, v104, s[28:29]
	v_cmp_gt_f32_e64 s[22:23], v96, v100
	v_cmp_gt_f32_e64 s[24:25], v97, v101
	v_cmp_gt_f32_e64 s[26:27], v98, v102
	v_cmp_gt_f32_e64 s[28:29], v99, v103
	ds_read_b128 v[96:99], v91 offset:176
	v_addc_co_u32_e64 v9, s[30:31], v9, 0, s[22:23]
	v_addc_co_u32_e64 v9, s[30:31], v9, 0, s[24:25]
	v_addc_co_u32_e64 v9, s[30:31], v9, 0, s[26:27]
	v_addc_co_u32_e64 v9, s[30:31], v9, 0, s[28:29]
	s_waitcnt lgkmcnt(1)
	v_cmp_lt_i32_e64 s[22:23], 40, v8
	v_cmp_lt_i32_e64 s[24:25], 41, v8
	v_cmp_lt_i32_e64 s[26:27], 42, v8
	v_cmp_lt_i32_e64 s[28:29], 43, v8
	v_cndmask_b32_e64 v100, v90, v104, s[22:23]
	v_cndmask_b32_e64 v101, v90, v104, s[24:25]
	v_cndmask_b32_e64 v102, v90, v104, s[26:27]
	v_cndmask_b32_e64 v103, v90, v104, s[28:29]
	v_cmp_gt_f32_e64 s[22:23], v92, v100
	v_cmp_gt_f32_e64 s[24:25], v93, v101
	v_cmp_gt_f32_e64 s[26:27], v94, v102
	v_cmp_gt_f32_e64 s[28:29], v95, v103
	ds_read_b64 v[92:93], v91 offset:192
	v_addc_co_u32_e64 v9, s[30:31], v9, 0, s[22:23]
	v_addc_co_u32_e64 v9, s[30:31], v9, 0, s[24:25]
	v_addc_co_u32_e64 v9, s[30:31], v9, 0, s[26:27]
	v_addc_co_u32_e64 v9, s[30:31], v9, 0, s[28:29]
	s_waitcnt lgkmcnt(1)
	v_cmp_lt_i32_e64 s[22:23], 44, v8
	v_cmp_lt_i32_e64 s[24:25], 45, v8
	v_cmp_lt_i32_e64 s[26:27], 46, v8
	v_cmp_lt_i32_e64 s[28:29], 47, v8
	v_cndmask_b32_e64 v100, v90, v104, s[22:23]
	v_cndmask_b32_e64 v101, v90, v104, s[24:25]
	v_cndmask_b32_e64 v102, v90, v104, s[26:27]
	v_cndmask_b32_e64 v103, v90, v104, s[28:29]
	v_cmp_gt_f32_e64 s[22:23], v96, v100
	v_cmp_gt_f32_e64 s[24:25], v97, v101
	v_cmp_gt_f32_e64 s[26:27], v98, v102
	v_cmp_gt_f32_e64 s[28:29], v99, v103
	v_addc_co_u32_e64 v9, s[30:31], v9, 0, s[22:23]
	v_addc_co_u32_e64 v9, s[30:31], v9, 0, s[24:25]
	v_addc_co_u32_e64 v9, s[30:31], v9, 0, s[26:27]
	v_addc_co_u32_e64 v9, s[30:31], v9, 0, s[28:29]
	s_waitcnt lgkmcnt(0)
	v_cmp_lt_i32_e64 s[22:23], 48, v8
	v_cmp_lt_i32_e64 s[24:25], 49, v8
	s_nop 0
	v_cndmask_b32_e64 v100, v90, v104, s[22:23]
	v_cndmask_b32_e64 v101, v90, v104, s[24:25]
	v_cmp_gt_f32_e64 s[22:23], v92, v100
	v_cmp_gt_f32_e64 s[24:25], v93, v101
	s_nop 0
	v_addc_co_u32_e64 v9, s[30:31], v9, 0, s[22:23]
	v_addc_co_u32_e64 v9, s[30:31], v9, 0, s[24:25]
	v_cmp_gt_u32_e32 vcc, 16, v9
	s_and_saveexec_b64 s[4:5], vcc
	s_cbranch_execz .LBB0_3609
	v_lshlrev_b32_e32 v9, 2, v9
	v_lshl_or_b32 v9, v89, 6, v9
	v_add_u32_e32 v9, 0, v9
	v_add_u32_e32 v89, 0x13c00, v9
	v_add_u32_e32 v9, 0x14c00, v9
	ds_write_b32 v89, v90
	ds_write_b32 v9, v8
	s_branch .LBB0_3609
